# v19: all 16 GEMM LDS-DMA loads per K-iteration use SGPR-base addressing (no 64-bit VALU address adds in the main loops)
# speedup vs baseline: 1.0108x; 1.0011x over previous
; #define PG8_STAGE(bufoff, gbase, voff) do { _Pragma("unroll") for (int _i = 0; _i < 2; ++_i) \
;         __builtin_amdgcn_global_load_lds((const unsigned*)((const char*)(gbase) + (voff)[_i]), (LAS unsigned*)(lds + (bufoff) + ldsw + _i * 8192), 16, 0, 0); } while (0)
; #define PG8_LDA(dst, b, h) do { _Pragma("unroll") for (int m = 0; m < 4; ++m) _Pragma("unroll") for (int k = 0; k < 2; ++k) dst[m][k] = *(const LAS f16x8*)(lds + PG8_SA(b, h) + aoff + m * 2048 + k * 1024); } while (0)
; #define PG8_LDB(dst, b, h) do { _Pragma("unroll") for (int n = 0; n < 2; ++n) _Pragma("unroll") for (int k = 0; k < 2; ++k) dst[n][k] = *(const LAS f16x8*)(lds + PG8_SB(b, h) + boff + n * 2048 + k * 1024); } while (0)
; #define PG8_MMA(ai, bj, At, Bt) do { __builtin_amdgcn_s_setprio(1); _Pragma("unroll") for (int m = 0; m < 4; ++m) _Pragma("unroll") for (int n = 0; n < 2; ++n) _Pragma("unroll") for (int k = 0; k < 2; ++k) \
;         acc[ai][bj][m][n] = mma16_<Epi::BF16>(Bt[n][k], At[m][k], acc[ai][bj][m][n]); __builtin_amdgcn_s_setprio(0); } while (0)
; #define PG8_WAIT_V(n) asm volatile("s_waitcnt vmcnt(" #n ")" ::: "memory")
; #define PG8_WAIT_L(n) asm volatile("s_waitcnt lgkmcnt(" #n ")" ::: "memory")
; #define PG8_BAR __builtin_amdgcn_s_barrier()
;     ...
;             const bool last = (t == nt - 2);
;             const char* a1 = cA + (size_t)(t + 1) * kstep;
;             const char* a2 = last ? nA : cA + (size_t)(t + 2) * kstep; const char* b2 = last ? nB : cB + (size_t)(t + 2) * kstep;
;             const char* a3 = a2 + kstep; const char* b3 = b2 + kstep;
;             if constexpr (SP2) {
;             PG8_LDB(B0, 0, 0); PG8_LDB(B1, 0, 1); PG8_SCHED; PG8_LDA(At, 0, 0); PG8_STAGE(PG8_SA(1, 1), a1 + hA, voffA);
;             PG8_WAIT_V(8); PG8_WAIT_L(0); PG8_BAR; PG8_MMA(0, 0, At, B0); PG8_MMA(0, 1, At, B1); PG8_BAR; PG8_SCHED;
;             PG8_LDA(At, 0, 1); PG8_STAGE(PG8_SB(0, 0), b2, voffB); PG8_STAGE(PG8_SB(0, 1), b2 + hB, voffB); PG8_STAGE(PG8_SA(0, 0), a2, voffA);
;             PG8_WAIT_V(8); PG8_WAIT_L(0); PG8_BAR; if (!cur.half) { PG8_MMA(1, 0, At, B0); PG8_MMA(1, 1, At, B1); } PG8_BAR; PG8_SCHED;
;             PG8_LDB(B0, 1, 0); PG8_LDB(B1, 1, 1); PG8_SCHED; PG8_LDA(At, 1, 0); PG8_STAGE(PG8_SA(0, 1), a2 + hA, voffA);
;             PG8_WAIT_V(8); PG8_WAIT_L(0); PG8_BAR; PG8_MMA(0, 0, At, B0); PG8_MMA(0, 1, At, B1); PG8_BAR; PG8_SCHED;
.LBB0_157:
	s_add_u32 s28, s26, 0xfffc0080
	s_addc_u32 s29, s27, -1
	s_add_i32 s50, 0, 0x10000
	s_cmp_eq_u32 s49, 12
	s_cselect_b32 s31, s2, s29
	s_cselect_b32 s30, s3, s28
	s_cselect_b32 s29, s11, s48
	s_cselect_b32 s28, s19, s47
	s_add_i32 s52, 0, 0x14000
	v_add_u32_e32 v156, s50, v141
	v_add_u32_e32 v172, s52, v141
	ds_read_b128 v[144:147], v156
	ds_read_b128 v[148:151], v156 offset:1024
	ds_read_b128 v[152:155], v156 offset:2048
	ds_read_b128 v[156:159], v156 offset:3072
	ds_read_b128 v[160:163], v172
	ds_read_b128 v[164:167], v172 offset:1024
	ds_read_b128 v[168:171], v172 offset:2048
	ds_read_b128 v[172:175], v172 offset:3072
	s_add_i32 m0, s25, 0xc000
	ds_read_b128 v[176:179], v143
	ds_read_b128 v[180:183], v143 offset:1024
	ds_read_b128 v[184:187], v143 offset:2048
	ds_read_b128 v[188:191], v143 offset:3072
	ds_read_b128 v[192:195], v143 offset:4096
	ds_read_b128 v[214:217], v143 offset:5120
	ds_read_b128 v[218:221], v143 offset:6144
	ds_read_b128 v[222:225], v143 offset:7168
	global_load_lds_dwordx4 v136, s[26:27]
	s_add_i32 m0, s25, 0xe000
	s_nop 0
	global_load_lds_dwordx4 v138, s[26:27]
	s_waitcnt vmcnt(8)
	s_waitcnt lgkmcnt(0)
	s_barrier
	s_setprio 1
	v_mfma_f32_16x16x32_bf16 v[126:129], v[144:147], v[176:179], v[126:129]
	v_mfma_f32_16x16x32_bf16 v[118:121], v[152:155], v[176:179], v[118:121]
	v_mfma_f32_16x16x32_bf16 v[110:113], v[144:147], v[184:187], v[110:113]
	v_mfma_f32_16x16x32_bf16 v[102:105], v[152:155], v[184:187], v[102:105]
	v_mfma_f32_16x16x32_bf16 v[94:97], v[144:147], v[192:195], v[94:97]
	v_mfma_f32_16x16x32_bf16 v[86:89], v[152:155], v[192:195], v[86:89]
	v_mfma_f32_16x16x32_bf16 v[78:81], v[144:147], v[218:221], v[78:81]
	v_mfma_f32_16x16x32_bf16 v[70:73], v[152:155], v[218:221], v[70:73]
	v_mfma_f32_16x16x32_bf16 v[126:129], v[148:151], v[180:183], v[126:129]
	v_mfma_f32_16x16x32_bf16 v[118:121], v[156:159], v[180:183], v[118:121]
	v_mfma_f32_16x16x32_bf16 v[110:113], v[148:151], v[188:191], v[110:113]
	v_mfma_f32_16x16x32_bf16 v[102:105], v[156:159], v[188:191], v[102:105]
	v_mfma_f32_16x16x32_bf16 v[94:97], v[148:151], v[214:217], v[94:97]
	v_mfma_f32_16x16x32_bf16 v[86:89], v[156:159], v[214:217], v[86:89]
	v_mfma_f32_16x16x32_bf16 v[78:81], v[148:151], v[222:225], v[78:81]
	v_mfma_f32_16x16x32_bf16 v[70:73], v[156:159], v[222:225], v[70:73]
	s_setprio 0
	s_setprio 1
	v_mfma_f32_16x16x32_bf16 v[122:125], v[160:163], v[176:179], v[122:125]
	v_mfma_f32_16x16x32_bf16 v[114:117], v[168:171], v[176:179], v[114:117]
	v_mfma_f32_16x16x32_bf16 v[106:109], v[160:163], v[184:187], v[106:109]
	v_mfma_f32_16x16x32_bf16 v[98:101], v[168:171], v[184:187], v[98:101]
	v_mfma_f32_16x16x32_bf16 v[90:93], v[160:163], v[192:195], v[90:93]
	v_mfma_f32_16x16x32_bf16 v[82:85], v[168:171], v[192:195], v[82:85]
	v_mfma_f32_16x16x32_bf16 v[74:77], v[160:163], v[218:221], v[74:77]
	v_mfma_f32_16x16x32_bf16 v[66:69], v[168:171], v[218:221], v[66:69]
	v_mfma_f32_16x16x32_bf16 v[122:125], v[164:167], v[180:183], v[122:125]
	v_mfma_f32_16x16x32_bf16 v[114:117], v[172:175], v[180:183], v[114:117]
	v_mfma_f32_16x16x32_bf16 v[106:109], v[164:167], v[188:191], v[106:109]
	v_mfma_f32_16x16x32_bf16 v[98:101], v[172:175], v[188:191], v[98:101]
	v_mfma_f32_16x16x32_bf16 v[90:93], v[164:167], v[214:217], v[90:93]
	v_mfma_f32_16x16x32_bf16 v[82:85], v[172:175], v[214:217], v[82:85]
	v_mfma_f32_16x16x32_bf16 v[74:77], v[164:167], v[222:225], v[74:77]
	v_mfma_f32_16x16x32_bf16 v[66:69], v[172:175], v[222:225], v[66:69]
	s_setprio 0
	s_barrier
	s_add_i32 s50, s50, s34
	s_mov_b32 m0, s50
	ds_read_b128 v[176:179], v143 offset:16384
	ds_read_b128 v[180:183], v143 offset:17408
	ds_read_b128 v[184:187], v143 offset:18432
	ds_read_b128 v[188:191], v143 offset:19456
	ds_read_b128 v[192:195], v143 offset:20480
	ds_read_b128 v[214:217], v143 offset:21504
	ds_read_b128 v[218:221], v143 offset:22528
	ds_read_b128 v[222:225], v143 offset:23552
	global_load_lds_dwordx4 v0, s[28:29]
	s_add_i32 m0, s50, 0x2000
	s_add_u32 s50, s28, 0x40000
	s_addc_u32 s51, s29, 0
	s_add_i32 s52, s52, s34
	global_load_lds_dwordx4 v130, s[28:29]
	s_mov_b32 m0, s52
	s_nop 0
	global_load_lds_dwordx4 v0, s[50:51]
	s_add_i32 m0, s52, 0x2000
	s_nop 0
	global_load_lds_dwordx4 v130, s[50:51]
	s_mov_b32 m0, s25
	s_nop 0
	global_load_lds_dwordx4 v134, s[30:31]
	s_mov_b32 m0, s36
	s_nop 0
	global_load_lds_dwordx4 v132, s[30:31]
	s_waitcnt vmcnt(8)
	s_waitcnt lgkmcnt(0)
	s_barrier
	s_setprio 1
	v_mfma_f32_16x16x32_bf16 v[62:65], v[144:147], v[176:179], v[62:65]
	v_mfma_f32_16x16x32_bf16 v[54:57], v[152:155], v[176:179], v[54:57]
	v_mfma_f32_16x16x32_bf16 v[46:49], v[144:147], v[184:187], v[46:49]
	v_mfma_f32_16x16x32_bf16 v[38:41], v[152:155], v[184:187], v[38:41]
	v_mfma_f32_16x16x32_bf16 v[30:33], v[144:147], v[192:195], v[30:33]
	v_mfma_f32_16x16x32_bf16 v[22:25], v[152:155], v[192:195], v[22:25]
	v_mfma_f32_16x16x32_bf16 v[14:17], v[144:147], v[218:221], v[14:17]
	v_mfma_f32_16x16x32_bf16 v[6:9], v[152:155], v[218:221], v[6:9]
	v_mfma_f32_16x16x32_bf16 v[62:65], v[148:151], v[180:183], v[62:65]
	v_mfma_f32_16x16x32_bf16 v[54:57], v[156:159], v[180:183], v[54:57]
	v_mfma_f32_16x16x32_bf16 v[46:49], v[148:151], v[188:191], v[46:49]
	v_mfma_f32_16x16x32_bf16 v[38:41], v[156:159], v[188:191], v[38:41]
	v_mfma_f32_16x16x32_bf16 v[30:33], v[148:151], v[214:217], v[30:33]
	v_mfma_f32_16x16x32_bf16 v[22:25], v[156:159], v[214:217], v[22:25]
	v_mfma_f32_16x16x32_bf16 v[14:17], v[148:151], v[222:225], v[14:17]
	v_mfma_f32_16x16x32_bf16 v[6:9], v[156:159], v[222:225], v[6:9]
	s_setprio 0
	s_setprio 1
	v_mfma_f32_16x16x32_bf16 v[58:61], v[160:163], v[176:179], v[58:61]
	v_mfma_f32_16x16x32_bf16 v[50:53], v[168:171], v[176:179], v[50:53]
	v_mfma_f32_16x16x32_bf16 v[42:45], v[160:163], v[184:187], v[42:45]
	v_mfma_f32_16x16x32_bf16 v[34:37], v[168:171], v[184:187], v[34:37]
	v_mfma_f32_16x16x32_bf16 v[26:29], v[160:163], v[192:195], v[26:29]
	v_mfma_f32_16x16x32_bf16 v[18:21], v[168:171], v[192:195], v[18:21]
	v_mfma_f32_16x16x32_bf16 v[10:13], v[160:163], v[218:221], v[10:13]
	v_mfma_f32_16x16x32_bf16 v[2:5], v[168:171], v[218:221], v[2:5]
	v_mfma_f32_16x16x32_bf16 v[58:61], v[164:167], v[180:183], v[58:61]
	v_mfma_f32_16x16x32_bf16 v[50:53], v[172:175], v[180:183], v[50:53]
	v_mfma_f32_16x16x32_bf16 v[42:45], v[164:167], v[188:191], v[42:45]
	v_mfma_f32_16x16x32_bf16 v[34:37], v[172:175], v[188:191], v[34:37]
	v_mfma_f32_16x16x32_bf16 v[26:29], v[164:167], v[214:217], v[26:29]
	v_mfma_f32_16x16x32_bf16 v[18:21], v[172:175], v[214:217], v[18:21]
	v_mfma_f32_16x16x32_bf16 v[10:13], v[164:167], v[222:225], v[10:13]
	v_mfma_f32_16x16x32_bf16 v[2:5], v[172:175], v[222:225], v[2:5]
	s_setprio 0
	s_barrier
; #define PG8_STAGE(bufoff, gbase, voff) do { _Pragma("unroll") for (int _i = 0; _i < 2; ++_i) \
;         __builtin_amdgcn_global_load_lds((const unsigned*)((const char*)(gbase) + (voff)[_i]), (LAS unsigned*)(lds + (bufoff) + ldsw + _i * 8192), 16, 0, 0); } while (0)
; #define PG8_LDA(dst, b, h) do { _Pragma("unroll") for (int m = 0; m < 4; ++m) _Pragma("unroll") for (int k = 0; k < 2; ++k) dst[m][k] = *(const LAS f16x8*)(lds + PG8_SA(b, h) + aoff + m * 2048 + k * 1024); } while (0)
; #define PG8_LDB(dst, b, h) do { _Pragma("unroll") for (int n = 0; n < 2; ++n) _Pragma("unroll") for (int k = 0; k < 2; ++k) dst[n][k] = *(const LAS f16x8*)(lds + PG8_SB(b, h) + boff + n * 2048 + k * 1024); } while (0)
; #define PG8_MMA(ai, bj, At, Bt) do { __builtin_amdgcn_s_setprio(1); _Pragma("unroll") for (int m = 0; m < 4; ++m) _Pragma("unroll") for (int n = 0; n < 2; ++n) _Pragma("unroll") for (int k = 0; k < 2; ++k) \
;         acc[ai][bj][m][n] = mma16_<Epi::BF16>(Bt[n][k], At[m][k], acc[ai][bj][m][n]); __builtin_amdgcn_s_setprio(0); } while (0)
; #define PG8_WAIT_V(n) asm volatile("s_waitcnt vmcnt(" #n ")" ::: "memory")
; #define PG8_WAIT_L(n) asm volatile("s_waitcnt lgkmcnt(" #n ")" ::: "memory")
; #define PG8_BAR __builtin_amdgcn_s_barrier()
; #define PG8_SCHED __builtin_amdgcn_sched_barrier(0)
;     ...
;         for (int t = 0; t < nt; t += 2) {
;     ...
;             PG8_LDB(B0, 1, 0); PG8_LDB(B1, 1, 1); PG8_SCHED; PG8_LDA(At, 1, 0); PG8_STAGE(PG8_SA(0, 1), a2 + hA, voffA);
;             PG8_WAIT_V(8); PG8_WAIT_L(0); PG8_BAR; PG8_MMA(0, 0, At, B0); PG8_MMA(0, 1, At, B1); PG8_BAR; PG8_SCHED;
;             PG8_LDA(At, 1, 1); PG8_STAGE(PG8_SB(1, 0), b3, voffB); PG8_STAGE(PG8_SB(1, 1), b3 + hB, voffB); PG8_STAGE(PG8_SA(1, 0), a3, voffA);
;             PG8_WAIT_V(8); PG8_WAIT_L(0); PG8_BAR; if (!cur.half) { PG8_MMA(1, 0, At, B0); PG8_MMA(1, 1, At, B1); } PG8_BAR; PG8_SCHED;
	s_add_i32 s50, 0, 0x18000
	s_add_i32 s51, 0, 0x1c000
	v_add_u32_e32 v156, s50, v141
	v_add_u32_e32 v172, s51, v141
	ds_read_b128 v[144:147], v156
	ds_read_b128 v[148:151], v156 offset:1024
	ds_read_b128 v[152:155], v156 offset:2048
	ds_read_b128 v[156:159], v156 offset:3072
	ds_read_b128 v[160:163], v172
	ds_read_b128 v[164:167], v172 offset:1024
	ds_read_b128 v[168:171], v172 offset:2048
	ds_read_b128 v[172:175], v172 offset:3072
	s_add_u32 s30, s30, 0x40000
	s_addc_u32 s31, s31, 0
	s_add_u32 s98, s30, 0xfffc0080
	s_addc_u32 s99, s31, -1
	s_mov_b32 m0, s37
	ds_read_b128 v[176:179], v143 offset:32768
	ds_read_b128 v[180:183], v143 offset:33792
	ds_read_b128 v[184:187], v143 offset:34816
	ds_read_b128 v[188:191], v143 offset:35840
	ds_read_b128 v[192:195], v143 offset:36864
	ds_read_b128 v[214:217], v143 offset:37888
	ds_read_b128 v[218:221], v143 offset:38912
	ds_read_b128 v[222:225], v143 offset:39936
	global_load_lds_dwordx4 v134, s[30:31]
	s_mov_b32 m0, s40
	s_nop 0
	global_load_lds_dwordx4 v132, s[30:31]
	s_waitcnt vmcnt(8)
	s_waitcnt lgkmcnt(0)
	s_barrier
	s_setprio 1
	v_mfma_f32_16x16x32_bf16 v[126:129], v[144:147], v[176:179], v[126:129]
	v_mfma_f32_16x16x32_bf16 v[118:121], v[152:155], v[176:179], v[118:121]
	v_mfma_f32_16x16x32_bf16 v[110:113], v[144:147], v[184:187], v[110:113]
	v_mfma_f32_16x16x32_bf16 v[102:105], v[152:155], v[184:187], v[102:105]
	v_mfma_f32_16x16x32_bf16 v[94:97], v[144:147], v[192:195], v[94:97]
	v_mfma_f32_16x16x32_bf16 v[86:89], v[152:155], v[192:195], v[86:89]
	v_mfma_f32_16x16x32_bf16 v[78:81], v[144:147], v[218:221], v[78:81]
	v_mfma_f32_16x16x32_bf16 v[70:73], v[152:155], v[218:221], v[70:73]
	v_mfma_f32_16x16x32_bf16 v[126:129], v[148:151], v[180:183], v[126:129]
	v_mfma_f32_16x16x32_bf16 v[118:121], v[156:159], v[180:183], v[118:121]
	v_mfma_f32_16x16x32_bf16 v[110:113], v[148:151], v[188:191], v[110:113]
	v_mfma_f32_16x16x32_bf16 v[102:105], v[156:159], v[188:191], v[102:105]
	v_mfma_f32_16x16x32_bf16 v[94:97], v[148:151], v[214:217], v[94:97]
	v_mfma_f32_16x16x32_bf16 v[86:89], v[156:159], v[214:217], v[86:89]
	v_mfma_f32_16x16x32_bf16 v[78:81], v[148:151], v[222:225], v[78:81]
	v_mfma_f32_16x16x32_bf16 v[70:73], v[156:159], v[222:225], v[70:73]
	s_setprio 0
	s_setprio 1
	v_mfma_f32_16x16x32_bf16 v[122:125], v[160:163], v[176:179], v[122:125]
	v_mfma_f32_16x16x32_bf16 v[114:117], v[168:171], v[176:179], v[114:117]
	v_mfma_f32_16x16x32_bf16 v[106:109], v[160:163], v[184:187], v[106:109]
	v_mfma_f32_16x16x32_bf16 v[98:101], v[168:171], v[184:187], v[98:101]
	v_mfma_f32_16x16x32_bf16 v[90:93], v[160:163], v[192:195], v[90:93]
	v_mfma_f32_16x16x32_bf16 v[82:85], v[168:171], v[192:195], v[82:85]
	v_mfma_f32_16x16x32_bf16 v[74:77], v[160:163], v[218:221], v[74:77]
	v_mfma_f32_16x16x32_bf16 v[66:69], v[168:171], v[218:221], v[66:69]
	v_mfma_f32_16x16x32_bf16 v[122:125], v[164:167], v[180:183], v[122:125]
	v_mfma_f32_16x16x32_bf16 v[114:117], v[172:175], v[180:183], v[114:117]
	v_mfma_f32_16x16x32_bf16 v[106:109], v[164:167], v[188:191], v[106:109]
	v_mfma_f32_16x16x32_bf16 v[98:101], v[172:175], v[188:191], v[98:101]
	v_mfma_f32_16x16x32_bf16 v[90:93], v[164:167], v[214:217], v[90:93]
	v_mfma_f32_16x16x32_bf16 v[82:85], v[172:175], v[214:217], v[82:85]
	v_mfma_f32_16x16x32_bf16 v[74:77], v[164:167], v[222:225], v[74:77]
	v_mfma_f32_16x16x32_bf16 v[66:69], v[172:175], v[222:225], v[66:69]
	s_setprio 0
	s_barrier
	s_add_i32 s30, s50, s34
	s_add_u32 s28, s28, 0x80
	s_addc_u32 s29, s29, 0
	s_mov_b32 m0, s30
	ds_read_b128 v[176:179], v143 offset:49152
	ds_read_b128 v[180:183], v143 offset:50176
	ds_read_b128 v[184:187], v143 offset:51200
	ds_read_b128 v[188:191], v143 offset:52224
	ds_read_b128 v[192:195], v143 offset:53248
	ds_read_b128 v[214:217], v143 offset:54272
	ds_read_b128 v[218:221], v143 offset:55296
	ds_read_b128 v[222:225], v143 offset:56320
	global_load_lds_dwordx4 v0, s[28:29]
	s_add_i32 m0, s30, 0x2000
	s_add_i32 s30, s51, s34
	global_load_lds_dwordx4 v130, s[28:29]
	s_add_u32 s28, s28, 0x40000
	s_addc_u32 s29, s29, 0
	s_mov_b32 m0, s30
	s_nop 0
	global_load_lds_dwordx4 v0, s[28:29]
	s_add_i32 m0, s30, 0x2000
	s_nop 0
	global_load_lds_dwordx4 v130, s[28:29]
	s_mov_b32 m0, s41
	s_nop 0
	global_load_lds_dwordx4 v134, s[98:99]
	s_mov_b32 m0, s42
	s_nop 0
	global_load_lds_dwordx4 v132, s[98:99]
	s_waitcnt vmcnt(8)
	s_waitcnt lgkmcnt(0)
	s_barrier
	s_setprio 1
	v_mfma_f32_16x16x32_bf16 v[62:65], v[144:147], v[176:179], v[62:65]
	v_mfma_f32_16x16x32_bf16 v[54:57], v[152:155], v[176:179], v[54:57]
	v_mfma_f32_16x16x32_bf16 v[46:49], v[144:147], v[184:187], v[46:49]
	v_mfma_f32_16x16x32_bf16 v[38:41], v[152:155], v[184:187], v[38:41]
	v_mfma_f32_16x16x32_bf16 v[30:33], v[144:147], v[192:195], v[30:33]
	v_mfma_f32_16x16x32_bf16 v[22:25], v[152:155], v[192:195], v[22:25]
	v_mfma_f32_16x16x32_bf16 v[14:17], v[144:147], v[218:221], v[14:17]
	v_mfma_f32_16x16x32_bf16 v[6:9], v[152:155], v[218:221], v[6:9]
	v_mfma_f32_16x16x32_bf16 v[62:65], v[148:151], v[180:183], v[62:65]
	v_mfma_f32_16x16x32_bf16 v[54:57], v[156:159], v[180:183], v[54:57]
	v_mfma_f32_16x16x32_bf16 v[46:49], v[148:151], v[188:191], v[46:49]
	v_mfma_f32_16x16x32_bf16 v[38:41], v[156:159], v[188:191], v[38:41]
	v_mfma_f32_16x16x32_bf16 v[30:33], v[148:151], v[214:217], v[30:33]
	v_mfma_f32_16x16x32_bf16 v[22:25], v[156:159], v[214:217], v[22:25]
	v_mfma_f32_16x16x32_bf16 v[14:17], v[148:151], v[222:225], v[14:17]
	v_mfma_f32_16x16x32_bf16 v[6:9], v[156:159], v[222:225], v[6:9]
	s_setprio 0
	s_setprio 1
	v_mfma_f32_16x16x32_bf16 v[58:61], v[160:163], v[176:179], v[58:61]
	v_mfma_f32_16x16x32_bf16 v[50:53], v[168:171], v[176:179], v[50:53]
	v_mfma_f32_16x16x32_bf16 v[42:45], v[160:163], v[184:187], v[42:45]
	v_mfma_f32_16x16x32_bf16 v[34:37], v[168:171], v[184:187], v[34:37]
	v_mfma_f32_16x16x32_bf16 v[26:29], v[160:163], v[192:195], v[26:29]
	v_mfma_f32_16x16x32_bf16 v[18:21], v[168:171], v[192:195], v[18:21]
	v_mfma_f32_16x16x32_bf16 v[10:13], v[160:163], v[218:221], v[10:13]
	v_mfma_f32_16x16x32_bf16 v[2:5], v[168:171], v[218:221], v[2:5]
	v_mfma_f32_16x16x32_bf16 v[58:61], v[164:167], v[180:183], v[58:61]
	v_mfma_f32_16x16x32_bf16 v[50:53], v[172:175], v[180:183], v[50:53]
	v_mfma_f32_16x16x32_bf16 v[42:45], v[164:167], v[188:191], v[42:45]
	v_mfma_f32_16x16x32_bf16 v[34:37], v[172:175], v[188:191], v[34:37]
	v_mfma_f32_16x16x32_bf16 v[26:29], v[164:167], v[214:217], v[26:29]
	v_mfma_f32_16x16x32_bf16 v[18:21], v[172:175], v[214:217], v[18:21]
	v_mfma_f32_16x16x32_bf16 v[10:13], v[164:167], v[222:225], v[10:13]
	v_mfma_f32_16x16x32_bf16 v[2:5], v[172:175], v[222:225], v[2:5]
	s_setprio 0
	s_barrier
	s_add_i32 s49, s49, 2
	s_add_u32 s26, s26, 0x100
	s_addc_u32 s27, s27, 0
	s_add_u32 s47, s47, 0x100
	s_addc_u32 s48, s48, 0
	s_cmp_gt_u32 s49, 13
	s_cbranch_scc0 .LBB0_157
	s_and_b64 vcc, exec, s[8:9]
	s_cbranch_vccz .LBB0_160
	s_barrier

; #define PG8_STAGE(bufoff, gbase, voff) do { _Pragma("unroll") for (int _i = 0; _i < 2; ++_i) \
;         __builtin_amdgcn_global_load_lds((const unsigned*)((const char*)(gbase) + (voff)[_i]), (LAS unsigned*)(lds + (bufoff) + ldsw + _i * 8192), 16, 0, 0); } while (0)
; #define PG8_LDA(dst, b, h) do { _Pragma("unroll") for (int m = 0; m < 4; ++m) _Pragma("unroll") for (int k = 0; k < 2; ++k) dst[m][k] = *(const LAS f16x8*)(lds + PG8_SA(b, h) + aoff + m * 2048 + k * 1024); } while (0)
; #define PG8_LDB(dst, b, h) do { _Pragma("unroll") for (int n = 0; n < 2; ++n) _Pragma("unroll") for (int k = 0; k < 2; ++k) dst[n][k] = *(const LAS f16x8*)(lds + PG8_SB(b, h) + boff + n * 2048 + k * 1024); } while (0)
; #define PG8_MMA(ai, bj, At, Bt) do { __builtin_amdgcn_s_setprio(1); _Pragma("unroll") for (int m = 0; m < 4; ++m) _Pragma("unroll") for (int n = 0; n < 2; ++n) _Pragma("unroll") for (int k = 0; k < 2; ++k) \
;         acc[ai][bj][m][n] = mma16_<Epi::BF16>(Bt[n][k], At[m][k], acc[ai][bj][m][n]); __builtin_amdgcn_s_setprio(0); } while (0)
; #define PG8_WAIT_V(n) asm volatile("s_waitcnt vmcnt(" #n ")" ::: "memory")
; #define PG8_WAIT_L(n) asm volatile("s_waitcnt lgkmcnt(" #n ")" ::: "memory")
; #define PG8_BAR __builtin_amdgcn_s_barrier()
; #define PG8_SCHED __builtin_amdgcn_sched_barrier(0)
;     ...
;             const bool last = (t == nt - 2);
;             const char* a1 = cA + (size_t)(t + 1) * kstep;
;             const char* a2 = last ? nA : cA + (size_t)(t + 2) * kstep; const char* b2 = last ? nB : cB + (size_t)(t + 2) * kstep;
;             const char* a3 = a2 + kstep; const char* b3 = b2 + kstep;
;             if constexpr (SP2) {
;             PG8_LDB(B0, 0, 0); PG8_LDB(B1, 0, 1); PG8_SCHED; PG8_LDA(At, 0, 0); PG8_STAGE(PG8_SA(1, 1), a1 + hA, voffA);
;             PG8_WAIT_V(8); PG8_WAIT_L(0); PG8_BAR; PG8_MMA(0, 0, At, B0); PG8_MMA(0, 1, At, B1); PG8_BAR; PG8_SCHED;
;             PG8_LDA(At, 0, 1); PG8_STAGE(PG8_SB(0, 0), b2, voffB); PG8_STAGE(PG8_SB(0, 1), b2 + hB, voffB); PG8_STAGE(PG8_SA(0, 0), a2, voffA);
;             PG8_WAIT_V(8); PG8_WAIT_L(0); PG8_BAR; if (!cur.half) { PG8_MMA(1, 0, At, B0); PG8_MMA(1, 1, At, B1); } PG8_BAR; PG8_SCHED;
.LBB0_242:
	s_mov_b64 s[42:43], s[44:45]
	s_add_u32 s44, s42, 0x100
	s_addc_u32 s45, s43, 0
	s_add_i32 s37, 0, 0x10000
	s_cmp_eq_u32 s14, 40
	s_cselect_b32 s55, s9, s45
	s_cselect_b32 s54, s8, s44
	s_cselect_b32 s53, s11, s3
	s_cselect_b32 s52, s10, s2
	s_add_i32 s78, 0, 0x14000
	v_add_u32_e32 v130, s37, v243
	v_add_u32_e32 v142, s78, v243
	ds_read_b128 v[146:149], v130
	ds_read_b128 v[150:153], v130 offset:1024
	ds_read_b128 v[154:157], v130 offset:2048
	ds_read_b128 v[158:161], v130 offset:3072
	ds_read_b128 v[130:133], v142
	ds_read_b128 v[134:137], v142 offset:1024
	ds_read_b128 v[138:141], v142 offset:2048
	ds_read_b128 v[142:145], v142 offset:3072
	s_add_i32 m0, s63, 0xc000
	s_waitcnt lgkmcnt(0)
	ds_read_b128 v[162:165], v244
	ds_read_b128 v[166:169], v244 offset:1024
	ds_read_b128 v[170:173], v244 offset:2048
	ds_read_b128 v[174:177], v244 offset:3072
	ds_read_b128 v[178:181], v244 offset:4096
	ds_read_b128 v[182:185], v244 offset:5120
	ds_read_b128 v[186:189], v244 offset:6144
	ds_read_b128 v[190:193], v244 offset:7168
	global_load_lds_dwordx4 v222, s[42:43]
	s_add_i32 m0, s63, 0xe000
	s_nop 0
	global_load_lds_dwordx4 v224, s[42:43]
	s_waitcnt vmcnt(8)
	s_waitcnt lgkmcnt(0)
	s_barrier
	s_setprio 1
	v_mfma_f32_16x16x32_bf16 v[126:129], v[146:149], v[162:165], v[126:129]
	v_mfma_f32_16x16x32_bf16 v[122:125], v[154:157], v[162:165], v[122:125]
	v_mfma_f32_16x16x32_bf16 v[118:121], v[146:149], v[170:173], v[118:121]
	v_mfma_f32_16x16x32_bf16 v[114:117], v[154:157], v[170:173], v[114:117]
	v_mfma_f32_16x16x32_bf16 v[110:113], v[146:149], v[178:181], v[110:113]
	v_mfma_f32_16x16x32_bf16 v[106:109], v[154:157], v[178:181], v[106:109]
	v_mfma_f32_16x16x32_bf16 v[102:105], v[146:149], v[186:189], v[102:105]
	v_mfma_f32_16x16x32_bf16 v[98:101], v[154:157], v[186:189], v[98:101]
	v_mfma_f32_16x16x32_bf16 v[126:129], v[150:153], v[166:169], v[126:129]
	v_mfma_f32_16x16x32_bf16 v[122:125], v[158:161], v[166:169], v[122:125]
	v_mfma_f32_16x16x32_bf16 v[118:121], v[150:153], v[174:177], v[118:121]
	v_mfma_f32_16x16x32_bf16 v[114:117], v[158:161], v[174:177], v[114:117]
	v_mfma_f32_16x16x32_bf16 v[110:113], v[150:153], v[182:185], v[110:113]
	v_mfma_f32_16x16x32_bf16 v[106:109], v[158:161], v[182:185], v[106:109]
	v_mfma_f32_16x16x32_bf16 v[102:105], v[150:153], v[190:193], v[102:105]
	v_mfma_f32_16x16x32_bf16 v[98:101], v[158:161], v[190:193], v[98:101]
	s_setprio 0
	s_setprio 1
	v_mfma_f32_16x16x32_bf16 v[70:73], v[130:133], v[162:165], v[70:73]
	v_mfma_f32_16x16x32_bf16 v[66:69], v[138:141], v[162:165], v[66:69]
	v_mfma_f32_16x16x32_bf16 v[54:57], v[130:133], v[170:173], v[54:57]
	v_mfma_f32_16x16x32_bf16 v[50:53], v[138:141], v[170:173], v[50:53]
	v_mfma_f32_16x16x32_bf16 v[46:49], v[130:133], v[178:181], v[46:49]
	v_mfma_f32_16x16x32_bf16 v[42:45], v[138:141], v[178:181], v[42:45]
	v_mfma_f32_16x16x32_bf16 v[38:41], v[130:133], v[186:189], v[38:41]
	v_mfma_f32_16x16x32_bf16 v[34:37], v[138:141], v[186:189], v[34:37]
	v_mfma_f32_16x16x32_bf16 v[70:73], v[134:137], v[166:169], v[70:73]
	v_mfma_f32_16x16x32_bf16 v[66:69], v[142:145], v[166:169], v[66:69]
	v_mfma_f32_16x16x32_bf16 v[54:57], v[134:137], v[174:177], v[54:57]
	v_mfma_f32_16x16x32_bf16 v[50:53], v[142:145], v[174:177], v[50:53]
	v_mfma_f32_16x16x32_bf16 v[46:49], v[134:137], v[182:185], v[46:49]
	v_mfma_f32_16x16x32_bf16 v[42:45], v[142:145], v[182:185], v[42:45]
	v_mfma_f32_16x16x32_bf16 v[38:41], v[134:137], v[190:193], v[38:41]
	v_mfma_f32_16x16x32_bf16 v[34:37], v[142:145], v[190:193], v[34:37]
	s_setprio 0
	s_barrier
	s_add_i32 s37, s37, s62
	s_mov_b32 m0, s37
	ds_read_b128 v[186:189], v244 offset:16384
	ds_read_b128 v[190:193], v244 offset:17408
	ds_read_b128 v[178:181], v244 offset:18432
	ds_read_b128 v[182:185], v244 offset:19456
	ds_read_b128 v[170:173], v244 offset:20480
	ds_read_b128 v[174:177], v244 offset:21504
	ds_read_b128 v[162:165], v244 offset:22528
	ds_read_b128 v[166:169], v244 offset:23552
	global_load_lds_dwordx4 v214, s[52:53]
	s_add_i32 m0, s37, 0x2000
	s_add_u32 s42, s52, 0xb0000
	s_addc_u32 s43, s53, 0
	s_add_i32 s37, s78, s62
	global_load_lds_dwordx4 v218, s[52:53]
	s_mov_b32 m0, s37
	s_nop 0
	global_load_lds_dwordx4 v214, s[42:43]
	s_add_i32 m0, s37, 0x2000
	s_nop 0
	global_load_lds_dwordx4 v218, s[42:43]
	s_mov_b32 m0, s63
	v_cndmask_b32_e64 v200, 0, 1, s[50:51]
	global_load_lds_dwordx4 v194, s[54:55]
	s_mov_b32 m0, s64
	v_cmp_ne_u32_e64 s[42:43], 1, v200
	global_load_lds_dwordx4 v216, s[54:55]
	s_waitcnt vmcnt(8)
	s_waitcnt lgkmcnt(0)
	s_andn2_b64 vcc, exec, s[50:51]
	s_barrier
	s_cbranch_vccnz .LBB0_244
	s_setprio 1
	v_mfma_f32_16x16x32_bf16 v[94:97], v[146:149], v[186:189], v[94:97]
	v_mfma_f32_16x16x32_bf16 v[90:93], v[154:157], v[186:189], v[90:93]
	v_mfma_f32_16x16x32_bf16 v[86:89], v[146:149], v[178:181], v[86:89]
	v_mfma_f32_16x16x32_bf16 v[82:85], v[154:157], v[178:181], v[82:85]
	v_mfma_f32_16x16x32_bf16 v[78:81], v[146:149], v[170:173], v[78:81]
	v_mfma_f32_16x16x32_bf16 v[74:77], v[154:157], v[170:173], v[74:77]
	v_mfma_f32_16x16x32_bf16 v[62:65], v[146:149], v[162:165], v[62:65]
	v_mfma_f32_16x16x32_bf16 v[58:61], v[154:157], v[162:165], v[58:61]
	v_mfma_f32_16x16x32_bf16 v[94:97], v[150:153], v[190:193], v[94:97]
	v_mfma_f32_16x16x32_bf16 v[90:93], v[158:161], v[190:193], v[90:93]
	v_mfma_f32_16x16x32_bf16 v[86:89], v[150:153], v[182:185], v[86:89]
	v_mfma_f32_16x16x32_bf16 v[82:85], v[158:161], v[182:185], v[82:85]
	v_mfma_f32_16x16x32_bf16 v[78:81], v[150:153], v[174:177], v[78:81]
	v_mfma_f32_16x16x32_bf16 v[74:77], v[158:161], v[174:177], v[74:77]
	v_mfma_f32_16x16x32_bf16 v[62:65], v[150:153], v[166:169], v[62:65]
	v_mfma_f32_16x16x32_bf16 v[58:61], v[158:161], v[166:169], v[58:61]
	s_setprio 0
	s_setprio 1
	v_mfma_f32_16x16x32_bf16 v[30:33], v[130:133], v[186:189], v[30:33]
	v_mfma_f32_16x16x32_bf16 v[26:29], v[138:141], v[186:189], v[26:29]
	v_mfma_f32_16x16x32_bf16 v[22:25], v[130:133], v[178:181], v[22:25]
	v_mfma_f32_16x16x32_bf16 v[18:21], v[138:141], v[178:181], v[18:21]
	v_mfma_f32_16x16x32_bf16 v[14:17], v[130:133], v[170:173], v[14:17]
	v_mfma_f32_16x16x32_bf16 v[10:13], v[138:141], v[170:173], v[10:13]
	v_mfma_f32_16x16x32_bf16 v[6:9], v[130:133], v[162:165], v[6:9]
	v_mfma_f32_16x16x32_bf16 v[2:5], v[138:141], v[162:165], v[2:5]
	v_mfma_f32_16x16x32_bf16 v[30:33], v[134:137], v[190:193], v[30:33]
	v_mfma_f32_16x16x32_bf16 v[26:29], v[142:145], v[190:193], v[26:29]
	v_mfma_f32_16x16x32_bf16 v[22:25], v[134:137], v[182:185], v[22:25]
	v_mfma_f32_16x16x32_bf16 v[18:21], v[142:145], v[182:185], v[18:21]
	v_mfma_f32_16x16x32_bf16 v[14:17], v[134:137], v[174:177], v[14:17]
	v_mfma_f32_16x16x32_bf16 v[10:13], v[142:145], v[174:177], v[10:13]
	v_mfma_f32_16x16x32_bf16 v[6:9], v[134:137], v[166:169], v[6:9]
	v_mfma_f32_16x16x32_bf16 v[2:5], v[142:145], v[166:169], v[2:5]
	s_setprio 0
; #define PG8_STAGE(bufoff, gbase, voff) do { _Pragma("unroll") for (int _i = 0; _i < 2; ++_i) \
;         __builtin_amdgcn_global_load_lds((const unsigned*)((const char*)(gbase) + (voff)[_i]), (LAS unsigned*)(lds + (bufoff) + ldsw + _i * 8192), 16, 0, 0); } while (0)
; #define PG8_LDA(dst, b, h) do { _Pragma("unroll") for (int m = 0; m < 4; ++m) _Pragma("unroll") for (int k = 0; k < 2; ++k) dst[m][k] = *(const LAS f16x8*)(lds + PG8_SA(b, h) + aoff + m * 2048 + k * 1024); } while (0)
; #define PG8_LDB(dst, b, h) do { _Pragma("unroll") for (int n = 0; n < 2; ++n) _Pragma("unroll") for (int k = 0; k < 2; ++k) dst[n][k] = *(const LAS f16x8*)(lds + PG8_SB(b, h) + boff + n * 2048 + k * 1024); } while (0)
; #define PG8_MMA(ai, bj, At, Bt) do { __builtin_amdgcn_s_setprio(1); _Pragma("unroll") for (int m = 0; m < 4; ++m) _Pragma("unroll") for (int n = 0; n < 2; ++n) _Pragma("unroll") for (int k = 0; k < 2; ++k) \
;         acc[ai][bj][m][n] = mma16_<Epi::BF16>(Bt[n][k], At[m][k], acc[ai][bj][m][n]); __builtin_amdgcn_s_setprio(0); } while (0)
; #define PG8_WAIT_V(n) asm volatile("s_waitcnt vmcnt(" #n ")" ::: "memory")
; #define PG8_WAIT_L(n) asm volatile("s_waitcnt lgkmcnt(" #n ")" ::: "memory")
; #define PG8_BAR __builtin_amdgcn_s_barrier()
; #define PG8_SCHED __builtin_amdgcn_sched_barrier(0)
;     ...
;             PG8_LDB(B0, 1, 0); PG8_LDB(B1, 1, 1); PG8_SCHED; PG8_LDA(At, 1, 0); PG8_STAGE(PG8_SA(0, 1), a2 + hA, voffA);
;             PG8_WAIT_V(8); PG8_WAIT_L(0); PG8_BAR; PG8_MMA(0, 0, At, B0); PG8_MMA(0, 1, At, B1); PG8_BAR; PG8_SCHED;
;             PG8_LDA(At, 1, 1); PG8_STAGE(PG8_SB(1, 0), b3, voffB); PG8_STAGE(PG8_SB(1, 1), b3 + hB, voffB); PG8_STAGE(PG8_SA(1, 0), a3, voffA);
;             PG8_WAIT_V(8); PG8_WAIT_L(0); PG8_BAR; if (!cur.half) { PG8_MMA(1, 0, At, B0); PG8_MMA(1, 1, At, B1); } PG8_BAR; PG8_SCHED;
.LBB0_244:
	s_barrier
	s_add_i32 s37, 0, 0x18000
	s_add_i32 s78, 0, 0x1c000
	v_add_u32_e32 v130, s37, v243
	v_add_u32_e32 v142, s78, v243
	ds_read_b128 v[146:149], v130
	ds_read_b128 v[150:153], v130 offset:1024
	ds_read_b128 v[154:157], v130 offset:2048
	ds_read_b128 v[158:161], v130 offset:3072
	ds_read_b128 v[130:133], v142
	ds_read_b128 v[134:137], v142 offset:1024
	ds_read_b128 v[138:141], v142 offset:2048
	ds_read_b128 v[142:145], v142 offset:3072
	s_add_u32 s54, s54, 0xb0000
	s_addc_u32 s55, s55, 0
	s_add_u32 s98, s54, 0xfff50080
	s_addc_u32 s99, s55, -1
	s_mov_b32 m0, s65
	s_waitcnt lgkmcnt(0)
	ds_read_b128 v[162:165], v244 offset:32768
	ds_read_b128 v[166:169], v244 offset:33792
	ds_read_b128 v[170:173], v244 offset:34816
	ds_read_b128 v[174:177], v244 offset:35840
	ds_read_b128 v[178:181], v244 offset:36864
	ds_read_b128 v[182:185], v244 offset:37888
	ds_read_b128 v[186:189], v244 offset:38912
	ds_read_b128 v[190:193], v244 offset:39936
	global_load_lds_dwordx4 v194, s[54:55]
	s_mov_b32 m0, s66
	s_nop 0
	global_load_lds_dwordx4 v216, s[54:55]
	s_waitcnt vmcnt(8)
	s_waitcnt lgkmcnt(0)
	s_barrier
	s_setprio 1
	v_mfma_f32_16x16x32_bf16 v[126:129], v[146:149], v[162:165], v[126:129]
	v_mfma_f32_16x16x32_bf16 v[122:125], v[154:157], v[162:165], v[122:125]
	v_mfma_f32_16x16x32_bf16 v[118:121], v[146:149], v[170:173], v[118:121]
	v_mfma_f32_16x16x32_bf16 v[114:117], v[154:157], v[170:173], v[114:117]
	v_mfma_f32_16x16x32_bf16 v[110:113], v[146:149], v[178:181], v[110:113]
	v_mfma_f32_16x16x32_bf16 v[106:109], v[154:157], v[178:181], v[106:109]
	v_mfma_f32_16x16x32_bf16 v[102:105], v[146:149], v[186:189], v[102:105]
	v_mfma_f32_16x16x32_bf16 v[98:101], v[154:157], v[186:189], v[98:101]
	v_mfma_f32_16x16x32_bf16 v[126:129], v[150:153], v[166:169], v[126:129]
	v_mfma_f32_16x16x32_bf16 v[122:125], v[158:161], v[166:169], v[122:125]
	v_mfma_f32_16x16x32_bf16 v[118:121], v[150:153], v[174:177], v[118:121]
	v_mfma_f32_16x16x32_bf16 v[114:117], v[158:161], v[174:177], v[114:117]
	v_mfma_f32_16x16x32_bf16 v[110:113], v[150:153], v[182:185], v[110:113]
	v_mfma_f32_16x16x32_bf16 v[106:109], v[158:161], v[182:185], v[106:109]
	v_mfma_f32_16x16x32_bf16 v[102:105], v[150:153], v[190:193], v[102:105]
	v_mfma_f32_16x16x32_bf16 v[98:101], v[158:161], v[190:193], v[98:101]
	s_setprio 0
	s_setprio 1
	v_mfma_f32_16x16x32_bf16 v[70:73], v[130:133], v[162:165], v[70:73]
	v_mfma_f32_16x16x32_bf16 v[66:69], v[138:141], v[162:165], v[66:69]
	v_mfma_f32_16x16x32_bf16 v[54:57], v[130:133], v[170:173], v[54:57]
	v_mfma_f32_16x16x32_bf16 v[50:53], v[138:141], v[170:173], v[50:53]
	v_mfma_f32_16x16x32_bf16 v[46:49], v[130:133], v[178:181], v[46:49]
	v_mfma_f32_16x16x32_bf16 v[42:45], v[138:141], v[178:181], v[42:45]
	v_mfma_f32_16x16x32_bf16 v[38:41], v[130:133], v[186:189], v[38:41]
	v_mfma_f32_16x16x32_bf16 v[34:37], v[138:141], v[186:189], v[34:37]
	v_mfma_f32_16x16x32_bf16 v[70:73], v[134:137], v[166:169], v[70:73]
	v_mfma_f32_16x16x32_bf16 v[66:69], v[142:145], v[166:169], v[66:69]
	v_mfma_f32_16x16x32_bf16 v[54:57], v[134:137], v[174:177], v[54:57]
	v_mfma_f32_16x16x32_bf16 v[50:53], v[142:145], v[174:177], v[50:53]
	v_mfma_f32_16x16x32_bf16 v[46:49], v[134:137], v[182:185], v[46:49]
	v_mfma_f32_16x16x32_bf16 v[42:45], v[142:145], v[182:185], v[42:45]
	v_mfma_f32_16x16x32_bf16 v[38:41], v[134:137], v[190:193], v[38:41]
	v_mfma_f32_16x16x32_bf16 v[34:37], v[142:145], v[190:193], v[34:37]
	s_setprio 0
	s_barrier
	s_add_i32 s37, s37, s62
	s_add_u32 s52, s52, 0x80
	s_addc_u32 s53, s53, 0
	s_mov_b32 m0, s37
	ds_read_b128 v[186:189], v244 offset:49152
	ds_read_b128 v[190:193], v244 offset:50176
	ds_read_b128 v[178:181], v244 offset:51200
	ds_read_b128 v[182:185], v244 offset:52224
	ds_read_b128 v[170:173], v244 offset:53248
	ds_read_b128 v[174:177], v244 offset:54272
	ds_read_b128 v[162:165], v244 offset:55296
	ds_read_b128 v[166:169], v244 offset:56320
	global_load_lds_dwordx4 v214, s[52:53]
	s_add_i32 m0, s37, 0x2000
	s_add_i32 s37, s78, s62
	global_load_lds_dwordx4 v218, s[52:53]
	s_add_u32 s52, s52, 0xb0000
	s_addc_u32 s53, s53, 0
	s_mov_b32 m0, s37
	s_and_b64 vcc, exec, s[42:43]
	global_load_lds_dwordx4 v214, s[52:53]
	s_add_i32 m0, s37, 0x2000
	s_nop 0
	global_load_lds_dwordx4 v218, s[52:53]
	s_mov_b32 m0, s0
	s_nop 0
	global_load_lds_dwordx4 v194, s[98:99]
	s_mov_b32 m0, s69
	s_nop 0
	global_load_lds_dwordx4 v216, s[98:99]
	s_waitcnt vmcnt(8)
	s_waitcnt lgkmcnt(0)
	s_barrier
	s_cbranch_vccnz .LBB0_241
	s_setprio 1
	v_mfma_f32_16x16x32_bf16 v[94:97], v[146:149], v[186:189], v[94:97]
	v_mfma_f32_16x16x32_bf16 v[90:93], v[154:157], v[186:189], v[90:93]
	v_mfma_f32_16x16x32_bf16 v[86:89], v[146:149], v[178:181], v[86:89]
	v_mfma_f32_16x16x32_bf16 v[82:85], v[154:157], v[178:181], v[82:85]
	v_mfma_f32_16x16x32_bf16 v[78:81], v[146:149], v[170:173], v[78:81]
	v_mfma_f32_16x16x32_bf16 v[74:77], v[154:157], v[170:173], v[74:77]
	v_mfma_f32_16x16x32_bf16 v[62:65], v[146:149], v[162:165], v[62:65]
	v_mfma_f32_16x16x32_bf16 v[58:61], v[154:157], v[162:165], v[58:61]
	v_mfma_f32_16x16x32_bf16 v[94:97], v[150:153], v[190:193], v[94:97]
	v_mfma_f32_16x16x32_bf16 v[90:93], v[158:161], v[190:193], v[90:93]
	v_mfma_f32_16x16x32_bf16 v[86:89], v[150:153], v[182:185], v[86:89]
	v_mfma_f32_16x16x32_bf16 v[82:85], v[158:161], v[182:185], v[82:85]
	v_mfma_f32_16x16x32_bf16 v[78:81], v[150:153], v[174:177], v[78:81]
	v_mfma_f32_16x16x32_bf16 v[74:77], v[158:161], v[174:177], v[74:77]
	v_mfma_f32_16x16x32_bf16 v[62:65], v[150:153], v[166:169], v[62:65]
	v_mfma_f32_16x16x32_bf16 v[58:61], v[158:161], v[166:169], v[58:61]
	s_setprio 0
	s_setprio 1
	v_mfma_f32_16x16x32_bf16 v[30:33], v[130:133], v[186:189], v[30:33]
	v_mfma_f32_16x16x32_bf16 v[26:29], v[138:141], v[186:189], v[26:29]
	v_mfma_f32_16x16x32_bf16 v[22:25], v[130:133], v[178:181], v[22:25]
	v_mfma_f32_16x16x32_bf16 v[18:21], v[138:141], v[178:181], v[18:21]
	v_mfma_f32_16x16x32_bf16 v[14:17], v[130:133], v[170:173], v[14:17]
	v_mfma_f32_16x16x32_bf16 v[10:13], v[138:141], v[170:173], v[10:13]
	v_mfma_f32_16x16x32_bf16 v[6:9], v[130:133], v[162:165], v[6:9]
	v_mfma_f32_16x16x32_bf16 v[2:5], v[138:141], v[162:165], v[2:5]
	v_mfma_f32_16x16x32_bf16 v[30:33], v[134:137], v[190:193], v[30:33]
	v_mfma_f32_16x16x32_bf16 v[26:29], v[142:145], v[190:193], v[26:29]
	v_mfma_f32_16x16x32_bf16 v[22:25], v[134:137], v[182:185], v[22:25]
	v_mfma_f32_16x16x32_bf16 v[18:21], v[142:145], v[182:185], v[18:21]
	v_mfma_f32_16x16x32_bf16 v[14:17], v[134:137], v[174:177], v[14:17]
	v_mfma_f32_16x16x32_bf16 v[10:13], v[142:145], v[174:177], v[10:13]
	v_mfma_f32_16x16x32_bf16 v[6:9], v[134:137], v[166:169], v[6:9]
	v_mfma_f32_16x16x32_bf16 v[2:5], v[142:145], v[166:169], v[2:5]
	s_setprio 0
	s_branch .LBB0_241

; #define PG8_STAGE(bufoff, gbase, voff) do { _Pragma("unroll") for (int _i = 0; _i < 2; ++_i) \
;         __builtin_amdgcn_global_load_lds((const unsigned*)((const char*)(gbase) + (voff)[_i]), (LAS unsigned*)(lds + (bufoff) + ldsw + _i * 8192), 16, 0, 0); } while (0)
; #define PG8_LDA(dst, b, h) do { _Pragma("unroll") for (int m = 0; m < 4; ++m) _Pragma("unroll") for (int k = 0; k < 2; ++k) dst[m][k] = *(const LAS f16x8*)(lds + PG8_SA(b, h) + aoff + m * 2048 + k * 1024); } while (0)
; #define PG8_LDB(dst, b, h) do { _Pragma("unroll") for (int n = 0; n < 2; ++n) _Pragma("unroll") for (int k = 0; k < 2; ++k) dst[n][k] = *(const LAS f16x8*)(lds + PG8_SB(b, h) + boff + n * 2048 + k * 1024); } while (0)
; #define PG8_MMA(ai, bj, At, Bt) do { __builtin_amdgcn_s_setprio(1); _Pragma("unroll") for (int m = 0; m < 4; ++m) _Pragma("unroll") for (int n = 0; n < 2; ++n) _Pragma("unroll") for (int k = 0; k < 2; ++k) \
;         acc[ai][bj][m][n] = mma16_<Epi::BF16>(Bt[n][k], At[m][k], acc[ai][bj][m][n]); __builtin_amdgcn_s_setprio(0); } while (0)
; #define PG8_WAIT_V(n) asm volatile("s_waitcnt vmcnt(" #n ")" ::: "memory")
; #define PG8_WAIT_L(n) asm volatile("s_waitcnt lgkmcnt(" #n ")" ::: "memory")
; #define PG8_BAR __builtin_amdgcn_s_barrier()
;     ...
;             const bool last = (t == nt - 2);
;             const char* a1 = cA + (size_t)(t + 1) * kstep;
;             const char* a2 = last ? nA : cA + (size_t)(t + 2) * kstep; const char* b2 = last ? nB : cB + (size_t)(t + 2) * kstep;
;             const char* a3 = a2 + kstep; const char* b3 = b2 + kstep;
;             if constexpr (SP2) {
;             PG8_LDB(B0, 0, 0); PG8_LDB(B1, 0, 1); PG8_SCHED; PG8_LDA(At, 0, 0); PG8_STAGE(PG8_SA(1, 1), a1 + hA, voffA);
;             PG8_WAIT_V(8); PG8_WAIT_L(0); PG8_BAR; PG8_MMA(0, 0, At, B0); PG8_MMA(0, 1, At, B1); PG8_BAR; PG8_SCHED;
;             PG8_LDA(At, 0, 1); PG8_STAGE(PG8_SB(0, 0), b2, voffB); PG8_STAGE(PG8_SB(0, 1), b2 + hB, voffB); PG8_STAGE(PG8_SA(0, 0), a2, voffA);
;             PG8_WAIT_V(8); PG8_WAIT_L(0); PG8_BAR; if (!cur.half) { PG8_MMA(1, 0, At, B0); PG8_MMA(1, 1, At, B1); } PG8_BAR; PG8_SCHED;
;             PG8_LDB(B0, 1, 0); PG8_LDB(B1, 1, 1); PG8_SCHED; PG8_LDA(At, 1, 0); PG8_STAGE(PG8_SA(0, 1), a2 + hA, voffA);
;             PG8_WAIT_V(8); PG8_WAIT_L(0); PG8_BAR; PG8_MMA(0, 0, At, B0); PG8_MMA(0, 1, At, B1); PG8_BAR; PG8_SCHED;
.LBB0_516:
	s_add_u32 s28, s26, 0xfffc0080
	s_addc_u32 s29, s27, -1
	s_add_i32 s50, 0, 0x10000
	s_cmp_eq_u32 s49, 12
	s_cselect_b32 s31, s2, s29
	s_cselect_b32 s30, s3, s28
	v_add_u32_e32 v142, s50, v145
	s_cselect_b32 s29, s19, s48
	s_cselect_b32 s28, s21, s47
	s_add_i32 s52, 0, 0x14000
	ds_read_b128 v[148:151], v142
	ds_read_b128 v[152:155], v142 offset:1024
	ds_read_b128 v[156:159], v142 offset:2048
	ds_read_b128 v[160:163], v142 offset:3072
	v_add_u32_e32 v142, s52, v145
	ds_read_b128 v[164:167], v142
	ds_read_b128 v[168:171], v142 offset:1024
	ds_read_b128 v[172:175], v142 offset:2048
	ds_read_b128 v[176:179], v142 offset:3072
	s_add_i32 m0, s17, 0xc000
	ds_read_b128 v[180:183], v147
	ds_read_b128 v[184:187], v147 offset:1024
	ds_read_b128 v[188:191], v147 offset:2048
	ds_read_b128 v[192:195], v147 offset:3072
	ds_read_b128 v[214:217], v147 offset:4096
	ds_read_b128 v[218:221], v147 offset:5120
	ds_read_b128 v[222:225], v147 offset:6144
	ds_read_b128 v[226:229], v147 offset:7168
	global_load_lds_dwordx4 v138, s[26:27]
	s_add_i32 m0, s17, 0xe000
	s_nop 0
	global_load_lds_dwordx4 v140, s[26:27]
	s_waitcnt vmcnt(8)
	s_waitcnt lgkmcnt(0)
	s_barrier
	s_setprio 1
	v_mfma_f32_16x16x32_bf16 v[126:129], v[148:151], v[180:183], v[126:129]
	v_mfma_f32_16x16x32_bf16 v[122:125], v[156:159], v[180:183], v[122:125]
	v_mfma_f32_16x16x32_bf16 v[118:121], v[148:151], v[188:191], v[118:121]
	v_mfma_f32_16x16x32_bf16 v[114:117], v[156:159], v[188:191], v[114:117]
	v_mfma_f32_16x16x32_bf16 v[102:105], v[148:151], v[214:217], v[102:105]
	v_mfma_f32_16x16x32_bf16 v[98:101], v[156:159], v[214:217], v[98:101]
	v_mfma_f32_16x16x32_bf16 v[86:89], v[148:151], v[222:225], v[86:89]
	v_mfma_f32_16x16x32_bf16 v[82:85], v[156:159], v[222:225], v[82:85]
	v_mfma_f32_16x16x32_bf16 v[126:129], v[152:155], v[184:187], v[126:129]
	v_mfma_f32_16x16x32_bf16 v[122:125], v[160:163], v[184:187], v[122:125]
	v_mfma_f32_16x16x32_bf16 v[118:121], v[152:155], v[192:195], v[118:121]
	v_mfma_f32_16x16x32_bf16 v[114:117], v[160:163], v[192:195], v[114:117]
	v_mfma_f32_16x16x32_bf16 v[102:105], v[152:155], v[218:221], v[102:105]
	v_mfma_f32_16x16x32_bf16 v[98:101], v[160:163], v[218:221], v[98:101]
	v_mfma_f32_16x16x32_bf16 v[86:89], v[152:155], v[226:229], v[86:89]
	v_mfma_f32_16x16x32_bf16 v[82:85], v[160:163], v[226:229], v[82:85]
	s_setprio 0
	s_setprio 1
	v_mfma_f32_16x16x32_bf16 v[110:113], v[164:167], v[180:183], v[110:113]
	v_mfma_f32_16x16x32_bf16 v[106:109], v[172:175], v[180:183], v[106:109]
	v_mfma_f32_16x16x32_bf16 v[94:97], v[164:167], v[188:191], v[94:97]
	v_mfma_f32_16x16x32_bf16 v[90:93], v[172:175], v[188:191], v[90:93]
	v_mfma_f32_16x16x32_bf16 v[78:81], v[164:167], v[214:217], v[78:81]
	v_mfma_f32_16x16x32_bf16 v[74:77], v[172:175], v[214:217], v[74:77]
	v_mfma_f32_16x16x32_bf16 v[70:73], v[164:167], v[222:225], v[70:73]
	v_mfma_f32_16x16x32_bf16 v[66:69], v[172:175], v[222:225], v[66:69]
	v_mfma_f32_16x16x32_bf16 v[110:113], v[168:171], v[184:187], v[110:113]
	v_mfma_f32_16x16x32_bf16 v[106:109], v[176:179], v[184:187], v[106:109]
	v_mfma_f32_16x16x32_bf16 v[94:97], v[168:171], v[192:195], v[94:97]
	v_mfma_f32_16x16x32_bf16 v[90:93], v[176:179], v[192:195], v[90:93]
	v_mfma_f32_16x16x32_bf16 v[78:81], v[168:171], v[218:221], v[78:81]
	v_mfma_f32_16x16x32_bf16 v[74:77], v[176:179], v[218:221], v[74:77]
	v_mfma_f32_16x16x32_bf16 v[70:73], v[168:171], v[226:229], v[70:73]
	v_mfma_f32_16x16x32_bf16 v[66:69], v[176:179], v[226:229], v[66:69]
	s_setprio 0
	s_barrier
	s_add_i32 s50, s50, s34
	s_mov_b32 m0, s50
	ds_read_b128 v[180:183], v147 offset:16384
	ds_read_b128 v[184:187], v147 offset:17408
	ds_read_b128 v[188:191], v147 offset:18432
	ds_read_b128 v[192:195], v147 offset:19456
	ds_read_b128 v[214:217], v147 offset:20480
	ds_read_b128 v[218:221], v147 offset:21504
	ds_read_b128 v[222:225], v147 offset:22528
	ds_read_b128 v[226:229], v147 offset:23552
	global_load_lds_dwordx4 v0, s[28:29]
	s_add_i32 m0, s50, 0x2000
	s_add_u32 s50, s28, 0x40000
	s_addc_u32 s51, s29, 0
	s_add_i32 s52, s52, s34
	global_load_lds_dwordx4 v130, s[28:29]
	s_mov_b32 m0, s52
	s_nop 0
	global_load_lds_dwordx4 v0, s[50:51]
	s_add_i32 m0, s52, 0x2000
	s_nop 0
	global_load_lds_dwordx4 v130, s[50:51]
	s_mov_b32 m0, s17
	s_nop 0
	global_load_lds_dwordx4 v134, s[30:31]
	s_mov_b32 m0, s36
	s_nop 0
	global_load_lds_dwordx4 v132, s[30:31]
	s_waitcnt vmcnt(8)
	s_waitcnt lgkmcnt(0)
	s_barrier
	s_setprio 1
	v_mfma_f32_16x16x32_bf16 v[62:65], v[148:151], v[180:183], v[62:65]
	v_mfma_f32_16x16x32_bf16 v[58:61], v[156:159], v[180:183], v[58:61]
	v_mfma_f32_16x16x32_bf16 v[54:57], v[148:151], v[188:191], v[54:57]
	v_mfma_f32_16x16x32_bf16 v[50:53], v[156:159], v[188:191], v[50:53]
	v_mfma_f32_16x16x32_bf16 v[38:41], v[148:151], v[214:217], v[38:41]
	v_mfma_f32_16x16x32_bf16 v[34:37], v[156:159], v[214:217], v[34:37]
	v_mfma_f32_16x16x32_bf16 v[22:25], v[148:151], v[222:225], v[22:25]
	v_mfma_f32_16x16x32_bf16 v[18:21], v[156:159], v[222:225], v[18:21]
	v_mfma_f32_16x16x32_bf16 v[62:65], v[152:155], v[184:187], v[62:65]
	v_mfma_f32_16x16x32_bf16 v[58:61], v[160:163], v[184:187], v[58:61]
	v_mfma_f32_16x16x32_bf16 v[54:57], v[152:155], v[192:195], v[54:57]
	v_mfma_f32_16x16x32_bf16 v[50:53], v[160:163], v[192:195], v[50:53]
	v_mfma_f32_16x16x32_bf16 v[38:41], v[152:155], v[218:221], v[38:41]
	v_mfma_f32_16x16x32_bf16 v[34:37], v[160:163], v[218:221], v[34:37]
	v_mfma_f32_16x16x32_bf16 v[22:25], v[152:155], v[226:229], v[22:25]
	v_mfma_f32_16x16x32_bf16 v[18:21], v[160:163], v[226:229], v[18:21]
	s_setprio 0
	s_setprio 1
	v_mfma_f32_16x16x32_bf16 v[46:49], v[164:167], v[180:183], v[46:49]
	v_mfma_f32_16x16x32_bf16 v[42:45], v[172:175], v[180:183], v[42:45]
	v_mfma_f32_16x16x32_bf16 v[30:33], v[164:167], v[188:191], v[30:33]
	v_mfma_f32_16x16x32_bf16 v[26:29], v[172:175], v[188:191], v[26:29]
	v_mfma_f32_16x16x32_bf16 v[14:17], v[164:167], v[214:217], v[14:17]
	v_mfma_f32_16x16x32_bf16 v[10:13], v[172:175], v[214:217], v[10:13]
	v_mfma_f32_16x16x32_bf16 v[6:9], v[164:167], v[222:225], v[6:9]
	v_mfma_f32_16x16x32_bf16 v[2:5], v[172:175], v[222:225], v[2:5]
	v_mfma_f32_16x16x32_bf16 v[46:49], v[168:171], v[184:187], v[46:49]
	v_mfma_f32_16x16x32_bf16 v[42:45], v[176:179], v[184:187], v[42:45]
	v_mfma_f32_16x16x32_bf16 v[30:33], v[168:171], v[192:195], v[30:33]
	v_mfma_f32_16x16x32_bf16 v[26:29], v[176:179], v[192:195], v[26:29]
	v_mfma_f32_16x16x32_bf16 v[14:17], v[168:171], v[218:221], v[14:17]
	v_mfma_f32_16x16x32_bf16 v[10:13], v[176:179], v[218:221], v[10:13]
	v_mfma_f32_16x16x32_bf16 v[6:9], v[168:171], v[226:229], v[6:9]
	v_mfma_f32_16x16x32_bf16 v[2:5], v[176:179], v[226:229], v[2:5]
	s_setprio 0
	s_barrier
; #define PG8_STAGE(bufoff, gbase, voff) do { _Pragma("unroll") for (int _i = 0; _i < 2; ++_i) \
;         __builtin_amdgcn_global_load_lds((const unsigned*)((const char*)(gbase) + (voff)[_i]), (LAS unsigned*)(lds + (bufoff) + ldsw + _i * 8192), 16, 0, 0); } while (0)
; #define PG8_LDA(dst, b, h) do { _Pragma("unroll") for (int m = 0; m < 4; ++m) _Pragma("unroll") for (int k = 0; k < 2; ++k) dst[m][k] = *(const LAS f16x8*)(lds + PG8_SA(b, h) + aoff + m * 2048 + k * 1024); } while (0)
; #define PG8_LDB(dst, b, h) do { _Pragma("unroll") for (int n = 0; n < 2; ++n) _Pragma("unroll") for (int k = 0; k < 2; ++k) dst[n][k] = *(const LAS f16x8*)(lds + PG8_SB(b, h) + boff + n * 2048 + k * 1024); } while (0)
; #define PG8_MMA(ai, bj, At, Bt) do { __builtin_amdgcn_s_setprio(1); _Pragma("unroll") for (int m = 0; m < 4; ++m) _Pragma("unroll") for (int n = 0; n < 2; ++n) _Pragma("unroll") for (int k = 0; k < 2; ++k) \
;         acc[ai][bj][m][n] = mma16_<Epi::BF16>(Bt[n][k], At[m][k], acc[ai][bj][m][n]); __builtin_amdgcn_s_setprio(0); } while (0)
; #define PG8_WAIT_V(n) asm volatile("s_waitcnt vmcnt(" #n ")" ::: "memory")
; #define PG8_WAIT_L(n) asm volatile("s_waitcnt lgkmcnt(" #n ")" ::: "memory")
; #define PG8_BAR __builtin_amdgcn_s_barrier()
; #define PG8_SCHED __builtin_amdgcn_sched_barrier(0)
;     ...
;             PG8_LDB(B0, 1, 0); PG8_LDB(B1, 1, 1); PG8_SCHED; PG8_LDA(At, 1, 0); PG8_STAGE(PG8_SA(0, 1), a2 + hA, voffA);
;             PG8_WAIT_V(8); PG8_WAIT_L(0); PG8_BAR; PG8_MMA(0, 0, At, B0); PG8_MMA(0, 1, At, B1); PG8_BAR; PG8_SCHED;
;             PG8_LDA(At, 1, 1); PG8_STAGE(PG8_SB(1, 0), b3, voffB); PG8_STAGE(PG8_SB(1, 1), b3 + hB, voffB); PG8_STAGE(PG8_SA(1, 0), a3, voffA);
;             PG8_WAIT_V(8); PG8_WAIT_L(0); PG8_BAR; if (!cur.half) { PG8_MMA(1, 0, At, B0); PG8_MMA(1, 1, At, B1); } PG8_BAR; PG8_SCHED;
;     __device__ __forceinline__ void operator()(const f32x4 (&acc)[2][2][4][2], const Unit& u, int wr, int wc, int fr, int fq) const {
;         const int row0 = u.pm * 256 + wr * 64 + fr;
;         if (u.pn < 26) {
	s_add_i32 s50, 0, 0x18000
	s_add_i32 s51, 0, 0x1c000
	v_add_u32_e32 v160, s50, v145
	v_add_u32_e32 v176, s51, v145
	ds_read_b128 v[148:151], v160
	ds_read_b128 v[152:155], v160 offset:1024
	ds_read_b128 v[156:159], v160 offset:2048
	ds_read_b128 v[160:163], v160 offset:3072
	ds_read_b128 v[164:167], v176
	ds_read_b128 v[168:171], v176 offset:1024
	ds_read_b128 v[172:175], v176 offset:2048
	ds_read_b128 v[176:179], v176 offset:3072
	s_add_u32 s30, s30, 0x40000
	s_addc_u32 s31, s31, 0
	s_add_u32 s98, s30, 0xfffc0080
	s_addc_u32 s99, s31, -1
	s_mov_b32 m0, s37
	ds_read_b128 v[180:183], v147 offset:32768
	ds_read_b128 v[184:187], v147 offset:33792
	ds_read_b128 v[188:191], v147 offset:34816
	ds_read_b128 v[192:195], v147 offset:35840
	ds_read_b128 v[214:217], v147 offset:36864
	ds_read_b128 v[218:221], v147 offset:37888
	ds_read_b128 v[222:225], v147 offset:38912
	ds_read_b128 v[226:229], v147 offset:39936
	global_load_lds_dwordx4 v134, s[30:31]
	s_mov_b32 m0, s40
	s_nop 0
	global_load_lds_dwordx4 v132, s[30:31]
	s_waitcnt vmcnt(8)
	s_waitcnt lgkmcnt(0)
	s_barrier
	s_setprio 1
	v_mfma_f32_16x16x32_bf16 v[126:129], v[148:151], v[180:183], v[126:129]
	v_mfma_f32_16x16x32_bf16 v[122:125], v[156:159], v[180:183], v[122:125]
	v_mfma_f32_16x16x32_bf16 v[118:121], v[148:151], v[188:191], v[118:121]
	v_mfma_f32_16x16x32_bf16 v[114:117], v[156:159], v[188:191], v[114:117]
	v_mfma_f32_16x16x32_bf16 v[102:105], v[148:151], v[214:217], v[102:105]
	v_mfma_f32_16x16x32_bf16 v[98:101], v[156:159], v[214:217], v[98:101]
	v_mfma_f32_16x16x32_bf16 v[86:89], v[148:151], v[222:225], v[86:89]
	v_mfma_f32_16x16x32_bf16 v[82:85], v[156:159], v[222:225], v[82:85]
	v_mfma_f32_16x16x32_bf16 v[126:129], v[152:155], v[184:187], v[126:129]
	v_mfma_f32_16x16x32_bf16 v[122:125], v[160:163], v[184:187], v[122:125]
	v_mfma_f32_16x16x32_bf16 v[118:121], v[152:155], v[192:195], v[118:121]
	v_mfma_f32_16x16x32_bf16 v[114:117], v[160:163], v[192:195], v[114:117]
	v_mfma_f32_16x16x32_bf16 v[102:105], v[152:155], v[218:221], v[102:105]
	v_mfma_f32_16x16x32_bf16 v[98:101], v[160:163], v[218:221], v[98:101]
	v_mfma_f32_16x16x32_bf16 v[86:89], v[152:155], v[226:229], v[86:89]
	v_mfma_f32_16x16x32_bf16 v[82:85], v[160:163], v[226:229], v[82:85]
	s_setprio 0
	s_setprio 1
	v_mfma_f32_16x16x32_bf16 v[110:113], v[164:167], v[180:183], v[110:113]
	v_mfma_f32_16x16x32_bf16 v[106:109], v[172:175], v[180:183], v[106:109]
	v_mfma_f32_16x16x32_bf16 v[94:97], v[164:167], v[188:191], v[94:97]
	v_mfma_f32_16x16x32_bf16 v[90:93], v[172:175], v[188:191], v[90:93]
	v_mfma_f32_16x16x32_bf16 v[78:81], v[164:167], v[214:217], v[78:81]
	v_mfma_f32_16x16x32_bf16 v[74:77], v[172:175], v[214:217], v[74:77]
	v_mfma_f32_16x16x32_bf16 v[70:73], v[164:167], v[222:225], v[70:73]
	v_mfma_f32_16x16x32_bf16 v[66:69], v[172:175], v[222:225], v[66:69]
	v_mfma_f32_16x16x32_bf16 v[110:113], v[168:171], v[184:187], v[110:113]
	v_mfma_f32_16x16x32_bf16 v[106:109], v[176:179], v[184:187], v[106:109]
	v_mfma_f32_16x16x32_bf16 v[94:97], v[168:171], v[192:195], v[94:97]
	v_mfma_f32_16x16x32_bf16 v[90:93], v[176:179], v[192:195], v[90:93]
	v_mfma_f32_16x16x32_bf16 v[78:81], v[168:171], v[218:221], v[78:81]
	v_mfma_f32_16x16x32_bf16 v[74:77], v[176:179], v[218:221], v[74:77]
	v_mfma_f32_16x16x32_bf16 v[70:73], v[168:171], v[226:229], v[70:73]
	v_mfma_f32_16x16x32_bf16 v[66:69], v[176:179], v[226:229], v[66:69]
	s_setprio 0
	s_barrier
	s_add_i32 s30, s50, s34
	s_add_u32 s28, s28, 0x80
	s_addc_u32 s29, s29, 0
	s_mov_b32 m0, s30
	ds_read_b128 v[180:183], v147 offset:49152
	ds_read_b128 v[184:187], v147 offset:50176
	ds_read_b128 v[188:191], v147 offset:51200
	ds_read_b128 v[192:195], v147 offset:52224
	ds_read_b128 v[214:217], v147 offset:53248
	ds_read_b128 v[218:221], v147 offset:54272
	ds_read_b128 v[222:225], v147 offset:55296
	ds_read_b128 v[226:229], v147 offset:56320
	global_load_lds_dwordx4 v0, s[28:29]
	s_add_i32 m0, s30, 0x2000
	s_add_i32 s30, s51, s34
	global_load_lds_dwordx4 v130, s[28:29]
	s_add_u32 s28, s28, 0x40000
	s_addc_u32 s29, s29, 0
	s_mov_b32 m0, s30
	s_nop 0
	global_load_lds_dwordx4 v0, s[28:29]
	s_add_i32 m0, s30, 0x2000
	s_nop 0
	global_load_lds_dwordx4 v130, s[28:29]
	s_mov_b32 m0, s41
	s_nop 0
	global_load_lds_dwordx4 v134, s[98:99]
	s_mov_b32 m0, s42
	s_nop 0
	global_load_lds_dwordx4 v132, s[98:99]
	s_waitcnt vmcnt(8)
	s_waitcnt lgkmcnt(0)
	s_barrier
	s_setprio 1
	v_mfma_f32_16x16x32_bf16 v[62:65], v[148:151], v[180:183], v[62:65]
	v_mfma_f32_16x16x32_bf16 v[58:61], v[156:159], v[180:183], v[58:61]
	v_mfma_f32_16x16x32_bf16 v[54:57], v[148:151], v[188:191], v[54:57]
	v_mfma_f32_16x16x32_bf16 v[50:53], v[156:159], v[188:191], v[50:53]
	v_mfma_f32_16x16x32_bf16 v[38:41], v[148:151], v[214:217], v[38:41]
	v_mfma_f32_16x16x32_bf16 v[34:37], v[156:159], v[214:217], v[34:37]
	v_mfma_f32_16x16x32_bf16 v[22:25], v[148:151], v[222:225], v[22:25]
	v_mfma_f32_16x16x32_bf16 v[18:21], v[156:159], v[222:225], v[18:21]
	v_mfma_f32_16x16x32_bf16 v[62:65], v[152:155], v[184:187], v[62:65]
	v_mfma_f32_16x16x32_bf16 v[58:61], v[160:163], v[184:187], v[58:61]
	v_mfma_f32_16x16x32_bf16 v[54:57], v[152:155], v[192:195], v[54:57]
	v_mfma_f32_16x16x32_bf16 v[50:53], v[160:163], v[192:195], v[50:53]
	v_mfma_f32_16x16x32_bf16 v[38:41], v[152:155], v[218:221], v[38:41]
	v_mfma_f32_16x16x32_bf16 v[34:37], v[160:163], v[218:221], v[34:37]
	v_mfma_f32_16x16x32_bf16 v[22:25], v[152:155], v[226:229], v[22:25]
	v_mfma_f32_16x16x32_bf16 v[18:21], v[160:163], v[226:229], v[18:21]
	s_setprio 0
	s_setprio 1
	v_mfma_f32_16x16x32_bf16 v[46:49], v[164:167], v[180:183], v[46:49]
	v_mfma_f32_16x16x32_bf16 v[42:45], v[172:175], v[180:183], v[42:45]
	v_mfma_f32_16x16x32_bf16 v[30:33], v[164:167], v[188:191], v[30:33]
	v_mfma_f32_16x16x32_bf16 v[26:29], v[172:175], v[188:191], v[26:29]
	v_mfma_f32_16x16x32_bf16 v[14:17], v[164:167], v[214:217], v[14:17]
	v_mfma_f32_16x16x32_bf16 v[10:13], v[172:175], v[214:217], v[10:13]
	v_mfma_f32_16x16x32_bf16 v[6:9], v[164:167], v[222:225], v[6:9]
	v_mfma_f32_16x16x32_bf16 v[2:5], v[172:175], v[222:225], v[2:5]
	v_mfma_f32_16x16x32_bf16 v[46:49], v[168:171], v[184:187], v[46:49]
	v_mfma_f32_16x16x32_bf16 v[42:45], v[176:179], v[184:187], v[42:45]
	v_mfma_f32_16x16x32_bf16 v[30:33], v[168:171], v[192:195], v[30:33]
	v_mfma_f32_16x16x32_bf16 v[26:29], v[176:179], v[192:195], v[26:29]
	v_mfma_f32_16x16x32_bf16 v[14:17], v[168:171], v[218:221], v[14:17]
	v_mfma_f32_16x16x32_bf16 v[10:13], v[176:179], v[218:221], v[10:13]
	v_mfma_f32_16x16x32_bf16 v[6:9], v[168:171], v[226:229], v[6:9]
	v_mfma_f32_16x16x32_bf16 v[2:5], v[176:179], v[226:229], v[2:5]
	s_setprio 0
	s_barrier
	s_add_i32 s49, s49, 2
	s_add_u32 s26, s26, 0x100
	s_addc_u32 s27, s27, 0
	s_add_u32 s47, s47, 0x100
	s_addc_u32 s48, s48, 0
	s_cmp_gt_u32 s49, 13
	s_cbranch_scc0 .LBB0_516
	s_and_b64 vcc, exec, s[8:9]
	s_cbranch_vccnz .LBB0_521
	v_lshl_add_u32 v142, s16, 8, v144
	s_cmp_gt_i32 s46, 25
	s_mov_b64 s[2:3], -1
	s_cbranch_scc1 .LBB0_522

; #define PG8_STAGE(bufoff, gbase, voff) do { _Pragma("unroll") for (int _i = 0; _i < 2; ++_i) \
;         __builtin_amdgcn_global_load_lds((const unsigned*)((const char*)(gbase) + (voff)[_i]), (LAS unsigned*)(lds + (bufoff) + ldsw + _i * 8192), 16, 0, 0); } while (0)
; #define PG8_LDA(dst, b, h) do { _Pragma("unroll") for (int m = 0; m < 4; ++m) _Pragma("unroll") for (int k = 0; k < 2; ++k) dst[m][k] = *(const LAS f16x8*)(lds + PG8_SA(b, h) + aoff + m * 2048 + k * 1024); } while (0)
; #define PG8_LDB(dst, b, h) do { _Pragma("unroll") for (int n = 0; n < 2; ++n) _Pragma("unroll") for (int k = 0; k < 2; ++k) dst[n][k] = *(const LAS f16x8*)(lds + PG8_SB(b, h) + boff + n * 2048 + k * 1024); } while (0)
; #define PG8_MMA(ai, bj, At, Bt) do { __builtin_amdgcn_s_setprio(1); _Pragma("unroll") for (int m = 0; m < 4; ++m) _Pragma("unroll") for (int n = 0; n < 2; ++n) _Pragma("unroll") for (int k = 0; k < 2; ++k) \
;         acc[ai][bj][m][n] = mma16_<Epi::BF16>(Bt[n][k], At[m][k], acc[ai][bj][m][n]); __builtin_amdgcn_s_setprio(0); } while (0)
; #define PG8_WAIT_V(n) asm volatile("s_waitcnt vmcnt(" #n ")" ::: "memory")
; #define PG8_WAIT_L(n) asm volatile("s_waitcnt lgkmcnt(" #n ")" ::: "memory")
; #define PG8_BAR __builtin_amdgcn_s_barrier()
; #define PG8_SCHED __builtin_amdgcn_sched_barrier(0)
;     ...
;             const bool last = (t == nt - 2);
;             const char* a1 = cA + (size_t)(t + 1) * kstep;
;             const char* a2 = last ? nA : cA + (size_t)(t + 2) * kstep; const char* b2 = last ? nB : cB + (size_t)(t + 2) * kstep;
;             const char* a3 = a2 + kstep; const char* b3 = b2 + kstep;
;             if constexpr (SP2) {
;             PG8_LDB(B0, 0, 0); PG8_LDB(B1, 0, 1); PG8_SCHED; PG8_LDA(At, 0, 0); PG8_STAGE(PG8_SA(1, 1), a1 + hA, voffA);
;             PG8_WAIT_V(8); PG8_WAIT_L(0); PG8_BAR; PG8_MMA(0, 0, At, B0); PG8_MMA(0, 1, At, B1); PG8_BAR; PG8_SCHED;
;             PG8_LDA(At, 0, 1); PG8_STAGE(PG8_SB(0, 0), b2, voffB); PG8_STAGE(PG8_SB(0, 1), b2 + hB, voffB); PG8_STAGE(PG8_SA(0, 0), a2, voffA);
;             PG8_WAIT_V(8); PG8_WAIT_L(0); PG8_BAR; if (!cur.half) { PG8_MMA(1, 0, At, B0); PG8_MMA(1, 1, At, B1); } PG8_BAR; PG8_SCHED;
.LBB0_758:
	s_mov_b64 s[30:31], s[10:11]
	s_add_u32 s10, s30, 0x100
	s_addc_u32 s11, s31, 0
	s_add_i32 s40, 0, 0x10000
	s_cmp_eq_u32 s59, 12
	s_cselect_b32 s29, s43, s11
	s_cselect_b32 s28, s42, s10
	v_add_u32_e32 v0, s40, v233
	s_cselect_b32 s27, s2, s58
	s_cselect_b32 s26, s3, s23
	s_add_i32 s41, 0, 0x14000
	ds_read_b128 v[148:151], v0
	ds_read_b128 v[152:155], v0 offset:1024
	ds_read_b128 v[156:159], v0 offset:2048
	ds_read_b128 v[160:163], v0 offset:3072
	v_add_u32_e32 v0, s41, v233
	ds_read_b128 v[132:135], v0
	ds_read_b128 v[136:139], v0 offset:1024
	ds_read_b128 v[140:143], v0 offset:2048
	ds_read_b128 v[144:147], v0 offset:3072
	s_add_i32 m0, s9, 0xc000
	s_waitcnt lgkmcnt(0)
	ds_read_b128 v[164:167], v243
	ds_read_b128 v[168:171], v243 offset:1024
	ds_read_b128 v[172:175], v243 offset:2048
	ds_read_b128 v[176:179], v243 offset:3072
	ds_read_b128 v[180:183], v243 offset:4096
	ds_read_b128 v[184:187], v243 offset:5120
	ds_read_b128 v[188:191], v243 offset:6144
	ds_read_b128 v[192:195], v243 offset:7168
	global_load_lds_dwordx4 v222, s[30:31]
	s_add_i32 m0, s9, 0xe000
	s_nop 0
	global_load_lds_dwordx4 v224, s[30:31]
	s_waitcnt vmcnt(8)
	s_waitcnt lgkmcnt(0)
	s_barrier
	s_setprio 1
	v_mfma_f32_16x16x32_f16 v[128:131], v[148:151], v[164:167], v[128:131]
	v_mfma_f32_16x16x32_f16 v[124:127], v[156:159], v[164:167], v[124:127]
	v_mfma_f32_16x16x32_f16 v[112:115], v[148:151], v[172:175], v[112:115]
	v_mfma_f32_16x16x32_f16 v[108:111], v[156:159], v[172:175], v[108:111]
	v_mfma_f32_16x16x32_f16 v[96:99], v[148:151], v[180:183], v[96:99]
	v_mfma_f32_16x16x32_f16 v[92:95], v[156:159], v[180:183], v[92:95]
	v_mfma_f32_16x16x32_f16 v[80:83], v[148:151], v[188:191], v[80:83]
	v_mfma_f32_16x16x32_f16 v[76:79], v[156:159], v[188:191], v[76:79]
	v_mfma_f32_16x16x32_f16 v[128:131], v[152:155], v[168:171], v[128:131]
	v_mfma_f32_16x16x32_f16 v[124:127], v[160:163], v[168:171], v[124:127]
	v_mfma_f32_16x16x32_f16 v[112:115], v[152:155], v[176:179], v[112:115]
	v_mfma_f32_16x16x32_f16 v[108:111], v[160:163], v[176:179], v[108:111]
	v_mfma_f32_16x16x32_f16 v[96:99], v[152:155], v[184:187], v[96:99]
	v_mfma_f32_16x16x32_f16 v[92:95], v[160:163], v[184:187], v[92:95]
	v_mfma_f32_16x16x32_f16 v[80:83], v[152:155], v[192:195], v[80:83]
	v_mfma_f32_16x16x32_f16 v[76:79], v[160:163], v[192:195], v[76:79]
	s_setprio 0
	s_setprio 1
	v_mfma_f32_16x16x32_f16 v[120:123], v[132:135], v[164:167], v[120:123]
	v_mfma_f32_16x16x32_f16 v[116:119], v[140:143], v[164:167], v[116:119]
	v_mfma_f32_16x16x32_f16 v[104:107], v[132:135], v[172:175], v[104:107]
	v_mfma_f32_16x16x32_f16 v[100:103], v[140:143], v[172:175], v[100:103]
	v_mfma_f32_16x16x32_f16 v[88:91], v[132:135], v[180:183], v[88:91]
	v_mfma_f32_16x16x32_f16 v[84:87], v[140:143], v[180:183], v[84:87]
	v_mfma_f32_16x16x32_f16 v[72:75], v[132:135], v[188:191], v[72:75]
	v_mfma_f32_16x16x32_f16 v[68:71], v[140:143], v[188:191], v[68:71]
	v_mfma_f32_16x16x32_f16 v[120:123], v[136:139], v[168:171], v[120:123]
	v_mfma_f32_16x16x32_f16 v[116:119], v[144:147], v[168:171], v[116:119]
	v_mfma_f32_16x16x32_f16 v[104:107], v[136:139], v[176:179], v[104:107]
	v_mfma_f32_16x16x32_f16 v[100:103], v[144:147], v[176:179], v[100:103]
	v_mfma_f32_16x16x32_f16 v[88:91], v[136:139], v[184:187], v[88:91]
	v_mfma_f32_16x16x32_f16 v[84:87], v[144:147], v[184:187], v[84:87]
	v_mfma_f32_16x16x32_f16 v[72:75], v[136:139], v[192:195], v[72:75]
	v_mfma_f32_16x16x32_f16 v[68:71], v[144:147], v[192:195], v[68:71]
	s_setprio 0
	s_barrier
	s_add_i32 s30, s40, s35
	s_mov_b32 m0, s30
	ds_read_b128 v[188:191], v243 offset:16384
	ds_read_b128 v[192:195], v243 offset:17408
	ds_read_b128 v[180:183], v243 offset:18432
	ds_read_b128 v[184:187], v243 offset:19456
	ds_read_b128 v[172:175], v243 offset:20480
	ds_read_b128 v[176:179], v243 offset:21504
	ds_read_b128 v[164:167], v243 offset:22528
	ds_read_b128 v[168:171], v243 offset:23552
	global_load_lds_dwordx4 v216, s[26:27]
	s_add_i32 m0, s30, 0x2000
	s_add_u32 s30, s26, 0x40000
	s_addc_u32 s31, s27, 0
	s_add_i32 s40, s41, s35
	global_load_lds_dwordx4 v220, s[26:27]
	s_mov_b32 m0, s40
	s_nop 0
	global_load_lds_dwordx4 v216, s[30:31]
	s_add_i32 m0, s40, 0x2000
	s_nop 0
	global_load_lds_dwordx4 v220, s[30:31]
	s_mov_b32 m0, s9
	v_cndmask_b32_e64 v0, 0, 1, s[24:25]
	global_load_lds_dwordx4 v214, s[28:29]
	s_mov_b32 m0, s36
	v_cmp_ne_u32_e64 s[40:41], 1, v0
	global_load_lds_dwordx4 v218, s[28:29]
	s_waitcnt vmcnt(8)
	s_waitcnt lgkmcnt(0)
	s_andn2_b64 vcc, exec, s[24:25]
	s_barrier
	s_cbranch_vccnz .LBB0_760
	s_setprio 1
	v_mfma_f32_16x16x32_f16 v[64:67], v[148:151], v[188:191], v[64:67]
	v_mfma_f32_16x16x32_f16 v[60:63], v[156:159], v[188:191], v[60:63]
	v_mfma_f32_16x16x32_f16 v[48:51], v[148:151], v[180:183], v[48:51]
	v_mfma_f32_16x16x32_f16 v[44:47], v[156:159], v[180:183], v[44:47]
	v_mfma_f32_16x16x32_f16 v[32:35], v[148:151], v[172:175], v[32:35]
	v_mfma_f32_16x16x32_f16 v[28:31], v[156:159], v[172:175], v[28:31]
	v_mfma_f32_16x16x32_f16 v[16:19], v[148:151], v[164:167], v[16:19]
	v_mfma_f32_16x16x32_f16 v[12:15], v[156:159], v[164:167], v[12:15]
	v_mfma_f32_16x16x32_f16 v[64:67], v[152:155], v[192:195], v[64:67]
	v_mfma_f32_16x16x32_f16 v[60:63], v[160:163], v[192:195], v[60:63]
	v_mfma_f32_16x16x32_f16 v[48:51], v[152:155], v[184:187], v[48:51]
	v_mfma_f32_16x16x32_f16 v[44:47], v[160:163], v[184:187], v[44:47]
	v_mfma_f32_16x16x32_f16 v[32:35], v[152:155], v[176:179], v[32:35]
	v_mfma_f32_16x16x32_f16 v[28:31], v[160:163], v[176:179], v[28:31]
	v_mfma_f32_16x16x32_f16 v[16:19], v[152:155], v[168:171], v[16:19]
	v_mfma_f32_16x16x32_f16 v[12:15], v[160:163], v[168:171], v[12:15]
	s_setprio 0
	s_setprio 1
	v_mfma_f32_16x16x32_f16 v[56:59], v[132:135], v[188:191], v[56:59]
	v_mfma_f32_16x16x32_f16 v[52:55], v[140:143], v[188:191], v[52:55]
	v_mfma_f32_16x16x32_f16 v[40:43], v[132:135], v[180:183], v[40:43]
	v_mfma_f32_16x16x32_f16 v[36:39], v[140:143], v[180:183], v[36:39]
	v_mfma_f32_16x16x32_f16 v[24:27], v[132:135], v[172:175], v[24:27]
	v_mfma_f32_16x16x32_f16 v[20:23], v[140:143], v[172:175], v[20:23]
	v_mfma_f32_16x16x32_f16 v[8:11], v[132:135], v[164:167], v[8:11]
	v_mfma_f32_16x16x32_f16 v[4:7], v[140:143], v[164:167], v[4:7]
	v_mfma_f32_16x16x32_f16 v[56:59], v[136:139], v[192:195], v[56:59]
	v_mfma_f32_16x16x32_f16 v[52:55], v[144:147], v[192:195], v[52:55]
	v_mfma_f32_16x16x32_f16 v[40:43], v[136:139], v[184:187], v[40:43]
	v_mfma_f32_16x16x32_f16 v[36:39], v[144:147], v[184:187], v[36:39]
	v_mfma_f32_16x16x32_f16 v[24:27], v[136:139], v[176:179], v[24:27]
	v_mfma_f32_16x16x32_f16 v[20:23], v[144:147], v[176:179], v[20:23]
	v_mfma_f32_16x16x32_f16 v[8:11], v[136:139], v[168:171], v[8:11]
	v_mfma_f32_16x16x32_f16 v[4:7], v[144:147], v[168:171], v[4:7]
	s_setprio 0
; #define PG8_STAGE(bufoff, gbase, voff) do { _Pragma("unroll") for (int _i = 0; _i < 2; ++_i) \
;         __builtin_amdgcn_global_load_lds((const unsigned*)((const char*)(gbase) + (voff)[_i]), (LAS unsigned*)(lds + (bufoff) + ldsw + _i * 8192), 16, 0, 0); } while (0)
; #define PG8_LDA(dst, b, h) do { _Pragma("unroll") for (int m = 0; m < 4; ++m) _Pragma("unroll") for (int k = 0; k < 2; ++k) dst[m][k] = *(const LAS f16x8*)(lds + PG8_SA(b, h) + aoff + m * 2048 + k * 1024); } while (0)
; #define PG8_LDB(dst, b, h) do { _Pragma("unroll") for (int n = 0; n < 2; ++n) _Pragma("unroll") for (int k = 0; k < 2; ++k) dst[n][k] = *(const LAS f16x8*)(lds + PG8_SB(b, h) + boff + n * 2048 + k * 1024); } while (0)
; #define PG8_MMA(ai, bj, At, Bt) do { __builtin_amdgcn_s_setprio(1); _Pragma("unroll") for (int m = 0; m < 4; ++m) _Pragma("unroll") for (int n = 0; n < 2; ++n) _Pragma("unroll") for (int k = 0; k < 2; ++k) \
;         acc[ai][bj][m][n] = mma16_<Epi::BF16>(Bt[n][k], At[m][k], acc[ai][bj][m][n]); __builtin_amdgcn_s_setprio(0); } while (0)
; #define PG8_WAIT_V(n) asm volatile("s_waitcnt vmcnt(" #n ")" ::: "memory")
; #define PG8_WAIT_L(n) asm volatile("s_waitcnt lgkmcnt(" #n ")" ::: "memory")
; #define PG8_BAR __builtin_amdgcn_s_barrier()
; #define PG8_SCHED __builtin_amdgcn_sched_barrier(0)
;     ...
;             PG8_LDB(B0, 1, 0); PG8_LDB(B1, 1, 1); PG8_SCHED; PG8_LDA(At, 1, 0); PG8_STAGE(PG8_SA(0, 1), a2 + hA, voffA);
;             PG8_WAIT_V(8); PG8_WAIT_L(0); PG8_BAR; PG8_MMA(0, 0, At, B0); PG8_MMA(0, 1, At, B1); PG8_BAR; PG8_SCHED;
;             PG8_LDA(At, 1, 1); PG8_STAGE(PG8_SB(1, 0), b3, voffB); PG8_STAGE(PG8_SB(1, 1), b3 + hB, voffB); PG8_STAGE(PG8_SA(1, 0), a3, voffA);
;             PG8_WAIT_V(8); PG8_WAIT_L(0); PG8_BAR; if (!cur.half) { PG8_MMA(1, 0, At, B0); PG8_MMA(1, 1, At, B1); } PG8_BAR; PG8_SCHED;
.LBB0_760:
	s_barrier
	s_add_i32 s30, 0, 0x18000
	v_add_u32_e32 v0, s30, v233
	s_add_i32 s31, 0, 0x1c000
	ds_read_b128 v[148:151], v0
	ds_read_b128 v[152:155], v0 offset:1024
	ds_read_b128 v[156:159], v0 offset:2048
	ds_read_b128 v[160:163], v0 offset:3072
	v_add_u32_e32 v0, s31, v233
	ds_read_b128 v[132:135], v0
	ds_read_b128 v[136:139], v0 offset:1024
	ds_read_b128 v[140:143], v0 offset:2048
	ds_read_b128 v[144:147], v0 offset:3072
	s_add_u32 s28, s28, 0x1a0000
	s_addc_u32 s29, s29, 0
	s_add_u32 s98, s28, 0xffe60080
	s_addc_u32 s99, s29, -1
	s_mov_b32 m0, s37
	s_waitcnt lgkmcnt(0)
	ds_read_b128 v[164:167], v243 offset:32768
	ds_read_b128 v[168:171], v243 offset:33792
	ds_read_b128 v[172:175], v243 offset:34816
	ds_read_b128 v[176:179], v243 offset:35840
	ds_read_b128 v[180:183], v243 offset:36864
	ds_read_b128 v[184:187], v243 offset:37888
	ds_read_b128 v[188:191], v243 offset:38912
	ds_read_b128 v[192:195], v243 offset:39936
	global_load_lds_dwordx4 v214, s[28:29]
	s_mov_b32 m0, s48
	s_nop 0
	global_load_lds_dwordx4 v218, s[28:29]
	s_waitcnt vmcnt(8)
	s_waitcnt lgkmcnt(0)
	s_barrier
	s_setprio 1
	v_mfma_f32_16x16x32_f16 v[128:131], v[148:151], v[164:167], v[128:131]
	v_mfma_f32_16x16x32_f16 v[124:127], v[156:159], v[164:167], v[124:127]
	v_mfma_f32_16x16x32_f16 v[112:115], v[148:151], v[172:175], v[112:115]
	v_mfma_f32_16x16x32_f16 v[108:111], v[156:159], v[172:175], v[108:111]
	v_mfma_f32_16x16x32_f16 v[96:99], v[148:151], v[180:183], v[96:99]
	v_mfma_f32_16x16x32_f16 v[92:95], v[156:159], v[180:183], v[92:95]
	v_mfma_f32_16x16x32_f16 v[80:83], v[148:151], v[188:191], v[80:83]
	v_mfma_f32_16x16x32_f16 v[76:79], v[156:159], v[188:191], v[76:79]
	v_mfma_f32_16x16x32_f16 v[128:131], v[152:155], v[168:171], v[128:131]
	v_mfma_f32_16x16x32_f16 v[124:127], v[160:163], v[168:171], v[124:127]
	v_mfma_f32_16x16x32_f16 v[112:115], v[152:155], v[176:179], v[112:115]
	v_mfma_f32_16x16x32_f16 v[108:111], v[160:163], v[176:179], v[108:111]
	v_mfma_f32_16x16x32_f16 v[96:99], v[152:155], v[184:187], v[96:99]
	v_mfma_f32_16x16x32_f16 v[92:95], v[160:163], v[184:187], v[92:95]
	v_mfma_f32_16x16x32_f16 v[80:83], v[152:155], v[192:195], v[80:83]
	v_mfma_f32_16x16x32_f16 v[76:79], v[160:163], v[192:195], v[76:79]
	s_setprio 0
	s_setprio 1
	v_mfma_f32_16x16x32_f16 v[120:123], v[132:135], v[164:167], v[120:123]
	v_mfma_f32_16x16x32_f16 v[116:119], v[140:143], v[164:167], v[116:119]
	v_mfma_f32_16x16x32_f16 v[104:107], v[132:135], v[172:175], v[104:107]
	v_mfma_f32_16x16x32_f16 v[100:103], v[140:143], v[172:175], v[100:103]
	v_mfma_f32_16x16x32_f16 v[88:91], v[132:135], v[180:183], v[88:91]
	v_mfma_f32_16x16x32_f16 v[84:87], v[140:143], v[180:183], v[84:87]
	v_mfma_f32_16x16x32_f16 v[72:75], v[132:135], v[188:191], v[72:75]
	v_mfma_f32_16x16x32_f16 v[68:71], v[140:143], v[188:191], v[68:71]
	v_mfma_f32_16x16x32_f16 v[120:123], v[136:139], v[168:171], v[120:123]
	v_mfma_f32_16x16x32_f16 v[116:119], v[144:147], v[168:171], v[116:119]
	v_mfma_f32_16x16x32_f16 v[104:107], v[136:139], v[176:179], v[104:107]
	v_mfma_f32_16x16x32_f16 v[100:103], v[144:147], v[176:179], v[100:103]
	v_mfma_f32_16x16x32_f16 v[88:91], v[136:139], v[184:187], v[88:91]
	v_mfma_f32_16x16x32_f16 v[84:87], v[144:147], v[184:187], v[84:87]
	v_mfma_f32_16x16x32_f16 v[72:75], v[136:139], v[192:195], v[72:75]
	v_mfma_f32_16x16x32_f16 v[68:71], v[144:147], v[192:195], v[68:71]
	s_setprio 0
	s_barrier
	s_add_i32 s28, s30, s35
	s_add_u32 s26, s26, 0x80
	s_addc_u32 s27, s27, 0
	s_mov_b32 m0, s28
	ds_read_b128 v[188:191], v243 offset:49152
	ds_read_b128 v[192:195], v243 offset:50176
	ds_read_b128 v[180:183], v243 offset:51200
	ds_read_b128 v[184:187], v243 offset:52224
	ds_read_b128 v[172:175], v243 offset:53248
	ds_read_b128 v[176:179], v243 offset:54272
	ds_read_b128 v[164:167], v243 offset:55296
	ds_read_b128 v[168:171], v243 offset:56320
	global_load_lds_dwordx4 v216, s[26:27]
	s_add_i32 m0, s28, 0x2000
	s_add_i32 s28, s31, s35
	global_load_lds_dwordx4 v220, s[26:27]
	s_add_u32 s26, s26, 0x40000
	s_addc_u32 s27, s27, 0
	s_mov_b32 m0, s28
	s_and_b64 vcc, exec, s[40:41]
	global_load_lds_dwordx4 v216, s[26:27]
	s_add_i32 m0, s28, 0x2000
	s_nop 0
	global_load_lds_dwordx4 v220, s[26:27]
	s_mov_b32 m0, s49
	s_nop 0
	global_load_lds_dwordx4 v214, s[98:99]
	s_mov_b32 m0, s50
	s_nop 0
	global_load_lds_dwordx4 v218, s[98:99]
	s_waitcnt vmcnt(8)
	s_waitcnt lgkmcnt(0)
	s_barrier
	s_cbranch_vccnz .LBB0_757
	s_setprio 1
	v_mfma_f32_16x16x32_f16 v[64:67], v[148:151], v[188:191], v[64:67]
	v_mfma_f32_16x16x32_f16 v[60:63], v[156:159], v[188:191], v[60:63]
	v_mfma_f32_16x16x32_f16 v[48:51], v[148:151], v[180:183], v[48:51]
	v_mfma_f32_16x16x32_f16 v[44:47], v[156:159], v[180:183], v[44:47]
	v_mfma_f32_16x16x32_f16 v[32:35], v[148:151], v[172:175], v[32:35]
	v_mfma_f32_16x16x32_f16 v[28:31], v[156:159], v[172:175], v[28:31]
	v_mfma_f32_16x16x32_f16 v[16:19], v[148:151], v[164:167], v[16:19]
	v_mfma_f32_16x16x32_f16 v[12:15], v[156:159], v[164:167], v[12:15]
	v_mfma_f32_16x16x32_f16 v[64:67], v[152:155], v[192:195], v[64:67]
	v_mfma_f32_16x16x32_f16 v[60:63], v[160:163], v[192:195], v[60:63]
	v_mfma_f32_16x16x32_f16 v[48:51], v[152:155], v[184:187], v[48:51]
	v_mfma_f32_16x16x32_f16 v[44:47], v[160:163], v[184:187], v[44:47]
	v_mfma_f32_16x16x32_f16 v[32:35], v[152:155], v[176:179], v[32:35]
	v_mfma_f32_16x16x32_f16 v[28:31], v[160:163], v[176:179], v[28:31]
	v_mfma_f32_16x16x32_f16 v[16:19], v[152:155], v[168:171], v[16:19]
	v_mfma_f32_16x16x32_f16 v[12:15], v[160:163], v[168:171], v[12:15]
	s_setprio 0
	s_setprio 1
	v_mfma_f32_16x16x32_f16 v[56:59], v[132:135], v[188:191], v[56:59]
	v_mfma_f32_16x16x32_f16 v[52:55], v[140:143], v[188:191], v[52:55]
	v_mfma_f32_16x16x32_f16 v[40:43], v[132:135], v[180:183], v[40:43]
	v_mfma_f32_16x16x32_f16 v[36:39], v[140:143], v[180:183], v[36:39]
	v_mfma_f32_16x16x32_f16 v[24:27], v[132:135], v[172:175], v[24:27]
	v_mfma_f32_16x16x32_f16 v[20:23], v[140:143], v[172:175], v[20:23]
	v_mfma_f32_16x16x32_f16 v[8:11], v[132:135], v[164:167], v[8:11]
	v_mfma_f32_16x16x32_f16 v[2:5], v[140:143], v[164:167], v[4:7]
	v_mfma_f32_16x16x32_f16 v[56:59], v[136:139], v[192:195], v[56:59]
	v_mfma_f32_16x16x32_f16 v[52:55], v[144:147], v[192:195], v[52:55]
	v_mfma_f32_16x16x32_f16 v[40:43], v[136:139], v[184:187], v[40:43]
	v_mfma_f32_16x16x32_f16 v[36:39], v[144:147], v[184:187], v[36:39]
	v_mfma_f32_16x16x32_f16 v[24:27], v[136:139], v[176:179], v[24:27]
	v_mfma_f32_16x16x32_f16 v[20:23], v[144:147], v[176:179], v[20:23]
	v_mfma_f32_16x16x32_f16 v[8:11], v[136:139], v[168:171], v[8:11]
	v_mfma_f32_16x16x32_f16 v[4:7], v[144:147], v[168:171], v[2:5]
	s_setprio 0
	s_branch .LBB0_757

; #define PG8_STAGE(bufoff, gbase, voff) do { _Pragma("unroll") for (int _i = 0; _i < 2; ++_i) \
;         __builtin_amdgcn_global_load_lds((const unsigned*)((const char*)(gbase) + (voff)[_i]), (LAS unsigned*)(lds + (bufoff) + ldsw + _i * 8192), 16, 0, 0); } while (0)
; #define PG8_LDA(dst, b, h) do { _Pragma("unroll") for (int m = 0; m < 4; ++m) _Pragma("unroll") for (int k = 0; k < 2; ++k) dst[m][k] = *(const LAS f16x8*)(lds + PG8_SA(b, h) + aoff + m * 2048 + k * 1024); } while (0)
; #define PG8_LDB(dst, b, h) do { _Pragma("unroll") for (int n = 0; n < 2; ++n) _Pragma("unroll") for (int k = 0; k < 2; ++k) dst[n][k] = *(const LAS f16x8*)(lds + PG8_SB(b, h) + boff + n * 2048 + k * 1024); } while (0)
; #define PG8_MMA(ai, bj, At, Bt) do { __builtin_amdgcn_s_setprio(1); _Pragma("unroll") for (int m = 0; m < 4; ++m) _Pragma("unroll") for (int n = 0; n < 2; ++n) _Pragma("unroll") for (int k = 0; k < 2; ++k) \
;         acc[ai][bj][m][n] = mma16_<Epi::BF16>(Bt[n][k], At[m][k], acc[ai][bj][m][n]); __builtin_amdgcn_s_setprio(0); } while (0)
; #define PG8_WAIT_V(n) asm volatile("s_waitcnt vmcnt(" #n ")" ::: "memory")
; #define PG8_WAIT_L(n) asm volatile("s_waitcnt lgkmcnt(" #n ")" ::: "memory")
; #define PG8_BAR __builtin_amdgcn_s_barrier()
; #define PG8_SCHED __builtin_amdgcn_sched_barrier(0)
;     ...
;             const char* a1 = cA + (size_t)(t + 1) * kstep;
;             const char* a2 = last ? nA : cA + (size_t)(t + 2) * kstep; const char* b2 = last ? nB : cB + (size_t)(t + 2) * kstep;
;             const char* a3 = a2 + kstep; const char* b3 = b2 + kstep;
;             if constexpr (SP2) {
;             PG8_LDB(B0, 0, 0); PG8_LDB(B1, 0, 1); PG8_SCHED; PG8_LDA(At, 0, 0); PG8_STAGE(PG8_SA(1, 1), a1 + hA, voffA);
;             PG8_WAIT_V(8); PG8_WAIT_L(0); PG8_BAR; PG8_MMA(0, 0, At, B0); PG8_MMA(0, 1, At, B1); PG8_BAR; PG8_SCHED;
;             PG8_LDA(At, 0, 1); PG8_STAGE(PG8_SB(0, 0), b2, voffB); PG8_STAGE(PG8_SB(0, 1), b2 + hB, voffB); PG8_STAGE(PG8_SA(0, 0), a2, voffA);
;             PG8_WAIT_V(8); PG8_WAIT_L(0); PG8_BAR; if (!cur.half) { PG8_MMA(1, 0, At, B0); PG8_MMA(1, 1, At, B1); } PG8_BAR; PG8_SCHED;
.LBB0_798:
	s_mov_b64 s[24:25], s[10:11]
	s_add_u32 s10, s24, 0x100
	s_addc_u32 s11, s25, 0
	s_add_i32 s40, 0, 0x10000
	s_cmp_eq_u32 s59, 12
	s_cselect_b32 s23, s51, s11
	s_cselect_b32 s22, s50, s10
	v_add_u32_e32 v0, s40, v233
	s_cselect_b32 s21, s2, s58
	s_cselect_b32 s20, s3, s49
	s_add_i32 s41, 0, 0x14000
	ds_read_b128 v[148:151], v0
	ds_read_b128 v[152:155], v0 offset:1024
	ds_read_b128 v[156:159], v0 offset:2048
	ds_read_b128 v[160:163], v0 offset:3072
	v_add_u32_e32 v0, s41, v233
	ds_read_b128 v[132:135], v0
	ds_read_b128 v[136:139], v0 offset:1024
	ds_read_b128 v[140:143], v0 offset:2048
	ds_read_b128 v[144:147], v0 offset:3072
	s_add_i32 m0, s9, 0xc000
	s_waitcnt lgkmcnt(0)
	ds_read_b128 v[164:167], v243
	ds_read_b128 v[168:171], v243 offset:1024
	ds_read_b128 v[172:175], v243 offset:2048
	ds_read_b128 v[176:179], v243 offset:3072
	ds_read_b128 v[180:183], v243 offset:4096
	ds_read_b128 v[184:187], v243 offset:5120
	ds_read_b128 v[188:191], v243 offset:6144
	ds_read_b128 v[192:195], v243 offset:7168
	global_load_lds_dwordx4 v222, s[24:25]
	s_add_i32 m0, s9, 0xe000
	s_nop 0
	global_load_lds_dwordx4 v224, s[24:25]
	s_waitcnt vmcnt(8)
	s_waitcnt lgkmcnt(0)
	s_barrier
	s_setprio 1
	v_mfma_f32_16x16x32_f16 v[128:131], v[148:151], v[164:167], v[128:131]
	v_mfma_f32_16x16x32_f16 v[124:127], v[156:159], v[164:167], v[124:127]
	v_mfma_f32_16x16x32_f16 v[112:115], v[148:151], v[172:175], v[112:115]
	v_mfma_f32_16x16x32_f16 v[108:111], v[156:159], v[172:175], v[108:111]
	v_mfma_f32_16x16x32_f16 v[96:99], v[148:151], v[180:183], v[96:99]
	v_mfma_f32_16x16x32_f16 v[92:95], v[156:159], v[180:183], v[92:95]
	v_mfma_f32_16x16x32_f16 v[80:83], v[148:151], v[188:191], v[80:83]
	v_mfma_f32_16x16x32_f16 v[76:79], v[156:159], v[188:191], v[76:79]
	v_mfma_f32_16x16x32_f16 v[128:131], v[152:155], v[168:171], v[128:131]
	v_mfma_f32_16x16x32_f16 v[124:127], v[160:163], v[168:171], v[124:127]
	v_mfma_f32_16x16x32_f16 v[112:115], v[152:155], v[176:179], v[112:115]
	v_mfma_f32_16x16x32_f16 v[108:111], v[160:163], v[176:179], v[108:111]
	v_mfma_f32_16x16x32_f16 v[96:99], v[152:155], v[184:187], v[96:99]
	v_mfma_f32_16x16x32_f16 v[92:95], v[160:163], v[184:187], v[92:95]
	v_mfma_f32_16x16x32_f16 v[80:83], v[152:155], v[192:195], v[80:83]
	v_mfma_f32_16x16x32_f16 v[76:79], v[160:163], v[192:195], v[76:79]
	s_setprio 0
	s_setprio 1
	v_mfma_f32_16x16x32_f16 v[120:123], v[132:135], v[164:167], v[120:123]
	v_mfma_f32_16x16x32_f16 v[116:119], v[140:143], v[164:167], v[116:119]
	v_mfma_f32_16x16x32_f16 v[104:107], v[132:135], v[172:175], v[104:107]
	v_mfma_f32_16x16x32_f16 v[100:103], v[140:143], v[172:175], v[100:103]
	v_mfma_f32_16x16x32_f16 v[88:91], v[132:135], v[180:183], v[88:91]
	v_mfma_f32_16x16x32_f16 v[84:87], v[140:143], v[180:183], v[84:87]
	v_mfma_f32_16x16x32_f16 v[72:75], v[132:135], v[188:191], v[72:75]
	v_mfma_f32_16x16x32_f16 v[68:71], v[140:143], v[188:191], v[68:71]
	v_mfma_f32_16x16x32_f16 v[120:123], v[136:139], v[168:171], v[120:123]
	v_mfma_f32_16x16x32_f16 v[116:119], v[144:147], v[168:171], v[116:119]
	v_mfma_f32_16x16x32_f16 v[104:107], v[136:139], v[176:179], v[104:107]
	v_mfma_f32_16x16x32_f16 v[100:103], v[144:147], v[176:179], v[100:103]
	v_mfma_f32_16x16x32_f16 v[88:91], v[136:139], v[184:187], v[88:91]
	v_mfma_f32_16x16x32_f16 v[84:87], v[144:147], v[184:187], v[84:87]
	v_mfma_f32_16x16x32_f16 v[72:75], v[136:139], v[192:195], v[72:75]
	v_mfma_f32_16x16x32_f16 v[68:71], v[144:147], v[192:195], v[68:71]
	s_setprio 0
	s_barrier
	s_add_i32 s24, s40, s27
	s_mov_b32 m0, s24
	ds_read_b128 v[188:191], v243 offset:16384
	ds_read_b128 v[192:195], v243 offset:17408
	ds_read_b128 v[180:183], v243 offset:18432
	ds_read_b128 v[184:187], v243 offset:19456
	ds_read_b128 v[172:175], v243 offset:20480
	ds_read_b128 v[176:179], v243 offset:21504
	ds_read_b128 v[164:167], v243 offset:22528
	ds_read_b128 v[168:171], v243 offset:23552
	global_load_lds_dwordx4 v216, s[20:21]
	s_add_i32 m0, s24, 0x2000
	s_add_u32 s24, s20, 0x40000
	s_addc_u32 s25, s21, 0
	s_add_i32 s40, s41, s27
	global_load_lds_dwordx4 v220, s[20:21]
	s_mov_b32 m0, s40
	s_nop 0
	global_load_lds_dwordx4 v216, s[24:25]
	s_add_i32 m0, s40, 0x2000
	s_nop 0
	global_load_lds_dwordx4 v220, s[24:25]
	s_mov_b32 m0, s9
	v_cndmask_b32_e64 v0, 0, 1, s[18:19]
	global_load_lds_dwordx4 v214, s[22:23]
	s_mov_b32 m0, s28
	v_cmp_ne_u32_e64 s[40:41], 1, v0
	global_load_lds_dwordx4 v218, s[22:23]
	s_waitcnt vmcnt(8)
	s_waitcnt lgkmcnt(0)
	s_andn2_b64 vcc, exec, s[18:19]
	s_barrier
	s_cbranch_vccnz .LBB0_800
	s_setprio 1
	v_mfma_f32_16x16x32_f16 v[64:67], v[148:151], v[188:191], v[64:67]
	v_mfma_f32_16x16x32_f16 v[60:63], v[156:159], v[188:191], v[60:63]
	v_mfma_f32_16x16x32_f16 v[48:51], v[148:151], v[180:183], v[48:51]
	v_mfma_f32_16x16x32_f16 v[44:47], v[156:159], v[180:183], v[44:47]
	v_mfma_f32_16x16x32_f16 v[32:35], v[148:151], v[172:175], v[32:35]
	v_mfma_f32_16x16x32_f16 v[28:31], v[156:159], v[172:175], v[28:31]
	v_mfma_f32_16x16x32_f16 v[16:19], v[148:151], v[164:167], v[16:19]
	v_mfma_f32_16x16x32_f16 v[12:15], v[156:159], v[164:167], v[12:15]
	v_mfma_f32_16x16x32_f16 v[64:67], v[152:155], v[192:195], v[64:67]
	v_mfma_f32_16x16x32_f16 v[60:63], v[160:163], v[192:195], v[60:63]
	v_mfma_f32_16x16x32_f16 v[48:51], v[152:155], v[184:187], v[48:51]
	v_mfma_f32_16x16x32_f16 v[44:47], v[160:163], v[184:187], v[44:47]
	v_mfma_f32_16x16x32_f16 v[32:35], v[152:155], v[176:179], v[32:35]
	v_mfma_f32_16x16x32_f16 v[28:31], v[160:163], v[176:179], v[28:31]
	v_mfma_f32_16x16x32_f16 v[16:19], v[152:155], v[168:171], v[16:19]
	v_mfma_f32_16x16x32_f16 v[12:15], v[160:163], v[168:171], v[12:15]
	s_setprio 0
	s_setprio 1
	v_mfma_f32_16x16x32_f16 v[56:59], v[132:135], v[188:191], v[56:59]
	v_mfma_f32_16x16x32_f16 v[52:55], v[140:143], v[188:191], v[52:55]
	v_mfma_f32_16x16x32_f16 v[40:43], v[132:135], v[180:183], v[40:43]
	v_mfma_f32_16x16x32_f16 v[36:39], v[140:143], v[180:183], v[36:39]
	v_mfma_f32_16x16x32_f16 v[24:27], v[132:135], v[172:175], v[24:27]
	v_mfma_f32_16x16x32_f16 v[20:23], v[140:143], v[172:175], v[20:23]
	v_mfma_f32_16x16x32_f16 v[8:11], v[132:135], v[164:167], v[8:11]
	v_mfma_f32_16x16x32_f16 v[4:7], v[140:143], v[164:167], v[4:7]
	v_mfma_f32_16x16x32_f16 v[56:59], v[136:139], v[192:195], v[56:59]
	v_mfma_f32_16x16x32_f16 v[52:55], v[144:147], v[192:195], v[52:55]
	v_mfma_f32_16x16x32_f16 v[40:43], v[136:139], v[184:187], v[40:43]
	v_mfma_f32_16x16x32_f16 v[36:39], v[144:147], v[184:187], v[36:39]
	v_mfma_f32_16x16x32_f16 v[24:27], v[136:139], v[176:179], v[24:27]
	v_mfma_f32_16x16x32_f16 v[20:23], v[144:147], v[176:179], v[20:23]
	v_mfma_f32_16x16x32_f16 v[8:11], v[136:139], v[168:171], v[8:11]
	v_mfma_f32_16x16x32_f16 v[4:7], v[144:147], v[168:171], v[4:7]
	s_setprio 0
; #define PG8_STAGE(bufoff, gbase, voff) do { _Pragma("unroll") for (int _i = 0; _i < 2; ++_i) \
;         __builtin_amdgcn_global_load_lds((const unsigned*)((const char*)(gbase) + (voff)[_i]), (LAS unsigned*)(lds + (bufoff) + ldsw + _i * 8192), 16, 0, 0); } while (0)
; #define PG8_LDA(dst, b, h) do { _Pragma("unroll") for (int m = 0; m < 4; ++m) _Pragma("unroll") for (int k = 0; k < 2; ++k) dst[m][k] = *(const LAS f16x8*)(lds + PG8_SA(b, h) + aoff + m * 2048 + k * 1024); } while (0)
; #define PG8_LDB(dst, b, h) do { _Pragma("unroll") for (int n = 0; n < 2; ++n) _Pragma("unroll") for (int k = 0; k < 2; ++k) dst[n][k] = *(const LAS f16x8*)(lds + PG8_SB(b, h) + boff + n * 2048 + k * 1024); } while (0)
; #define PG8_MMA(ai, bj, At, Bt) do { __builtin_amdgcn_s_setprio(1); _Pragma("unroll") for (int m = 0; m < 4; ++m) _Pragma("unroll") for (int n = 0; n < 2; ++n) _Pragma("unroll") for (int k = 0; k < 2; ++k) \
;         acc[ai][bj][m][n] = mma16_<Epi::BF16>(Bt[n][k], At[m][k], acc[ai][bj][m][n]); __builtin_amdgcn_s_setprio(0); } while (0)
; #define PG8_WAIT_V(n) asm volatile("s_waitcnt vmcnt(" #n ")" ::: "memory")
; #define PG8_WAIT_L(n) asm volatile("s_waitcnt lgkmcnt(" #n ")" ::: "memory")
; #define PG8_BAR __builtin_amdgcn_s_barrier()
; #define PG8_SCHED __builtin_amdgcn_sched_barrier(0)
;     ...
;             PG8_LDB(B0, 1, 0); PG8_LDB(B1, 1, 1); PG8_SCHED; PG8_LDA(At, 1, 0); PG8_STAGE(PG8_SA(0, 1), a2 + hA, voffA);
;             PG8_WAIT_V(8); PG8_WAIT_L(0); PG8_BAR; PG8_MMA(0, 0, At, B0); PG8_MMA(0, 1, At, B1); PG8_BAR; PG8_SCHED;
;             PG8_LDA(At, 1, 1); PG8_STAGE(PG8_SB(1, 0), b3, voffB); PG8_STAGE(PG8_SB(1, 1), b3 + hB, voffB); PG8_STAGE(PG8_SA(1, 0), a3, voffA);
;             PG8_WAIT_V(8); PG8_WAIT_L(0); PG8_BAR; if (!cur.half) { PG8_MMA(1, 0, At, B0); PG8_MMA(1, 1, At, B1); } PG8_BAR; PG8_SCHED;
.LBB0_800:
	s_barrier
	s_add_i32 s24, 0, 0x18000
	v_add_u32_e32 v0, s24, v233
	s_add_i32 s25, 0, 0x1c000
	ds_read_b128 v[148:151], v0
	ds_read_b128 v[152:155], v0 offset:1024
	ds_read_b128 v[156:159], v0 offset:2048
	ds_read_b128 v[160:163], v0 offset:3072
	v_add_u32_e32 v0, s25, v233
	ds_read_b128 v[132:135], v0
	ds_read_b128 v[136:139], v0 offset:1024
	ds_read_b128 v[140:143], v0 offset:2048
	ds_read_b128 v[144:147], v0 offset:3072
	s_add_u32 s22, s22, 0x1a0000
	s_addc_u32 s23, s23, 0
	s_add_u32 s98, s22, 0xffe60080
	s_addc_u32 s99, s23, -1
	s_mov_b32 m0, s29
	s_waitcnt lgkmcnt(0)
	ds_read_b128 v[164:167], v243 offset:32768
	ds_read_b128 v[168:171], v243 offset:33792
	ds_read_b128 v[172:175], v243 offset:34816
	ds_read_b128 v[176:179], v243 offset:35840
	ds_read_b128 v[180:183], v243 offset:36864
	ds_read_b128 v[184:187], v243 offset:37888
	ds_read_b128 v[188:191], v243 offset:38912
	ds_read_b128 v[192:195], v243 offset:39936
	global_load_lds_dwordx4 v214, s[22:23]
	s_mov_b32 m0, s30
	s_nop 0
	global_load_lds_dwordx4 v218, s[22:23]
	s_waitcnt vmcnt(8)
	s_waitcnt lgkmcnt(0)
	s_barrier
	s_setprio 1
	v_mfma_f32_16x16x32_f16 v[128:131], v[148:151], v[164:167], v[128:131]
	v_mfma_f32_16x16x32_f16 v[124:127], v[156:159], v[164:167], v[124:127]
	v_mfma_f32_16x16x32_f16 v[112:115], v[148:151], v[172:175], v[112:115]
	v_mfma_f32_16x16x32_f16 v[108:111], v[156:159], v[172:175], v[108:111]
	v_mfma_f32_16x16x32_f16 v[96:99], v[148:151], v[180:183], v[96:99]
	v_mfma_f32_16x16x32_f16 v[92:95], v[156:159], v[180:183], v[92:95]
	v_mfma_f32_16x16x32_f16 v[80:83], v[148:151], v[188:191], v[80:83]
	v_mfma_f32_16x16x32_f16 v[76:79], v[156:159], v[188:191], v[76:79]
	v_mfma_f32_16x16x32_f16 v[128:131], v[152:155], v[168:171], v[128:131]
	v_mfma_f32_16x16x32_f16 v[124:127], v[160:163], v[168:171], v[124:127]
	v_mfma_f32_16x16x32_f16 v[112:115], v[152:155], v[176:179], v[112:115]
	v_mfma_f32_16x16x32_f16 v[108:111], v[160:163], v[176:179], v[108:111]
	v_mfma_f32_16x16x32_f16 v[96:99], v[152:155], v[184:187], v[96:99]
	v_mfma_f32_16x16x32_f16 v[92:95], v[160:163], v[184:187], v[92:95]
	v_mfma_f32_16x16x32_f16 v[80:83], v[152:155], v[192:195], v[80:83]
	v_mfma_f32_16x16x32_f16 v[76:79], v[160:163], v[192:195], v[76:79]
	s_setprio 0
	s_setprio 1
	v_mfma_f32_16x16x32_f16 v[120:123], v[132:135], v[164:167], v[120:123]
	v_mfma_f32_16x16x32_f16 v[116:119], v[140:143], v[164:167], v[116:119]
	v_mfma_f32_16x16x32_f16 v[104:107], v[132:135], v[172:175], v[104:107]
	v_mfma_f32_16x16x32_f16 v[100:103], v[140:143], v[172:175], v[100:103]
	v_mfma_f32_16x16x32_f16 v[88:91], v[132:135], v[180:183], v[88:91]
	v_mfma_f32_16x16x32_f16 v[84:87], v[140:143], v[180:183], v[84:87]
	v_mfma_f32_16x16x32_f16 v[72:75], v[132:135], v[188:191], v[72:75]
	v_mfma_f32_16x16x32_f16 v[68:71], v[140:143], v[188:191], v[68:71]
	v_mfma_f32_16x16x32_f16 v[120:123], v[136:139], v[168:171], v[120:123]
	v_mfma_f32_16x16x32_f16 v[116:119], v[144:147], v[168:171], v[116:119]
	v_mfma_f32_16x16x32_f16 v[104:107], v[136:139], v[176:179], v[104:107]
	v_mfma_f32_16x16x32_f16 v[100:103], v[144:147], v[176:179], v[100:103]
	v_mfma_f32_16x16x32_f16 v[88:91], v[136:139], v[184:187], v[88:91]
	v_mfma_f32_16x16x32_f16 v[84:87], v[144:147], v[184:187], v[84:87]
	v_mfma_f32_16x16x32_f16 v[72:75], v[136:139], v[192:195], v[72:75]
	v_mfma_f32_16x16x32_f16 v[68:71], v[144:147], v[192:195], v[68:71]
	s_setprio 0
	s_barrier
	s_add_i32 s22, s24, s27
	s_add_u32 s20, s20, 0x80
	s_addc_u32 s21, s21, 0
	s_mov_b32 m0, s22
	ds_read_b128 v[188:191], v243 offset:49152
	ds_read_b128 v[192:195], v243 offset:50176
	ds_read_b128 v[180:183], v243 offset:51200
	ds_read_b128 v[184:187], v243 offset:52224
	ds_read_b128 v[172:175], v243 offset:53248
	ds_read_b128 v[176:179], v243 offset:54272
	ds_read_b128 v[164:167], v243 offset:55296
	ds_read_b128 v[168:171], v243 offset:56320
	global_load_lds_dwordx4 v216, s[20:21]
	s_add_i32 m0, s22, 0x2000
	s_add_i32 s22, s25, s27
	global_load_lds_dwordx4 v220, s[20:21]
	s_add_u32 s20, s20, 0x40000
	s_addc_u32 s21, s21, 0
	s_mov_b32 m0, s22
	s_and_b64 vcc, exec, s[40:41]
	global_load_lds_dwordx4 v216, s[20:21]
	s_add_i32 m0, s22, 0x2000
	s_nop 0
	global_load_lds_dwordx4 v220, s[20:21]
	s_mov_b32 m0, s31
	s_nop 0
	global_load_lds_dwordx4 v214, s[98:99]
	s_mov_b32 m0, s34
	s_nop 0
	global_load_lds_dwordx4 v218, s[98:99]
	s_waitcnt vmcnt(8)
	s_waitcnt lgkmcnt(0)
	s_barrier
	s_cbranch_vccnz .LBB0_797
	s_setprio 1
	v_mfma_f32_16x16x32_f16 v[64:67], v[148:151], v[188:191], v[64:67]
	v_mfma_f32_16x16x32_f16 v[60:63], v[156:159], v[188:191], v[60:63]
	v_mfma_f32_16x16x32_f16 v[48:51], v[148:151], v[180:183], v[48:51]
	v_mfma_f32_16x16x32_f16 v[44:47], v[156:159], v[180:183], v[44:47]
	v_mfma_f32_16x16x32_f16 v[32:35], v[148:151], v[172:175], v[32:35]
	v_mfma_f32_16x16x32_f16 v[28:31], v[156:159], v[172:175], v[28:31]
	v_mfma_f32_16x16x32_f16 v[16:19], v[148:151], v[164:167], v[16:19]
	v_mfma_f32_16x16x32_f16 v[12:15], v[156:159], v[164:167], v[12:15]
	v_mfma_f32_16x16x32_f16 v[64:67], v[152:155], v[192:195], v[64:67]
	v_mfma_f32_16x16x32_f16 v[60:63], v[160:163], v[192:195], v[60:63]
	v_mfma_f32_16x16x32_f16 v[48:51], v[152:155], v[184:187], v[48:51]
	v_mfma_f32_16x16x32_f16 v[44:47], v[160:163], v[184:187], v[44:47]
	v_mfma_f32_16x16x32_f16 v[32:35], v[152:155], v[176:179], v[32:35]
	v_mfma_f32_16x16x32_f16 v[28:31], v[160:163], v[176:179], v[28:31]
	v_mfma_f32_16x16x32_f16 v[16:19], v[152:155], v[168:171], v[16:19]
	v_mfma_f32_16x16x32_f16 v[12:15], v[160:163], v[168:171], v[12:15]
	s_setprio 0
	s_setprio 1
	v_mfma_f32_16x16x32_f16 v[56:59], v[132:135], v[188:191], v[56:59]
	v_mfma_f32_16x16x32_f16 v[52:55], v[140:143], v[188:191], v[52:55]
	v_mfma_f32_16x16x32_f16 v[40:43], v[132:135], v[180:183], v[40:43]
	v_mfma_f32_16x16x32_f16 v[36:39], v[140:143], v[180:183], v[36:39]
	v_mfma_f32_16x16x32_f16 v[24:27], v[132:135], v[172:175], v[24:27]
	v_mfma_f32_16x16x32_f16 v[20:23], v[140:143], v[172:175], v[20:23]
	v_mfma_f32_16x16x32_f16 v[8:11], v[132:135], v[164:167], v[8:11]
	v_mfma_f32_16x16x32_f16 v[2:5], v[140:143], v[164:167], v[4:7]
	v_mfma_f32_16x16x32_f16 v[56:59], v[136:139], v[192:195], v[56:59]
	v_mfma_f32_16x16x32_f16 v[52:55], v[144:147], v[192:195], v[52:55]
	v_mfma_f32_16x16x32_f16 v[40:43], v[136:139], v[184:187], v[40:43]
	v_mfma_f32_16x16x32_f16 v[36:39], v[144:147], v[184:187], v[36:39]
	v_mfma_f32_16x16x32_f16 v[24:27], v[136:139], v[176:179], v[24:27]
	v_mfma_f32_16x16x32_f16 v[20:23], v[144:147], v[176:179], v[20:23]
	v_mfma_f32_16x16x32_f16 v[8:11], v[136:139], v[168:171], v[8:11]
	v_mfma_f32_16x16x32_f16 v[4:7], v[144:147], v[168:171], v[2:5]
	s_setprio 0
	s_branch .LBB0_797

; #define PG8_STAGE(bufoff, gbase, voff) do { _Pragma("unroll") for (int _i = 0; _i < 2; ++_i) \
;         __builtin_amdgcn_global_load_lds((const unsigned*)((const char*)(gbase) + (voff)[_i]), (LAS unsigned*)(lds + (bufoff) + ldsw + _i * 8192), 16, 0, 0); } while (0)
; #define PG8_LDA(dst, b, h) do { _Pragma("unroll") for (int m = 0; m < 4; ++m) _Pragma("unroll") for (int k = 0; k < 2; ++k) dst[m][k] = *(const LAS f16x8*)(lds + PG8_SA(b, h) + aoff + m * 2048 + k * 1024); } while (0)
; #define PG8_LDB(dst, b, h) do { _Pragma("unroll") for (int n = 0; n < 2; ++n) _Pragma("unroll") for (int k = 0; k < 2; ++k) dst[n][k] = *(const LAS f16x8*)(lds + PG8_SB(b, h) + boff + n * 2048 + k * 1024); } while (0)
; #define PG8_MMA(ai, bj, At, Bt) do { __builtin_amdgcn_s_setprio(1); _Pragma("unroll") for (int m = 0; m < 4; ++m) _Pragma("unroll") for (int n = 0; n < 2; ++n) _Pragma("unroll") for (int k = 0; k < 2; ++k) \
;         acc[ai][bj][m][n] = mma16_<Epi::BF16>(Bt[n][k], At[m][k], acc[ai][bj][m][n]); __builtin_amdgcn_s_setprio(0); } while (0)
; #define PG8_WAIT_V(n) asm volatile("s_waitcnt vmcnt(" #n ")" ::: "memory")
; #define PG8_WAIT_L(n) asm volatile("s_waitcnt lgkmcnt(" #n ")" ::: "memory")
; #define PG8_BAR __builtin_amdgcn_s_barrier()
; #define PG8_SCHED __builtin_amdgcn_sched_barrier(0)
;     ...
;             const char* a1 = cA + (size_t)(t + 1) * kstep;
;             const char* a2 = last ? nA : cA + (size_t)(t + 2) * kstep; const char* b2 = last ? nB : cB + (size_t)(t + 2) * kstep;
;             const char* a3 = a2 + kstep; const char* b3 = b2 + kstep;
;             if constexpr (SP2) {
;             PG8_LDB(B0, 0, 0); PG8_LDB(B1, 0, 1); PG8_SCHED; PG8_LDA(At, 0, 0); PG8_STAGE(PG8_SA(1, 1), a1 + hA, voffA);
;             PG8_WAIT_V(8); PG8_WAIT_L(0); PG8_BAR; PG8_MMA(0, 0, At, B0); PG8_MMA(0, 1, At, B1); PG8_BAR; PG8_SCHED;
;             PG8_LDA(At, 0, 1); PG8_STAGE(PG8_SB(0, 0), b2, voffB); PG8_STAGE(PG8_SB(0, 1), b2 + hB, voffB); PG8_STAGE(PG8_SA(0, 0), a2, voffA);
;             PG8_WAIT_V(8); PG8_WAIT_L(0); PG8_BAR; if (!cur.half) { PG8_MMA(1, 0, At, B0); PG8_MMA(1, 1, At, B1); } PG8_BAR; PG8_SCHED;
.LBB0_886:
	s_add_u32 s25, s36, 0xfffc0080
	s_addc_u32 s27, s37, -1
	s_add_i32 s40, 0, 0x10000
	s_cmp_eq_u32 s14, 12
	s_cselect_b32 s45, s29, s27
	s_cselect_b32 s44, s28, s25
	s_waitcnt lgkmcnt(0)
	v_add_u32_e32 v106, s40, v244
	s_cselect_b32 s43, s2, s11
	s_cselect_b32 s42, s3, s9
	s_add_i32 s25, 0, 0x14000
	ds_read_b128 v[154:157], v106
	ds_read_b128 v[158:161], v106 offset:1024
	ds_read_b128 v[162:165], v106 offset:2048
	ds_read_b128 v[166:169], v106 offset:3072
	v_add_u32_e32 v106, s25, v244
	ds_read_b128 v[138:141], v106
	ds_read_b128 v[142:145], v106 offset:1024
	ds_read_b128 v[146:149], v106 offset:2048
	ds_read_b128 v[150:153], v106 offset:3072
	s_add_i32 m0, s51, 0xc000
	ds_read_b128 v[170:173], v245
	ds_read_b128 v[174:177], v245 offset:1024
	ds_read_b128 v[178:181], v245 offset:2048
	ds_read_b128 v[182:185], v245 offset:3072
	ds_read_b128 v[186:189], v245 offset:4096
	ds_read_b128 v[190:193], v245 offset:5120
	ds_read_b128 v[226:229], v245 offset:6144
	ds_read_b128 v[230:233], v245 offset:7168
	global_load_lds_dwordx4 v222, s[36:37]
	s_add_i32 m0, s51, 0xe000
	s_nop 0
	global_load_lds_dwordx4 v224, s[36:37]
	s_waitcnt vmcnt(8)
	s_waitcnt lgkmcnt(0)
	s_barrier
	s_setprio 1
	v_mfma_f32_16x16x32_bf16 v[106:109], v[154:157], v[170:173], v[134:137]
	v_mfma_f32_16x16x32_bf16 v[110:113], v[162:165], v[170:173], v[130:133]
	v_mfma_f32_16x16x32_bf16 v[126:129], v[154:157], v[178:181], v[126:129]
	v_mfma_f32_16x16x32_bf16 v[122:125], v[162:165], v[178:181], v[122:125]
	v_mfma_f32_16x16x32_bf16 v[118:121], v[154:157], v[186:189], v[118:121]
	v_mfma_f32_16x16x32_bf16 v[114:117], v[162:165], v[186:189], v[114:117]
	v_mfma_f32_16x16x32_bf16 v[102:105], v[154:157], v[226:229], v[102:105]
	v_mfma_f32_16x16x32_bf16 v[98:101], v[162:165], v[226:229], v[98:101]
	v_mfma_f32_16x16x32_bf16 v[106:109], v[158:161], v[174:177], v[106:109]
	v_mfma_f32_16x16x32_bf16 v[110:113], v[166:169], v[174:177], v[110:113]
	v_mfma_f32_16x16x32_bf16 v[126:129], v[158:161], v[182:185], v[126:129]
	v_mfma_f32_16x16x32_bf16 v[122:125], v[166:169], v[182:185], v[122:125]
	v_mfma_f32_16x16x32_bf16 v[118:121], v[158:161], v[190:193], v[118:121]
	v_mfma_f32_16x16x32_bf16 v[114:117], v[166:169], v[190:193], v[114:117]
	v_mfma_f32_16x16x32_bf16 v[102:105], v[158:161], v[230:233], v[102:105]
	v_mfma_f32_16x16x32_bf16 v[98:101], v[166:169], v[230:233], v[98:101]
	s_setprio 0
	s_setprio 1
	v_mfma_f32_16x16x32_bf16 v[70:73], v[138:141], v[170:173], v[70:73]
	v_mfma_f32_16x16x32_bf16 v[66:69], v[146:149], v[170:173], v[66:69]
	v_mfma_f32_16x16x32_bf16 v[58:61], v[138:141], v[178:181], v[58:61]
	v_mfma_f32_16x16x32_bf16 v[50:53], v[146:149], v[178:181], v[50:53]
	v_mfma_f32_16x16x32_bf16 v[46:49], v[138:141], v[186:189], v[46:49]
	v_mfma_f32_16x16x32_bf16 v[42:45], v[146:149], v[186:189], v[42:45]
	v_mfma_f32_16x16x32_bf16 v[38:41], v[138:141], v[226:229], v[38:41]
	v_mfma_f32_16x16x32_bf16 v[34:37], v[146:149], v[226:229], v[34:37]
	v_mfma_f32_16x16x32_bf16 v[70:73], v[142:145], v[174:177], v[70:73]
	v_mfma_f32_16x16x32_bf16 v[66:69], v[150:153], v[174:177], v[66:69]
	v_mfma_f32_16x16x32_bf16 v[58:61], v[142:145], v[182:185], v[58:61]
	v_mfma_f32_16x16x32_bf16 v[50:53], v[150:153], v[182:185], v[50:53]
	v_mfma_f32_16x16x32_bf16 v[46:49], v[142:145], v[190:193], v[46:49]
	v_mfma_f32_16x16x32_bf16 v[42:45], v[150:153], v[190:193], v[42:45]
	v_mfma_f32_16x16x32_bf16 v[38:41], v[142:145], v[230:233], v[38:41]
	v_mfma_f32_16x16x32_bf16 v[34:37], v[150:153], v[230:233], v[34:37]
	s_setprio 0
	s_barrier
	s_add_i32 s27, s40, s50
	s_mov_b32 m0, s27
	ds_read_b128 v[186:189], v245 offset:16384
	ds_read_b128 v[190:193], v245 offset:17408
	ds_read_b128 v[178:181], v245 offset:18432
	ds_read_b128 v[182:185], v245 offset:19456
	ds_read_b128 v[170:173], v245 offset:20480
	ds_read_b128 v[174:177], v245 offset:21504
	ds_read_b128 v[130:133], v245 offset:22528
	ds_read_b128 v[134:137], v245 offset:23552
	global_load_lds_dwordx4 v214, s[42:43]
	s_add_i32 m0, s27, 0x2000
	s_add_u32 s40, s42, 0x40000
	s_addc_u32 s41, s43, 0
	s_add_i32 s25, s25, s50
	global_load_lds_dwordx4 v218, s[42:43]
	s_mov_b32 m0, s25
	s_nop 0
	global_load_lds_dwordx4 v214, s[40:41]
	s_add_i32 m0, s25, 0x2000
	s_nop 0
	global_load_lds_dwordx4 v218, s[40:41]
	s_mov_b32 m0, s51
	v_cndmask_b32_e64 v200, 0, 1, s[34:35]
	global_load_lds_dwordx4 v194, s[44:45]
	s_mov_b32 m0, s52
	v_cmp_ne_u32_e64 s[40:41], 1, v200
	global_load_lds_dwordx4 v216, s[44:45]
	s_waitcnt vmcnt(8)
	s_waitcnt lgkmcnt(0)
	s_andn2_b64 vcc, exec, s[34:35]
	s_barrier
	s_cbranch_vccnz .LBB0_888
	s_setprio 1
	v_mfma_f32_16x16x32_bf16 v[94:97], v[154:157], v[186:189], v[94:97]
	v_mfma_f32_16x16x32_bf16 v[90:93], v[162:165], v[186:189], v[90:93]
	v_mfma_f32_16x16x32_bf16 v[86:89], v[154:157], v[178:181], v[86:89]
	v_mfma_f32_16x16x32_bf16 v[82:85], v[162:165], v[178:181], v[82:85]
	v_mfma_f32_16x16x32_bf16 v[78:81], v[154:157], v[170:173], v[78:81]
	v_mfma_f32_16x16x32_bf16 v[74:77], v[162:165], v[170:173], v[74:77]
	v_mfma_f32_16x16x32_bf16 v[62:65], v[154:157], v[130:133], v[62:65]
	v_mfma_f32_16x16x32_bf16 v[54:57], v[162:165], v[130:133], v[54:57]
	v_mfma_f32_16x16x32_bf16 v[94:97], v[158:161], v[190:193], v[94:97]
	v_mfma_f32_16x16x32_bf16 v[90:93], v[166:169], v[190:193], v[90:93]
	v_mfma_f32_16x16x32_bf16 v[86:89], v[158:161], v[182:185], v[86:89]
	v_mfma_f32_16x16x32_bf16 v[82:85], v[166:169], v[182:185], v[82:85]
	v_mfma_f32_16x16x32_bf16 v[78:81], v[158:161], v[174:177], v[78:81]
	v_mfma_f32_16x16x32_bf16 v[74:77], v[166:169], v[174:177], v[74:77]
	v_mfma_f32_16x16x32_bf16 v[62:65], v[158:161], v[134:137], v[62:65]
	v_mfma_f32_16x16x32_bf16 v[54:57], v[166:169], v[134:137], v[54:57]
	s_setprio 0
	s_setprio 1
	v_mfma_f32_16x16x32_bf16 v[30:33], v[138:141], v[186:189], v[30:33]
	v_mfma_f32_16x16x32_bf16 v[26:29], v[146:149], v[186:189], v[26:29]
	v_mfma_f32_16x16x32_bf16 v[22:25], v[138:141], v[178:181], v[22:25]
	v_mfma_f32_16x16x32_bf16 v[18:21], v[146:149], v[178:181], v[18:21]
	v_mfma_f32_16x16x32_bf16 v[14:17], v[138:141], v[170:173], v[14:17]
	v_mfma_f32_16x16x32_bf16 v[10:13], v[146:149], v[170:173], v[10:13]
	v_mfma_f32_16x16x32_bf16 v[6:9], v[138:141], v[130:133], v[6:9]
	v_mfma_f32_16x16x32_bf16 v[2:5], v[146:149], v[130:133], v[2:5]
	v_mfma_f32_16x16x32_bf16 v[30:33], v[142:145], v[190:193], v[30:33]
	v_mfma_f32_16x16x32_bf16 v[26:29], v[150:153], v[190:193], v[26:29]
	v_mfma_f32_16x16x32_bf16 v[22:25], v[142:145], v[182:185], v[22:25]
	v_mfma_f32_16x16x32_bf16 v[18:21], v[150:153], v[182:185], v[18:21]
	v_mfma_f32_16x16x32_bf16 v[14:17], v[142:145], v[174:177], v[14:17]
	v_mfma_f32_16x16x32_bf16 v[10:13], v[150:153], v[174:177], v[10:13]
	v_mfma_f32_16x16x32_bf16 v[6:9], v[142:145], v[134:137], v[6:9]
	v_mfma_f32_16x16x32_bf16 v[2:5], v[150:153], v[134:137], v[2:5]
	s_setprio 0
; #define PG8_STAGE(bufoff, gbase, voff) do { _Pragma("unroll") for (int _i = 0; _i < 2; ++_i) \
;         __builtin_amdgcn_global_load_lds((const unsigned*)((const char*)(gbase) + (voff)[_i]), (LAS unsigned*)(lds + (bufoff) + ldsw + _i * 8192), 16, 0, 0); } while (0)
; #define PG8_LDA(dst, b, h) do { _Pragma("unroll") for (int m = 0; m < 4; ++m) _Pragma("unroll") for (int k = 0; k < 2; ++k) dst[m][k] = *(const LAS f16x8*)(lds + PG8_SA(b, h) + aoff + m * 2048 + k * 1024); } while (0)
; #define PG8_LDB(dst, b, h) do { _Pragma("unroll") for (int n = 0; n < 2; ++n) _Pragma("unroll") for (int k = 0; k < 2; ++k) dst[n][k] = *(const LAS f16x8*)(lds + PG8_SB(b, h) + boff + n * 2048 + k * 1024); } while (0)
; #define PG8_MMA(ai, bj, At, Bt) do { __builtin_amdgcn_s_setprio(1); _Pragma("unroll") for (int m = 0; m < 4; ++m) _Pragma("unroll") for (int n = 0; n < 2; ++n) _Pragma("unroll") for (int k = 0; k < 2; ++k) \
;         acc[ai][bj][m][n] = mma16_<Epi::BF16>(Bt[n][k], At[m][k], acc[ai][bj][m][n]); __builtin_amdgcn_s_setprio(0); } while (0)
; #define PG8_WAIT_V(n) asm volatile("s_waitcnt vmcnt(" #n ")" ::: "memory")
; #define PG8_WAIT_L(n) asm volatile("s_waitcnt lgkmcnt(" #n ")" ::: "memory")
; #define PG8_BAR __builtin_amdgcn_s_barrier()
; #define PG8_SCHED __builtin_amdgcn_sched_barrier(0)
;     ...
;             PG8_LDB(B0, 1, 0); PG8_LDB(B1, 1, 1); PG8_SCHED; PG8_LDA(At, 1, 0); PG8_STAGE(PG8_SA(0, 1), a2 + hA, voffA);
;             PG8_WAIT_V(8); PG8_WAIT_L(0); PG8_BAR; PG8_MMA(0, 0, At, B0); PG8_MMA(0, 1, At, B1); PG8_BAR; PG8_SCHED;
;             PG8_LDA(At, 1, 1); PG8_STAGE(PG8_SB(1, 0), b3, voffB); PG8_STAGE(PG8_SB(1, 1), b3 + hB, voffB); PG8_STAGE(PG8_SA(1, 0), a3, voffA);
;             PG8_WAIT_V(8); PG8_WAIT_L(0); PG8_BAR; if (!cur.half) { PG8_MMA(1, 0, At, B0); PG8_MMA(1, 1, At, B1); } PG8_BAR; PG8_SCHED;
.LBB0_888:
	s_barrier
	s_add_i32 s25, 0, 0x18000
	s_waitcnt lgkmcnt(0)
	v_add_u32_e32 v130, s25, v244
	s_add_i32 s27, 0, 0x1c000
	ds_read_b128 v[154:157], v130
	ds_read_b128 v[158:161], v130 offset:1024
	ds_read_b128 v[162:165], v130 offset:2048
	ds_read_b128 v[166:169], v130 offset:3072
	v_add_u32_e32 v130, s27, v244
	ds_read_b128 v[138:141], v130
	ds_read_b128 v[142:145], v130 offset:1024
	ds_read_b128 v[146:149], v130 offset:2048
	ds_read_b128 v[150:153], v130 offset:3072
	s_add_u32 s44, s44, 0x40000
	s_addc_u32 s45, s45, 0
	s_add_u32 s98, s44, 0xfffc0080
	s_addc_u32 s99, s45, -1
	s_mov_b32 m0, s53
	ds_read_b128 v[170:173], v245 offset:32768
	ds_read_b128 v[174:177], v245 offset:33792
	ds_read_b128 v[178:181], v245 offset:34816
	ds_read_b128 v[182:185], v245 offset:35840
	ds_read_b128 v[186:189], v245 offset:36864
	ds_read_b128 v[190:193], v245 offset:37888
	ds_read_b128 v[246:249], v245 offset:38912
	ds_read_b128 v[200:203], v245 offset:39936
	global_load_lds_dwordx4 v194, s[44:45]
	s_mov_b32 m0, s54
	s_nop 0
	global_load_lds_dwordx4 v216, s[44:45]
	s_waitcnt vmcnt(8)
	s_waitcnt lgkmcnt(0)
	s_barrier
	s_setprio 1
	v_mfma_f32_16x16x32_bf16 v[106:109], v[154:157], v[170:173], v[106:109]
	v_mfma_f32_16x16x32_bf16 v[134:137], v[158:161], v[174:177], v[106:109]
	v_mfma_f32_16x16x32_bf16 v[106:109], v[162:165], v[170:173], v[110:113]
	v_mfma_f32_16x16x32_bf16 v[130:133], v[166:169], v[174:177], v[106:109]
	v_mfma_f32_16x16x32_bf16 v[106:109], v[154:157], v[178:181], v[126:129]
	v_mfma_f32_16x16x32_bf16 v[126:129], v[158:161], v[182:185], v[106:109]
	v_mfma_f32_16x16x32_bf16 v[106:109], v[162:165], v[178:181], v[122:125]
	v_mfma_f32_16x16x32_bf16 v[122:125], v[166:169], v[182:185], v[106:109]
	v_mfma_f32_16x16x32_bf16 v[106:109], v[154:157], v[186:189], v[118:121]
	v_mfma_f32_16x16x32_bf16 v[118:121], v[158:161], v[190:193], v[106:109]
	v_mfma_f32_16x16x32_bf16 v[106:109], v[162:165], v[186:189], v[114:117]
	v_mfma_f32_16x16x32_bf16 v[102:105], v[154:157], v[246:249], v[102:105]
	v_mfma_f32_16x16x32_bf16 v[98:101], v[162:165], v[246:249], v[98:101]
	v_mfma_f32_16x16x32_bf16 v[114:117], v[166:169], v[190:193], v[106:109]
	v_mfma_f32_16x16x32_bf16 v[102:105], v[158:161], v[200:203], v[102:105]
	v_mfma_f32_16x16x32_bf16 v[98:101], v[166:169], v[200:203], v[98:101]
	s_setprio 0
	s_setprio 1
	v_mfma_f32_16x16x32_bf16 v[70:73], v[138:141], v[170:173], v[70:73]
	v_mfma_f32_16x16x32_bf16 v[66:69], v[146:149], v[170:173], v[66:69]
	v_mfma_f32_16x16x32_bf16 v[58:61], v[138:141], v[178:181], v[58:61]
	v_mfma_f32_16x16x32_bf16 v[50:53], v[146:149], v[178:181], v[50:53]
	v_mfma_f32_16x16x32_bf16 v[46:49], v[138:141], v[186:189], v[46:49]
	v_mfma_f32_16x16x32_bf16 v[42:45], v[146:149], v[186:189], v[42:45]
	v_mfma_f32_16x16x32_bf16 v[38:41], v[138:141], v[246:249], v[38:41]
	v_mfma_f32_16x16x32_bf16 v[34:37], v[146:149], v[246:249], v[34:37]
	v_mfma_f32_16x16x32_bf16 v[70:73], v[142:145], v[174:177], v[70:73]
	v_mfma_f32_16x16x32_bf16 v[66:69], v[150:153], v[174:177], v[66:69]
	v_mfma_f32_16x16x32_bf16 v[58:61], v[142:145], v[182:185], v[58:61]
	v_mfma_f32_16x16x32_bf16 v[50:53], v[150:153], v[182:185], v[50:53]
	v_mfma_f32_16x16x32_bf16 v[46:49], v[142:145], v[190:193], v[46:49]
	v_mfma_f32_16x16x32_bf16 v[42:45], v[150:153], v[190:193], v[42:45]
	v_mfma_f32_16x16x32_bf16 v[38:41], v[142:145], v[200:203], v[38:41]
	v_mfma_f32_16x16x32_bf16 v[34:37], v[150:153], v[200:203], v[34:37]
	s_setprio 0
	s_barrier
	s_add_i32 s25, s25, s50
	s_add_u32 s42, s42, 0x80
	s_addc_u32 s43, s43, 0
	s_mov_b32 m0, s25
	ds_read_b128 v[186:189], v245 offset:49152
	ds_read_b128 v[190:193], v245 offset:50176
	ds_read_b128 v[178:181], v245 offset:51200
	ds_read_b128 v[182:185], v245 offset:52224
	ds_read_b128 v[170:173], v245 offset:53248
	ds_read_b128 v[174:177], v245 offset:54272
	ds_read_b128 v[106:109], v245 offset:55296
	ds_read_b128 v[110:113], v245 offset:56320
	global_load_lds_dwordx4 v214, s[42:43]
	s_add_i32 m0, s25, 0x2000
	s_add_i32 s25, s27, s50
	global_load_lds_dwordx4 v218, s[42:43]
	s_add_u32 s42, s42, 0x40000
	s_addc_u32 s43, s43, 0
	s_mov_b32 m0, s25
	s_and_b64 vcc, exec, s[40:41]
	global_load_lds_dwordx4 v214, s[42:43]
	s_add_i32 m0, s25, 0x2000
	s_nop 0
	global_load_lds_dwordx4 v218, s[42:43]
	s_mov_b32 m0, s57
	s_nop 0
	global_load_lds_dwordx4 v194, s[98:99]
	s_mov_b32 m0, s58
	s_nop 0
	global_load_lds_dwordx4 v216, s[98:99]
	s_waitcnt vmcnt(8)
	s_waitcnt lgkmcnt(0)
	s_barrier
	s_cbranch_vccnz .LBB0_885
	s_setprio 1
	v_mfma_f32_16x16x32_bf16 v[94:97], v[154:157], v[186:189], v[94:97]
	v_mfma_f32_16x16x32_bf16 v[90:93], v[162:165], v[186:189], v[90:93]
	v_mfma_f32_16x16x32_bf16 v[86:89], v[154:157], v[178:181], v[86:89]
	v_mfma_f32_16x16x32_bf16 v[82:85], v[162:165], v[178:181], v[82:85]
	v_mfma_f32_16x16x32_bf16 v[78:81], v[154:157], v[170:173], v[78:81]
	v_mfma_f32_16x16x32_bf16 v[74:77], v[162:165], v[170:173], v[74:77]
	v_mfma_f32_16x16x32_bf16 v[62:65], v[154:157], v[106:109], v[62:65]
	v_mfma_f32_16x16x32_bf16 v[54:57], v[162:165], v[106:109], v[54:57]
	v_mfma_f32_16x16x32_bf16 v[94:97], v[158:161], v[190:193], v[94:97]
	v_mfma_f32_16x16x32_bf16 v[90:93], v[166:169], v[190:193], v[90:93]
	v_mfma_f32_16x16x32_bf16 v[86:89], v[158:161], v[182:185], v[86:89]
	v_mfma_f32_16x16x32_bf16 v[82:85], v[166:169], v[182:185], v[82:85]
	v_mfma_f32_16x16x32_bf16 v[78:81], v[158:161], v[174:177], v[78:81]
	v_mfma_f32_16x16x32_bf16 v[74:77], v[166:169], v[174:177], v[74:77]
	v_mfma_f32_16x16x32_bf16 v[62:65], v[158:161], v[110:113], v[62:65]
	v_mfma_f32_16x16x32_bf16 v[54:57], v[166:169], v[110:113], v[54:57]
	s_setprio 0
	s_setprio 1
	v_mfma_f32_16x16x32_bf16 v[30:33], v[138:141], v[186:189], v[30:33]
	v_mfma_f32_16x16x32_bf16 v[26:29], v[146:149], v[186:189], v[26:29]
	v_mfma_f32_16x16x32_bf16 v[22:25], v[138:141], v[178:181], v[22:25]
	v_mfma_f32_16x16x32_bf16 v[18:21], v[146:149], v[178:181], v[18:21]
	v_mfma_f32_16x16x32_bf16 v[14:17], v[138:141], v[170:173], v[14:17]
	v_mfma_f32_16x16x32_bf16 v[10:13], v[146:149], v[170:173], v[10:13]
	v_mfma_f32_16x16x32_bf16 v[6:9], v[138:141], v[106:109], v[6:9]
	v_mfma_f32_16x16x32_bf16 v[2:5], v[146:149], v[106:109], v[2:5]
	v_mfma_f32_16x16x32_bf16 v[30:33], v[142:145], v[190:193], v[30:33]
	v_mfma_f32_16x16x32_bf16 v[26:29], v[150:153], v[190:193], v[26:29]
	v_mfma_f32_16x16x32_bf16 v[22:25], v[142:145], v[182:185], v[22:25]
	v_mfma_f32_16x16x32_bf16 v[18:21], v[150:153], v[182:185], v[18:21]
	v_mfma_f32_16x16x32_bf16 v[14:17], v[142:145], v[174:177], v[14:17]
	v_mfma_f32_16x16x32_bf16 v[10:13], v[150:153], v[174:177], v[10:13]
	v_mfma_f32_16x16x32_bf16 v[6:9], v[142:145], v[110:113], v[6:9]
	v_mfma_f32_16x16x32_bf16 v[2:5], v[150:153], v[110:113], v[2:5]
	s_setprio 0
	s_branch .LBB0_885

; #define PG8_STAGE(bufoff, gbase, voff) do { _Pragma("unroll") for (int _i = 0; _i < 2; ++_i) \
;         __builtin_amdgcn_global_load_lds((const unsigned*)((const char*)(gbase) + (voff)[_i]), (LAS unsigned*)(lds + (bufoff) + ldsw + _i * 8192), 16, 0, 0); } while (0)
; #define PG8_LDA(dst, b, h) do { _Pragma("unroll") for (int m = 0; m < 4; ++m) _Pragma("unroll") for (int k = 0; k < 2; ++k) dst[m][k] = *(const LAS f16x8*)(lds + PG8_SA(b, h) + aoff + m * 2048 + k * 1024); } while (0)
; #define PG8_LDB(dst, b, h) do { _Pragma("unroll") for (int n = 0; n < 2; ++n) _Pragma("unroll") for (int k = 0; k < 2; ++k) dst[n][k] = *(const LAS f16x8*)(lds + PG8_SB(b, h) + boff + n * 2048 + k * 1024); } while (0)
; #define PG8_MMA(ai, bj, At, Bt) do { __builtin_amdgcn_s_setprio(1); _Pragma("unroll") for (int m = 0; m < 4; ++m) _Pragma("unroll") for (int n = 0; n < 2; ++n) _Pragma("unroll") for (int k = 0; k < 2; ++k) \
;         acc[ai][bj][m][n] = mma16_<Epi::BF16>(Bt[n][k], At[m][k], acc[ai][bj][m][n]); __builtin_amdgcn_s_setprio(0); } while (0)
; #define PG8_WAIT_V(n) asm volatile("s_waitcnt vmcnt(" #n ")" ::: "memory")
; #define PG8_WAIT_L(n) asm volatile("s_waitcnt lgkmcnt(" #n ")" ::: "memory")
; #define PG8_BAR __builtin_amdgcn_s_barrier()
; #define PG8_SCHED __builtin_amdgcn_sched_barrier(0)
;     ...
;             const char* a1 = cA + (size_t)(t + 1) * kstep;
;             const char* a2 = last ? nA : cA + (size_t)(t + 2) * kstep; const char* b2 = last ? nB : cB + (size_t)(t + 2) * kstep;
;             const char* a3 = a2 + kstep; const char* b3 = b2 + kstep;
;             if constexpr (SP2) {
;             PG8_LDB(B0, 0, 0); PG8_LDB(B1, 0, 1); PG8_SCHED; PG8_LDA(At, 0, 0); PG8_STAGE(PG8_SA(1, 1), a1 + hA, voffA);
;             PG8_WAIT_V(8); PG8_WAIT_L(0); PG8_BAR; PG8_MMA(0, 0, At, B0); PG8_MMA(0, 1, At, B1); PG8_BAR; PG8_SCHED;
;             PG8_LDA(At, 0, 1); PG8_STAGE(PG8_SB(0, 0), b2, voffB); PG8_STAGE(PG8_SB(0, 1), b2 + hB, voffB); PG8_STAGE(PG8_SA(0, 0), a2, voffA);
;             PG8_WAIT_V(8); PG8_WAIT_L(0); PG8_BAR; if (!cur.half) { PG8_MMA(1, 0, At, B0); PG8_MMA(1, 1, At, B1); } PG8_BAR; PG8_SCHED;
.LBB0_1018:
	s_add_u32 s34, s30, 0xfffc0080
	s_addc_u32 s35, s31, -1
	s_add_i32 s54, 0, 0x10000
	s_cmp_eq_u32 s53, 12
	s_cselect_b32 s37, s2, s35
	s_cselect_b32 s36, s3, s34
	s_cselect_b32 s35, s19, s52
	s_cselect_b32 s34, s21, s51
	s_add_i32 s56, 0, 0x14000
	v_add_u32_e32 v156, s54, v141
	v_add_u32_e32 v172, s56, v141
	ds_read_b128 v[144:147], v156
	ds_read_b128 v[148:151], v156 offset:1024
	ds_read_b128 v[152:155], v156 offset:2048
	ds_read_b128 v[156:159], v156 offset:3072
	ds_read_b128 v[160:163], v172
	ds_read_b128 v[164:167], v172 offset:1024
	ds_read_b128 v[168:171], v172 offset:2048
	ds_read_b128 v[172:175], v172 offset:3072
	s_add_i32 m0, s27, 0xc000
	ds_read_b128 v[176:179], v143
	ds_read_b128 v[180:183], v143 offset:1024
	ds_read_b128 v[184:187], v143 offset:2048
	ds_read_b128 v[188:191], v143 offset:3072
	ds_read_b128 v[192:195], v143 offset:4096
	ds_read_b128 v[200:203], v143 offset:5120
	ds_read_b128 v[214:217], v143 offset:6144
	ds_read_b128 v[218:221], v143 offset:7168
	global_load_lds_dwordx4 v136, s[30:31]
	s_add_i32 m0, s27, 0xe000
	s_nop 0
	global_load_lds_dwordx4 v138, s[30:31]
	s_waitcnt vmcnt(8)
	s_waitcnt lgkmcnt(0)
	s_barrier
	s_setprio 1
	v_mfma_f32_16x16x32_bf16 v[126:129], v[144:147], v[176:179], v[126:129]
	v_mfma_f32_16x16x32_bf16 v[118:121], v[152:155], v[176:179], v[118:121]
	v_mfma_f32_16x16x32_bf16 v[110:113], v[144:147], v[184:187], v[110:113]
	v_mfma_f32_16x16x32_bf16 v[102:105], v[152:155], v[184:187], v[102:105]
	v_mfma_f32_16x16x32_bf16 v[94:97], v[144:147], v[192:195], v[94:97]
	v_mfma_f32_16x16x32_bf16 v[86:89], v[152:155], v[192:195], v[86:89]
	v_mfma_f32_16x16x32_bf16 v[78:81], v[144:147], v[214:217], v[78:81]
	v_mfma_f32_16x16x32_bf16 v[70:73], v[152:155], v[214:217], v[70:73]
	v_mfma_f32_16x16x32_bf16 v[126:129], v[148:151], v[180:183], v[126:129]
	v_mfma_f32_16x16x32_bf16 v[118:121], v[156:159], v[180:183], v[118:121]
	v_mfma_f32_16x16x32_bf16 v[110:113], v[148:151], v[188:191], v[110:113]
	v_mfma_f32_16x16x32_bf16 v[102:105], v[156:159], v[188:191], v[102:105]
	v_mfma_f32_16x16x32_bf16 v[94:97], v[148:151], v[200:203], v[94:97]
	v_mfma_f32_16x16x32_bf16 v[86:89], v[156:159], v[200:203], v[86:89]
	v_mfma_f32_16x16x32_bf16 v[78:81], v[148:151], v[218:221], v[78:81]
	v_mfma_f32_16x16x32_bf16 v[70:73], v[156:159], v[218:221], v[70:73]
	s_setprio 0
	s_setprio 1
	v_mfma_f32_16x16x32_bf16 v[122:125], v[160:163], v[176:179], v[122:125]
	v_mfma_f32_16x16x32_bf16 v[114:117], v[168:171], v[176:179], v[114:117]
	v_mfma_f32_16x16x32_bf16 v[106:109], v[160:163], v[184:187], v[106:109]
	v_mfma_f32_16x16x32_bf16 v[98:101], v[168:171], v[184:187], v[98:101]
	v_mfma_f32_16x16x32_bf16 v[90:93], v[160:163], v[192:195], v[90:93]
	v_mfma_f32_16x16x32_bf16 v[82:85], v[168:171], v[192:195], v[82:85]
	v_mfma_f32_16x16x32_bf16 v[74:77], v[160:163], v[214:217], v[74:77]
	v_mfma_f32_16x16x32_bf16 v[66:69], v[168:171], v[214:217], v[66:69]
	v_mfma_f32_16x16x32_bf16 v[122:125], v[164:167], v[180:183], v[122:125]
	v_mfma_f32_16x16x32_bf16 v[114:117], v[172:175], v[180:183], v[114:117]
	v_mfma_f32_16x16x32_bf16 v[106:109], v[164:167], v[188:191], v[106:109]
	v_mfma_f32_16x16x32_bf16 v[98:101], v[172:175], v[188:191], v[98:101]
	v_mfma_f32_16x16x32_bf16 v[90:93], v[164:167], v[200:203], v[90:93]
	v_mfma_f32_16x16x32_bf16 v[82:85], v[172:175], v[200:203], v[82:85]
	v_mfma_f32_16x16x32_bf16 v[74:77], v[164:167], v[218:221], v[74:77]
	v_mfma_f32_16x16x32_bf16 v[66:69], v[172:175], v[218:221], v[66:69]
	s_setprio 0
	s_barrier
	s_add_i32 s54, s54, s40
	s_mov_b32 m0, s54
	ds_read_b128 v[176:179], v143 offset:16384
	ds_read_b128 v[180:183], v143 offset:17408
	ds_read_b128 v[184:187], v143 offset:18432
	ds_read_b128 v[188:191], v143 offset:19456
	ds_read_b128 v[192:195], v143 offset:20480
	ds_read_b128 v[200:203], v143 offset:21504
	ds_read_b128 v[214:217], v143 offset:22528
	ds_read_b128 v[218:221], v143 offset:23552
	global_load_lds_dwordx4 v0, s[34:35]
	s_add_i32 m0, s54, 0x2000
	s_add_u32 s54, s34, 0x40000
	s_addc_u32 s55, s35, 0
	s_add_i32 s56, s56, s40
	global_load_lds_dwordx4 v130, s[34:35]
	s_mov_b32 m0, s56
	s_nop 0
	global_load_lds_dwordx4 v0, s[54:55]
	s_add_i32 m0, s56, 0x2000
	s_nop 0
	global_load_lds_dwordx4 v130, s[54:55]
	s_mov_b32 m0, s27
	s_nop 0
	global_load_lds_dwordx4 v134, s[36:37]
	s_mov_b32 m0, s29
	s_nop 0
	global_load_lds_dwordx4 v132, s[36:37]
	s_waitcnt vmcnt(8)
	s_waitcnt lgkmcnt(0)
	s_barrier
	s_setprio 1
	v_mfma_f32_16x16x32_bf16 v[62:65], v[144:147], v[176:179], v[62:65]
	v_mfma_f32_16x16x32_bf16 v[54:57], v[152:155], v[176:179], v[54:57]
	v_mfma_f32_16x16x32_bf16 v[46:49], v[144:147], v[184:187], v[46:49]
	v_mfma_f32_16x16x32_bf16 v[38:41], v[152:155], v[184:187], v[38:41]
	v_mfma_f32_16x16x32_bf16 v[30:33], v[144:147], v[192:195], v[30:33]
	v_mfma_f32_16x16x32_bf16 v[22:25], v[152:155], v[192:195], v[22:25]
	v_mfma_f32_16x16x32_bf16 v[14:17], v[144:147], v[214:217], v[14:17]
	v_mfma_f32_16x16x32_bf16 v[6:9], v[152:155], v[214:217], v[6:9]
	v_mfma_f32_16x16x32_bf16 v[62:65], v[148:151], v[180:183], v[62:65]
	v_mfma_f32_16x16x32_bf16 v[54:57], v[156:159], v[180:183], v[54:57]
	v_mfma_f32_16x16x32_bf16 v[46:49], v[148:151], v[188:191], v[46:49]
	v_mfma_f32_16x16x32_bf16 v[38:41], v[156:159], v[188:191], v[38:41]
	v_mfma_f32_16x16x32_bf16 v[30:33], v[148:151], v[200:203], v[30:33]
	v_mfma_f32_16x16x32_bf16 v[22:25], v[156:159], v[200:203], v[22:25]
	v_mfma_f32_16x16x32_bf16 v[14:17], v[148:151], v[218:221], v[14:17]
	v_mfma_f32_16x16x32_bf16 v[6:9], v[156:159], v[218:221], v[6:9]
	s_setprio 0
	s_setprio 1
	v_mfma_f32_16x16x32_bf16 v[58:61], v[160:163], v[176:179], v[58:61]
	v_mfma_f32_16x16x32_bf16 v[50:53], v[168:171], v[176:179], v[50:53]
	v_mfma_f32_16x16x32_bf16 v[42:45], v[160:163], v[184:187], v[42:45]
	v_mfma_f32_16x16x32_bf16 v[34:37], v[168:171], v[184:187], v[34:37]
	v_mfma_f32_16x16x32_bf16 v[26:29], v[160:163], v[192:195], v[26:29]
	v_mfma_f32_16x16x32_bf16 v[18:21], v[168:171], v[192:195], v[18:21]
	v_mfma_f32_16x16x32_bf16 v[10:13], v[160:163], v[214:217], v[10:13]
	v_mfma_f32_16x16x32_bf16 v[2:5], v[168:171], v[214:217], v[2:5]
	v_mfma_f32_16x16x32_bf16 v[58:61], v[164:167], v[180:183], v[58:61]
	v_mfma_f32_16x16x32_bf16 v[50:53], v[172:175], v[180:183], v[50:53]
	v_mfma_f32_16x16x32_bf16 v[42:45], v[164:167], v[188:191], v[42:45]
	v_mfma_f32_16x16x32_bf16 v[34:37], v[172:175], v[188:191], v[34:37]
	v_mfma_f32_16x16x32_bf16 v[26:29], v[164:167], v[200:203], v[26:29]
	v_mfma_f32_16x16x32_bf16 v[18:21], v[172:175], v[200:203], v[18:21]
	v_mfma_f32_16x16x32_bf16 v[10:13], v[164:167], v[218:221], v[10:13]
	v_mfma_f32_16x16x32_bf16 v[2:5], v[172:175], v[218:221], v[2:5]
	s_setprio 0
	s_barrier
; #define PG8_STAGE(bufoff, gbase, voff) do { _Pragma("unroll") for (int _i = 0; _i < 2; ++_i) \
;         __builtin_amdgcn_global_load_lds((const unsigned*)((const char*)(gbase) + (voff)[_i]), (LAS unsigned*)(lds + (bufoff) + ldsw + _i * 8192), 16, 0, 0); } while (0)
; #define PG8_LDA(dst, b, h) do { _Pragma("unroll") for (int m = 0; m < 4; ++m) _Pragma("unroll") for (int k = 0; k < 2; ++k) dst[m][k] = *(const LAS f16x8*)(lds + PG8_SA(b, h) + aoff + m * 2048 + k * 1024); } while (0)
; #define PG8_LDB(dst, b, h) do { _Pragma("unroll") for (int n = 0; n < 2; ++n) _Pragma("unroll") for (int k = 0; k < 2; ++k) dst[n][k] = *(const LAS f16x8*)(lds + PG8_SB(b, h) + boff + n * 2048 + k * 1024); } while (0)
; #define PG8_MMA(ai, bj, At, Bt) do { __builtin_amdgcn_s_setprio(1); _Pragma("unroll") for (int m = 0; m < 4; ++m) _Pragma("unroll") for (int n = 0; n < 2; ++n) _Pragma("unroll") for (int k = 0; k < 2; ++k) \
;         acc[ai][bj][m][n] = mma16_<Epi::BF16>(Bt[n][k], At[m][k], acc[ai][bj][m][n]); __builtin_amdgcn_s_setprio(0); } while (0)
; #define PG8_WAIT_V(n) asm volatile("s_waitcnt vmcnt(" #n ")" ::: "memory")
; #define PG8_WAIT_L(n) asm volatile("s_waitcnt lgkmcnt(" #n ")" ::: "memory")
; #define PG8_BAR __builtin_amdgcn_s_barrier()
; #define PG8_SCHED __builtin_amdgcn_sched_barrier(0)
;     ...
;             PG8_LDB(B0, 1, 0); PG8_LDB(B1, 1, 1); PG8_SCHED; PG8_LDA(At, 1, 0); PG8_STAGE(PG8_SA(0, 1), a2 + hA, voffA);
;             PG8_WAIT_V(8); PG8_WAIT_L(0); PG8_BAR; PG8_MMA(0, 0, At, B0); PG8_MMA(0, 1, At, B1); PG8_BAR; PG8_SCHED;
;             PG8_LDA(At, 1, 1); PG8_STAGE(PG8_SB(1, 0), b3, voffB); PG8_STAGE(PG8_SB(1, 1), b3 + hB, voffB); PG8_STAGE(PG8_SA(1, 0), a3, voffA);
;             PG8_WAIT_V(8); PG8_WAIT_L(0); PG8_BAR; if (!cur.half) { PG8_MMA(1, 0, At, B0); PG8_MMA(1, 1, At, B1); } PG8_BAR; PG8_SCHED;
;     ...
;         if constexpr (ALIGN_EPI) { if (wr == 0) PG8_BAR; }
	s_add_i32 s54, 0, 0x18000
	s_add_i32 s55, 0, 0x1c000
	v_add_u32_e32 v156, s54, v141
	v_add_u32_e32 v172, s55, v141
	ds_read_b128 v[144:147], v156
	ds_read_b128 v[148:151], v156 offset:1024
	ds_read_b128 v[152:155], v156 offset:2048
	ds_read_b128 v[156:159], v156 offset:3072
	ds_read_b128 v[160:163], v172
	ds_read_b128 v[164:167], v172 offset:1024
	ds_read_b128 v[168:171], v172 offset:2048
	ds_read_b128 v[172:175], v172 offset:3072
	s_add_u32 s36, s36, 0x40000
	s_addc_u32 s37, s37, 0
	s_add_u32 s98, s36, 0xfffc0080
	s_addc_u32 s99, s37, -1
	s_mov_b32 m0, s43
	ds_read_b128 v[176:179], v143 offset:32768
	ds_read_b128 v[180:183], v143 offset:33792
	ds_read_b128 v[184:187], v143 offset:34816
	ds_read_b128 v[188:191], v143 offset:35840
	ds_read_b128 v[192:195], v143 offset:36864
	ds_read_b128 v[200:203], v143 offset:37888
	ds_read_b128 v[214:217], v143 offset:38912
	ds_read_b128 v[218:221], v143 offset:39936
	global_load_lds_dwordx4 v134, s[36:37]
	s_mov_b32 m0, s44
	s_nop 0
	global_load_lds_dwordx4 v132, s[36:37]
	s_waitcnt vmcnt(8)
	s_waitcnt lgkmcnt(0)
	s_barrier
	s_setprio 1
	v_mfma_f32_16x16x32_bf16 v[126:129], v[144:147], v[176:179], v[126:129]
	v_mfma_f32_16x16x32_bf16 v[118:121], v[152:155], v[176:179], v[118:121]
	v_mfma_f32_16x16x32_bf16 v[110:113], v[144:147], v[184:187], v[110:113]
	v_mfma_f32_16x16x32_bf16 v[102:105], v[152:155], v[184:187], v[102:105]
	v_mfma_f32_16x16x32_bf16 v[94:97], v[144:147], v[192:195], v[94:97]
	v_mfma_f32_16x16x32_bf16 v[86:89], v[152:155], v[192:195], v[86:89]
	v_mfma_f32_16x16x32_bf16 v[78:81], v[144:147], v[214:217], v[78:81]
	v_mfma_f32_16x16x32_bf16 v[70:73], v[152:155], v[214:217], v[70:73]
	v_mfma_f32_16x16x32_bf16 v[126:129], v[148:151], v[180:183], v[126:129]
	v_mfma_f32_16x16x32_bf16 v[118:121], v[156:159], v[180:183], v[118:121]
	v_mfma_f32_16x16x32_bf16 v[110:113], v[148:151], v[188:191], v[110:113]
	v_mfma_f32_16x16x32_bf16 v[102:105], v[156:159], v[188:191], v[102:105]
	v_mfma_f32_16x16x32_bf16 v[94:97], v[148:151], v[200:203], v[94:97]
	v_mfma_f32_16x16x32_bf16 v[86:89], v[156:159], v[200:203], v[86:89]
	v_mfma_f32_16x16x32_bf16 v[78:81], v[148:151], v[218:221], v[78:81]
	v_mfma_f32_16x16x32_bf16 v[70:73], v[156:159], v[218:221], v[70:73]
	s_setprio 0
	s_setprio 1
	v_mfma_f32_16x16x32_bf16 v[122:125], v[160:163], v[176:179], v[122:125]
	v_mfma_f32_16x16x32_bf16 v[114:117], v[168:171], v[176:179], v[114:117]
	v_mfma_f32_16x16x32_bf16 v[106:109], v[160:163], v[184:187], v[106:109]
	v_mfma_f32_16x16x32_bf16 v[98:101], v[168:171], v[184:187], v[98:101]
	v_mfma_f32_16x16x32_bf16 v[90:93], v[160:163], v[192:195], v[90:93]
	v_mfma_f32_16x16x32_bf16 v[82:85], v[168:171], v[192:195], v[82:85]
	v_mfma_f32_16x16x32_bf16 v[74:77], v[160:163], v[214:217], v[74:77]
	v_mfma_f32_16x16x32_bf16 v[66:69], v[168:171], v[214:217], v[66:69]
	v_mfma_f32_16x16x32_bf16 v[122:125], v[164:167], v[180:183], v[122:125]
	v_mfma_f32_16x16x32_bf16 v[114:117], v[172:175], v[180:183], v[114:117]
	v_mfma_f32_16x16x32_bf16 v[106:109], v[164:167], v[188:191], v[106:109]
	v_mfma_f32_16x16x32_bf16 v[98:101], v[172:175], v[188:191], v[98:101]
	v_mfma_f32_16x16x32_bf16 v[90:93], v[164:167], v[200:203], v[90:93]
	v_mfma_f32_16x16x32_bf16 v[82:85], v[172:175], v[200:203], v[82:85]
	v_mfma_f32_16x16x32_bf16 v[74:77], v[164:167], v[218:221], v[74:77]
	v_mfma_f32_16x16x32_bf16 v[66:69], v[172:175], v[218:221], v[66:69]
	s_setprio 0
	s_barrier
	s_add_i32 s36, s54, s40
	s_add_u32 s34, s34, 0x80
	s_addc_u32 s35, s35, 0
	s_mov_b32 m0, s36
	ds_read_b128 v[176:179], v143 offset:49152
	ds_read_b128 v[180:183], v143 offset:50176
	ds_read_b128 v[184:187], v143 offset:51200
	ds_read_b128 v[188:191], v143 offset:52224
	ds_read_b128 v[192:195], v143 offset:53248
	ds_read_b128 v[200:203], v143 offset:54272
	ds_read_b128 v[214:217], v143 offset:55296
	ds_read_b128 v[218:221], v143 offset:56320
	global_load_lds_dwordx4 v0, s[34:35]
	s_add_i32 m0, s36, 0x2000
	s_add_i32 s36, s55, s40
	global_load_lds_dwordx4 v130, s[34:35]
	s_add_u32 s34, s34, 0x40000
	s_addc_u32 s35, s35, 0
	s_mov_b32 m0, s36
	s_nop 0
	global_load_lds_dwordx4 v0, s[34:35]
	s_add_i32 m0, s36, 0x2000
	s_nop 0
	global_load_lds_dwordx4 v130, s[34:35]
	s_mov_b32 m0, s45
	s_nop 0
	global_load_lds_dwordx4 v134, s[98:99]
	s_mov_b32 m0, s47
	s_nop 0
	global_load_lds_dwordx4 v132, s[98:99]
	s_waitcnt vmcnt(8)
	s_waitcnt lgkmcnt(0)
	s_barrier
	s_setprio 1
	v_mfma_f32_16x16x32_bf16 v[62:65], v[144:147], v[176:179], v[62:65]
	v_mfma_f32_16x16x32_bf16 v[54:57], v[152:155], v[176:179], v[54:57]
	v_mfma_f32_16x16x32_bf16 v[46:49], v[144:147], v[184:187], v[46:49]
	v_mfma_f32_16x16x32_bf16 v[38:41], v[152:155], v[184:187], v[38:41]
	v_mfma_f32_16x16x32_bf16 v[30:33], v[144:147], v[192:195], v[30:33]
	v_mfma_f32_16x16x32_bf16 v[22:25], v[152:155], v[192:195], v[22:25]
	v_mfma_f32_16x16x32_bf16 v[14:17], v[144:147], v[214:217], v[14:17]
	v_mfma_f32_16x16x32_bf16 v[6:9], v[152:155], v[214:217], v[6:9]
	v_mfma_f32_16x16x32_bf16 v[62:65], v[148:151], v[180:183], v[62:65]
	v_mfma_f32_16x16x32_bf16 v[54:57], v[156:159], v[180:183], v[54:57]
	v_mfma_f32_16x16x32_bf16 v[46:49], v[148:151], v[188:191], v[46:49]
	v_mfma_f32_16x16x32_bf16 v[38:41], v[156:159], v[188:191], v[38:41]
	v_mfma_f32_16x16x32_bf16 v[30:33], v[148:151], v[200:203], v[30:33]
	v_mfma_f32_16x16x32_bf16 v[22:25], v[156:159], v[200:203], v[22:25]
	v_mfma_f32_16x16x32_bf16 v[14:17], v[148:151], v[218:221], v[14:17]
	v_mfma_f32_16x16x32_bf16 v[6:9], v[156:159], v[218:221], v[6:9]
	s_setprio 0
	s_setprio 1
	v_mfma_f32_16x16x32_bf16 v[58:61], v[160:163], v[176:179], v[58:61]
	v_mfma_f32_16x16x32_bf16 v[50:53], v[168:171], v[176:179], v[50:53]
	v_mfma_f32_16x16x32_bf16 v[42:45], v[160:163], v[184:187], v[42:45]
	v_mfma_f32_16x16x32_bf16 v[34:37], v[168:171], v[184:187], v[34:37]
	v_mfma_f32_16x16x32_bf16 v[26:29], v[160:163], v[192:195], v[26:29]
	v_mfma_f32_16x16x32_bf16 v[18:21], v[168:171], v[192:195], v[18:21]
	v_mfma_f32_16x16x32_bf16 v[10:13], v[160:163], v[214:217], v[10:13]
	v_mfma_f32_16x16x32_bf16 v[2:5], v[168:171], v[214:217], v[2:5]
	v_mfma_f32_16x16x32_bf16 v[58:61], v[164:167], v[180:183], v[58:61]
	v_mfma_f32_16x16x32_bf16 v[50:53], v[172:175], v[180:183], v[50:53]
	v_mfma_f32_16x16x32_bf16 v[42:45], v[164:167], v[188:191], v[42:45]
	v_mfma_f32_16x16x32_bf16 v[34:37], v[172:175], v[188:191], v[34:37]
	v_mfma_f32_16x16x32_bf16 v[26:29], v[164:167], v[200:203], v[26:29]
	v_mfma_f32_16x16x32_bf16 v[18:21], v[172:175], v[200:203], v[18:21]
	v_mfma_f32_16x16x32_bf16 v[10:13], v[164:167], v[218:221], v[10:13]
	v_mfma_f32_16x16x32_bf16 v[2:5], v[172:175], v[218:221], v[2:5]
	s_setprio 0
	s_barrier
	s_add_i32 s53, s53, 2
	s_add_u32 s30, s30, 0x100
	s_addc_u32 s31, s31, 0
	s_add_u32 s51, s51, 0x100
	s_addc_u32 s52, s52, 0
	s_cmp_gt_u32 s53, 13
	s_cbranch_scc0 .LBB0_1018
	s_and_b64 vcc, exec, s[10:11]
	s_cbranch_vccz .LBB0_1021
	s_barrier

; #define PG8_STAGE(bufoff, gbase, voff) do { _Pragma("unroll") for (int _i = 0; _i < 2; ++_i) \
;         __builtin_amdgcn_global_load_lds((const unsigned*)((const char*)(gbase) + (voff)[_i]), (LAS unsigned*)(lds + (bufoff) + ldsw + _i * 8192), 16, 0, 0); } while (0)
; #define PG8_LDA(dst, b, h) do { _Pragma("unroll") for (int m = 0; m < 4; ++m) _Pragma("unroll") for (int k = 0; k < 2; ++k) dst[m][k] = *(const LAS f16x8*)(lds + PG8_SA(b, h) + aoff + m * 2048 + k * 1024); } while (0)
; #define PG8_LDB(dst, b, h) do { _Pragma("unroll") for (int n = 0; n < 2; ++n) _Pragma("unroll") for (int k = 0; k < 2; ++k) dst[n][k] = *(const LAS f16x8*)(lds + PG8_SB(b, h) + boff + n * 2048 + k * 1024); } while (0)
; #define PG8_MMA(ai, bj, At, Bt) do { __builtin_amdgcn_s_setprio(1); _Pragma("unroll") for (int m = 0; m < 4; ++m) _Pragma("unroll") for (int n = 0; n < 2; ++n) _Pragma("unroll") for (int k = 0; k < 2; ++k) \
;         acc[ai][bj][m][n] = mma16_<Epi::BF16>(Bt[n][k], At[m][k], acc[ai][bj][m][n]); __builtin_amdgcn_s_setprio(0); } while (0)
; #define PG8_WAIT_V(n) asm volatile("s_waitcnt vmcnt(" #n ")" ::: "memory")
; #define PG8_WAIT_L(n) asm volatile("s_waitcnt lgkmcnt(" #n ")" ::: "memory")
; #define PG8_BAR __builtin_amdgcn_s_barrier()
; #define PG8_SCHED __builtin_amdgcn_sched_barrier(0)
;     ...
;             const char* a1 = cA + (size_t)(t + 1) * kstep;
;             const char* a2 = last ? nA : cA + (size_t)(t + 2) * kstep; const char* b2 = last ? nB : cB + (size_t)(t + 2) * kstep;
;             const char* a3 = a2 + kstep; const char* b3 = b2 + kstep;
;             if constexpr (SP2) {
;             PG8_LDB(B0, 0, 0); PG8_LDB(B1, 0, 1); PG8_SCHED; PG8_LDA(At, 0, 0); PG8_STAGE(PG8_SA(1, 1), a1 + hA, voffA);
;             PG8_WAIT_V(8); PG8_WAIT_L(0); PG8_BAR; PG8_MMA(0, 0, At, B0); PG8_MMA(0, 1, At, B1); PG8_BAR; PG8_SCHED;
;             PG8_LDA(At, 0, 1); PG8_STAGE(PG8_SB(0, 0), b2, voffB); PG8_STAGE(PG8_SB(0, 1), b2 + hB, voffB); PG8_STAGE(PG8_SA(0, 0), a2, voffA);
;             PG8_WAIT_V(8); PG8_WAIT_L(0); PG8_BAR; if (!cur.half) { PG8_MMA(1, 0, At, B0); PG8_MMA(1, 1, At, B1); } PG8_BAR; PG8_SCHED;
.LBB0_1103:
	s_mov_b64 s[42:43], s[30:31]
	s_add_u32 s30, s42, 0x100
	s_addc_u32 s31, s43, 0
	s_add_i32 s29, 0, 0x10000
	s_cmp_eq_u32 s14, 40
	s_cselect_b32 s45, s25, s31
	s_cselect_b32 s44, s24, s30
	s_cselect_b32 s37, s27, s3
	s_cselect_b32 s36, s26, s2
	s_add_i32 s69, 0, 0x14000
	v_add_u32_e32 v130, s29, v243
	v_add_u32_e32 v142, s69, v243
	ds_read_b128 v[146:149], v130
	ds_read_b128 v[150:153], v130 offset:1024
	ds_read_b128 v[154:157], v130 offset:2048
	ds_read_b128 v[158:161], v130 offset:3072
	ds_read_b128 v[130:133], v142
	ds_read_b128 v[134:137], v142 offset:1024
	ds_read_b128 v[138:141], v142 offset:2048
	ds_read_b128 v[142:145], v142 offset:3072
	s_add_i32 m0, s53, 0xc000
	s_waitcnt lgkmcnt(0)
	ds_read_b128 v[162:165], v244
	ds_read_b128 v[166:169], v244 offset:1024
	ds_read_b128 v[170:173], v244 offset:2048
	ds_read_b128 v[174:177], v244 offset:3072
	ds_read_b128 v[178:181], v244 offset:4096
	ds_read_b128 v[182:185], v244 offset:5120
	ds_read_b128 v[186:189], v244 offset:6144
	ds_read_b128 v[190:193], v244 offset:7168
	global_load_lds_dwordx4 v222, s[42:43]
	s_add_i32 m0, s53, 0xe000
	s_nop 0
	global_load_lds_dwordx4 v224, s[42:43]
	s_waitcnt vmcnt(8)
	s_waitcnt lgkmcnt(0)
	s_barrier
	s_setprio 1
	v_mfma_f32_16x16x32_bf16 v[126:129], v[146:149], v[162:165], v[126:129]
	v_mfma_f32_16x16x32_bf16 v[122:125], v[154:157], v[162:165], v[122:125]
	v_mfma_f32_16x16x32_bf16 v[118:121], v[146:149], v[170:173], v[118:121]
	v_mfma_f32_16x16x32_bf16 v[114:117], v[154:157], v[170:173], v[114:117]
	v_mfma_f32_16x16x32_bf16 v[110:113], v[146:149], v[178:181], v[110:113]
	v_mfma_f32_16x16x32_bf16 v[106:109], v[154:157], v[178:181], v[106:109]
	v_mfma_f32_16x16x32_bf16 v[102:105], v[146:149], v[186:189], v[102:105]
	v_mfma_f32_16x16x32_bf16 v[98:101], v[154:157], v[186:189], v[98:101]
	v_mfma_f32_16x16x32_bf16 v[126:129], v[150:153], v[166:169], v[126:129]
	v_mfma_f32_16x16x32_bf16 v[122:125], v[158:161], v[166:169], v[122:125]
	v_mfma_f32_16x16x32_bf16 v[118:121], v[150:153], v[174:177], v[118:121]
	v_mfma_f32_16x16x32_bf16 v[114:117], v[158:161], v[174:177], v[114:117]
	v_mfma_f32_16x16x32_bf16 v[110:113], v[150:153], v[182:185], v[110:113]
	v_mfma_f32_16x16x32_bf16 v[106:109], v[158:161], v[182:185], v[106:109]
	v_mfma_f32_16x16x32_bf16 v[102:105], v[150:153], v[190:193], v[102:105]
	v_mfma_f32_16x16x32_bf16 v[98:101], v[158:161], v[190:193], v[98:101]
	s_setprio 0
	s_setprio 1
	v_mfma_f32_16x16x32_bf16 v[78:81], v[130:133], v[162:165], v[78:81]
	v_mfma_f32_16x16x32_bf16 v[74:77], v[138:141], v[162:165], v[74:77]
	v_mfma_f32_16x16x32_bf16 v[62:65], v[130:133], v[170:173], v[62:65]
	v_mfma_f32_16x16x32_bf16 v[58:61], v[138:141], v[170:173], v[58:61]
	v_mfma_f32_16x16x32_bf16 v[46:49], v[130:133], v[178:181], v[46:49]
	v_mfma_f32_16x16x32_bf16 v[42:45], v[138:141], v[178:181], v[42:45]
	v_mfma_f32_16x16x32_bf16 v[38:41], v[130:133], v[186:189], v[38:41]
	v_mfma_f32_16x16x32_bf16 v[34:37], v[138:141], v[186:189], v[34:37]
	v_mfma_f32_16x16x32_bf16 v[78:81], v[134:137], v[166:169], v[78:81]
	v_mfma_f32_16x16x32_bf16 v[74:77], v[142:145], v[166:169], v[74:77]
	v_mfma_f32_16x16x32_bf16 v[62:65], v[134:137], v[174:177], v[62:65]
	v_mfma_f32_16x16x32_bf16 v[58:61], v[142:145], v[174:177], v[58:61]
	v_mfma_f32_16x16x32_bf16 v[46:49], v[134:137], v[182:185], v[46:49]
	v_mfma_f32_16x16x32_bf16 v[42:45], v[142:145], v[182:185], v[42:45]
	v_mfma_f32_16x16x32_bf16 v[38:41], v[134:137], v[190:193], v[38:41]
	v_mfma_f32_16x16x32_bf16 v[34:37], v[142:145], v[190:193], v[34:37]
	s_setprio 0
	s_barrier
	s_add_i32 s29, s29, s52
	s_mov_b32 m0, s29
	ds_read_b128 v[186:189], v244 offset:16384
	ds_read_b128 v[190:193], v244 offset:17408
	ds_read_b128 v[178:181], v244 offset:18432
	ds_read_b128 v[182:185], v244 offset:19456
	ds_read_b128 v[170:173], v244 offset:20480
	ds_read_b128 v[174:177], v244 offset:21504
	ds_read_b128 v[162:165], v244 offset:22528
	ds_read_b128 v[166:169], v244 offset:23552
	global_load_lds_dwordx4 v214, s[36:37]
	s_add_i32 m0, s29, 0x2000
	s_add_u32 s42, s36, 0xb0000
	s_addc_u32 s43, s37, 0
	s_add_i32 s29, s69, s52
	global_load_lds_dwordx4 v218, s[36:37]
	s_mov_b32 m0, s29
	s_nop 0
	global_load_lds_dwordx4 v214, s[42:43]
	s_add_i32 m0, s29, 0x2000
	s_nop 0
	global_load_lds_dwordx4 v218, s[42:43]
	s_mov_b32 m0, s53
	v_cndmask_b32_e64 v200, 0, 1, s[34:35]
	global_load_lds_dwordx4 v194, s[44:45]
	s_mov_b32 m0, s54
	v_cmp_ne_u32_e64 s[42:43], 1, v200
	global_load_lds_dwordx4 v216, s[44:45]
	s_waitcnt vmcnt(8)
	s_waitcnt lgkmcnt(0)
	s_andn2_b64 vcc, exec, s[34:35]
	s_barrier
	s_cbranch_vccnz .LBB0_1105
	s_setprio 1
	v_mfma_f32_16x16x32_bf16 v[94:97], v[146:149], v[186:189], v[94:97]
	v_mfma_f32_16x16x32_bf16 v[90:93], v[154:157], v[186:189], v[90:93]
	v_mfma_f32_16x16x32_bf16 v[86:89], v[146:149], v[178:181], v[86:89]
	v_mfma_f32_16x16x32_bf16 v[82:85], v[154:157], v[178:181], v[82:85]
	v_mfma_f32_16x16x32_bf16 v[70:73], v[146:149], v[170:173], v[70:73]
	v_mfma_f32_16x16x32_bf16 v[66:69], v[154:157], v[170:173], v[66:69]
	v_mfma_f32_16x16x32_bf16 v[54:57], v[146:149], v[162:165], v[54:57]
	v_mfma_f32_16x16x32_bf16 v[50:53], v[154:157], v[162:165], v[50:53]
	v_mfma_f32_16x16x32_bf16 v[94:97], v[150:153], v[190:193], v[94:97]
	v_mfma_f32_16x16x32_bf16 v[90:93], v[158:161], v[190:193], v[90:93]
	v_mfma_f32_16x16x32_bf16 v[86:89], v[150:153], v[182:185], v[86:89]
	v_mfma_f32_16x16x32_bf16 v[82:85], v[158:161], v[182:185], v[82:85]
	v_mfma_f32_16x16x32_bf16 v[70:73], v[150:153], v[174:177], v[70:73]
	v_mfma_f32_16x16x32_bf16 v[66:69], v[158:161], v[174:177], v[66:69]
	v_mfma_f32_16x16x32_bf16 v[54:57], v[150:153], v[166:169], v[54:57]
	v_mfma_f32_16x16x32_bf16 v[50:53], v[158:161], v[166:169], v[50:53]
	s_setprio 0
	s_setprio 1
	v_mfma_f32_16x16x32_bf16 v[30:33], v[130:133], v[186:189], v[30:33]
	v_mfma_f32_16x16x32_bf16 v[26:29], v[138:141], v[186:189], v[26:29]
	v_mfma_f32_16x16x32_bf16 v[22:25], v[130:133], v[178:181], v[22:25]
	v_mfma_f32_16x16x32_bf16 v[18:21], v[138:141], v[178:181], v[18:21]
	v_mfma_f32_16x16x32_bf16 v[14:17], v[130:133], v[170:173], v[14:17]
	v_mfma_f32_16x16x32_bf16 v[10:13], v[138:141], v[170:173], v[10:13]
	v_mfma_f32_16x16x32_bf16 v[6:9], v[130:133], v[162:165], v[6:9]
	v_mfma_f32_16x16x32_bf16 v[2:5], v[138:141], v[162:165], v[2:5]
	v_mfma_f32_16x16x32_bf16 v[30:33], v[134:137], v[190:193], v[30:33]
	v_mfma_f32_16x16x32_bf16 v[26:29], v[142:145], v[190:193], v[26:29]
	v_mfma_f32_16x16x32_bf16 v[22:25], v[134:137], v[182:185], v[22:25]
	v_mfma_f32_16x16x32_bf16 v[18:21], v[142:145], v[182:185], v[18:21]
	v_mfma_f32_16x16x32_bf16 v[14:17], v[134:137], v[174:177], v[14:17]
	v_mfma_f32_16x16x32_bf16 v[10:13], v[142:145], v[174:177], v[10:13]
	v_mfma_f32_16x16x32_bf16 v[6:9], v[134:137], v[166:169], v[6:9]
	v_mfma_f32_16x16x32_bf16 v[2:5], v[142:145], v[166:169], v[2:5]
	s_setprio 0
; #define PG8_STAGE(bufoff, gbase, voff) do { _Pragma("unroll") for (int _i = 0; _i < 2; ++_i) \
;         __builtin_amdgcn_global_load_lds((const unsigned*)((const char*)(gbase) + (voff)[_i]), (LAS unsigned*)(lds + (bufoff) + ldsw + _i * 8192), 16, 0, 0); } while (0)
; #define PG8_LDA(dst, b, h) do { _Pragma("unroll") for (int m = 0; m < 4; ++m) _Pragma("unroll") for (int k = 0; k < 2; ++k) dst[m][k] = *(const LAS f16x8*)(lds + PG8_SA(b, h) + aoff + m * 2048 + k * 1024); } while (0)
; #define PG8_LDB(dst, b, h) do { _Pragma("unroll") for (int n = 0; n < 2; ++n) _Pragma("unroll") for (int k = 0; k < 2; ++k) dst[n][k] = *(const LAS f16x8*)(lds + PG8_SB(b, h) + boff + n * 2048 + k * 1024); } while (0)
; #define PG8_MMA(ai, bj, At, Bt) do { __builtin_amdgcn_s_setprio(1); _Pragma("unroll") for (int m = 0; m < 4; ++m) _Pragma("unroll") for (int n = 0; n < 2; ++n) _Pragma("unroll") for (int k = 0; k < 2; ++k) \
;         acc[ai][bj][m][n] = mma16_<Epi::BF16>(Bt[n][k], At[m][k], acc[ai][bj][m][n]); __builtin_amdgcn_s_setprio(0); } while (0)
; #define PG8_WAIT_V(n) asm volatile("s_waitcnt vmcnt(" #n ")" ::: "memory")
; #define PG8_WAIT_L(n) asm volatile("s_waitcnt lgkmcnt(" #n ")" ::: "memory")
; #define PG8_BAR __builtin_amdgcn_s_barrier()
; #define PG8_SCHED __builtin_amdgcn_sched_barrier(0)
;     ...
;             PG8_LDB(B0, 1, 0); PG8_LDB(B1, 1, 1); PG8_SCHED; PG8_LDA(At, 1, 0); PG8_STAGE(PG8_SA(0, 1), a2 + hA, voffA);
;             PG8_WAIT_V(8); PG8_WAIT_L(0); PG8_BAR; PG8_MMA(0, 0, At, B0); PG8_MMA(0, 1, At, B1); PG8_BAR; PG8_SCHED;
;             PG8_LDA(At, 1, 1); PG8_STAGE(PG8_SB(1, 0), b3, voffB); PG8_STAGE(PG8_SB(1, 1), b3 + hB, voffB); PG8_STAGE(PG8_SA(1, 0), a3, voffA);
;             PG8_WAIT_V(8); PG8_WAIT_L(0); PG8_BAR; if (!cur.half) { PG8_MMA(1, 0, At, B0); PG8_MMA(1, 1, At, B1); } PG8_BAR; PG8_SCHED;
.LBB0_1105:
	s_barrier
	s_add_i32 s29, 0, 0x18000
	s_add_i32 s69, 0, 0x1c000
	v_add_u32_e32 v130, s29, v243
	v_add_u32_e32 v142, s69, v243
	ds_read_b128 v[146:149], v130
	ds_read_b128 v[150:153], v130 offset:1024
	ds_read_b128 v[154:157], v130 offset:2048
	ds_read_b128 v[158:161], v130 offset:3072
	ds_read_b128 v[130:133], v142
	ds_read_b128 v[134:137], v142 offset:1024
	ds_read_b128 v[138:141], v142 offset:2048
	ds_read_b128 v[142:145], v142 offset:3072
	s_add_u32 s44, s44, 0xb0000
	s_addc_u32 s45, s45, 0
	s_add_u32 s98, s44, 0xfff50080
	s_addc_u32 s99, s45, -1
	s_mov_b32 m0, s55
	s_waitcnt lgkmcnt(0)
	ds_read_b128 v[162:165], v244 offset:32768
	ds_read_b128 v[166:169], v244 offset:33792
	ds_read_b128 v[170:173], v244 offset:34816
	ds_read_b128 v[174:177], v244 offset:35840
	ds_read_b128 v[178:181], v244 offset:36864
	ds_read_b128 v[182:185], v244 offset:37888
	ds_read_b128 v[186:189], v244 offset:38912
	ds_read_b128 v[190:193], v244 offset:39936
	global_load_lds_dwordx4 v194, s[44:45]
	s_mov_b32 m0, s56
	s_nop 0
	global_load_lds_dwordx4 v216, s[44:45]
	s_waitcnt vmcnt(8)
	s_waitcnt lgkmcnt(0)
	s_barrier
	s_setprio 1
	v_mfma_f32_16x16x32_bf16 v[126:129], v[146:149], v[162:165], v[126:129]
	v_mfma_f32_16x16x32_bf16 v[122:125], v[154:157], v[162:165], v[122:125]
	v_mfma_f32_16x16x32_bf16 v[118:121], v[146:149], v[170:173], v[118:121]
	v_mfma_f32_16x16x32_bf16 v[114:117], v[154:157], v[170:173], v[114:117]
	v_mfma_f32_16x16x32_bf16 v[110:113], v[146:149], v[178:181], v[110:113]
	v_mfma_f32_16x16x32_bf16 v[106:109], v[154:157], v[178:181], v[106:109]
	v_mfma_f32_16x16x32_bf16 v[102:105], v[146:149], v[186:189], v[102:105]
	v_mfma_f32_16x16x32_bf16 v[98:101], v[154:157], v[186:189], v[98:101]
	v_mfma_f32_16x16x32_bf16 v[126:129], v[150:153], v[166:169], v[126:129]
	v_mfma_f32_16x16x32_bf16 v[122:125], v[158:161], v[166:169], v[122:125]
	v_mfma_f32_16x16x32_bf16 v[118:121], v[150:153], v[174:177], v[118:121]
	v_mfma_f32_16x16x32_bf16 v[114:117], v[158:161], v[174:177], v[114:117]
	v_mfma_f32_16x16x32_bf16 v[110:113], v[150:153], v[182:185], v[110:113]
	v_mfma_f32_16x16x32_bf16 v[106:109], v[158:161], v[182:185], v[106:109]
	v_mfma_f32_16x16x32_bf16 v[102:105], v[150:153], v[190:193], v[102:105]
	v_mfma_f32_16x16x32_bf16 v[98:101], v[158:161], v[190:193], v[98:101]
	s_setprio 0
	s_setprio 1
	v_mfma_f32_16x16x32_bf16 v[78:81], v[130:133], v[162:165], v[78:81]
	v_mfma_f32_16x16x32_bf16 v[74:77], v[138:141], v[162:165], v[74:77]
	v_mfma_f32_16x16x32_bf16 v[62:65], v[130:133], v[170:173], v[62:65]
	v_mfma_f32_16x16x32_bf16 v[58:61], v[138:141], v[170:173], v[58:61]
	v_mfma_f32_16x16x32_bf16 v[46:49], v[130:133], v[178:181], v[46:49]
	v_mfma_f32_16x16x32_bf16 v[42:45], v[138:141], v[178:181], v[42:45]
	v_mfma_f32_16x16x32_bf16 v[38:41], v[130:133], v[186:189], v[38:41]
	v_mfma_f32_16x16x32_bf16 v[34:37], v[138:141], v[186:189], v[34:37]
	v_mfma_f32_16x16x32_bf16 v[78:81], v[134:137], v[166:169], v[78:81]
	v_mfma_f32_16x16x32_bf16 v[74:77], v[142:145], v[166:169], v[74:77]
	v_mfma_f32_16x16x32_bf16 v[62:65], v[134:137], v[174:177], v[62:65]
	v_mfma_f32_16x16x32_bf16 v[58:61], v[142:145], v[174:177], v[58:61]
	v_mfma_f32_16x16x32_bf16 v[46:49], v[134:137], v[182:185], v[46:49]
	v_mfma_f32_16x16x32_bf16 v[42:45], v[142:145], v[182:185], v[42:45]
	v_mfma_f32_16x16x32_bf16 v[38:41], v[134:137], v[190:193], v[38:41]
	v_mfma_f32_16x16x32_bf16 v[34:37], v[142:145], v[190:193], v[34:37]
	s_setprio 0
	s_barrier
	s_add_i32 s29, s29, s52
	s_add_u32 s36, s36, 0x80
	s_addc_u32 s37, s37, 0
	s_mov_b32 m0, s29
	ds_read_b128 v[186:189], v244 offset:49152
	ds_read_b128 v[190:193], v244 offset:50176
	ds_read_b128 v[178:181], v244 offset:51200
	ds_read_b128 v[182:185], v244 offset:52224
	ds_read_b128 v[170:173], v244 offset:53248
	ds_read_b128 v[174:177], v244 offset:54272
	ds_read_b128 v[162:165], v244 offset:55296
	ds_read_b128 v[166:169], v244 offset:56320
	global_load_lds_dwordx4 v214, s[36:37]
	s_add_i32 m0, s29, 0x2000
	s_add_i32 s29, s69, s52
	global_load_lds_dwordx4 v218, s[36:37]
	s_add_u32 s36, s36, 0xb0000
	s_addc_u32 s37, s37, 0
	s_mov_b32 m0, s29
	s_and_b64 vcc, exec, s[42:43]
	global_load_lds_dwordx4 v214, s[36:37]
	s_add_i32 m0, s29, 0x2000
	s_nop 0
	global_load_lds_dwordx4 v218, s[36:37]
	s_mov_b32 m0, s59
	s_nop 0
	global_load_lds_dwordx4 v194, s[98:99]
	s_mov_b32 m0, s60
	s_nop 0
	global_load_lds_dwordx4 v216, s[98:99]
	s_waitcnt vmcnt(8)
	s_waitcnt lgkmcnt(0)
	s_barrier
	s_cbranch_vccnz .LBB0_1102
	s_setprio 1
	v_mfma_f32_16x16x32_bf16 v[94:97], v[146:149], v[186:189], v[94:97]
	v_mfma_f32_16x16x32_bf16 v[90:93], v[154:157], v[186:189], v[90:93]
	v_mfma_f32_16x16x32_bf16 v[86:89], v[146:149], v[178:181], v[86:89]
	v_mfma_f32_16x16x32_bf16 v[82:85], v[154:157], v[178:181], v[82:85]
	v_mfma_f32_16x16x32_bf16 v[70:73], v[146:149], v[170:173], v[70:73]
	v_mfma_f32_16x16x32_bf16 v[66:69], v[154:157], v[170:173], v[66:69]
	v_mfma_f32_16x16x32_bf16 v[54:57], v[146:149], v[162:165], v[54:57]
	v_mfma_f32_16x16x32_bf16 v[50:53], v[154:157], v[162:165], v[50:53]
	v_mfma_f32_16x16x32_bf16 v[94:97], v[150:153], v[190:193], v[94:97]
	v_mfma_f32_16x16x32_bf16 v[90:93], v[158:161], v[190:193], v[90:93]
	v_mfma_f32_16x16x32_bf16 v[86:89], v[150:153], v[182:185], v[86:89]
	v_mfma_f32_16x16x32_bf16 v[82:85], v[158:161], v[182:185], v[82:85]
	v_mfma_f32_16x16x32_bf16 v[70:73], v[150:153], v[174:177], v[70:73]
	v_mfma_f32_16x16x32_bf16 v[66:69], v[158:161], v[174:177], v[66:69]
	v_mfma_f32_16x16x32_bf16 v[54:57], v[150:153], v[166:169], v[54:57]
	v_mfma_f32_16x16x32_bf16 v[50:53], v[158:161], v[166:169], v[50:53]
	s_setprio 0
	s_setprio 1
	v_mfma_f32_16x16x32_bf16 v[30:33], v[130:133], v[186:189], v[30:33]
	v_mfma_f32_16x16x32_bf16 v[26:29], v[138:141], v[186:189], v[26:29]
	v_mfma_f32_16x16x32_bf16 v[22:25], v[130:133], v[178:181], v[22:25]
	v_mfma_f32_16x16x32_bf16 v[18:21], v[138:141], v[178:181], v[18:21]
	v_mfma_f32_16x16x32_bf16 v[14:17], v[130:133], v[170:173], v[14:17]
	v_mfma_f32_16x16x32_bf16 v[10:13], v[138:141], v[170:173], v[10:13]
	v_mfma_f32_16x16x32_bf16 v[6:9], v[130:133], v[162:165], v[6:9]
	v_mfma_f32_16x16x32_bf16 v[2:5], v[138:141], v[162:165], v[2:5]
	v_mfma_f32_16x16x32_bf16 v[30:33], v[134:137], v[190:193], v[30:33]
	v_mfma_f32_16x16x32_bf16 v[26:29], v[142:145], v[190:193], v[26:29]
	v_mfma_f32_16x16x32_bf16 v[22:25], v[134:137], v[182:185], v[22:25]
	v_mfma_f32_16x16x32_bf16 v[18:21], v[142:145], v[182:185], v[18:21]
	v_mfma_f32_16x16x32_bf16 v[14:17], v[134:137], v[174:177], v[14:17]
	v_mfma_f32_16x16x32_bf16 v[10:13], v[142:145], v[174:177], v[10:13]
	v_mfma_f32_16x16x32_bf16 v[6:9], v[134:137], v[166:169], v[6:9]
	v_mfma_f32_16x16x32_bf16 v[2:5], v[142:145], v[166:169], v[2:5]
	s_setprio 0
	s_branch .LBB0_1102
